# v11 with all s_setprio removed from GEMM loops (equal priority)
# speedup vs baseline: 1.0094x; 1.0004x over previous
.LBB0_80:
	s_add_u32 s2, s14, 0x100
	v_mov_b32_e32 v0, 0
	s_addc_u32 s8, s15, 0
	s_mov_b32 s9, -2
	v_mov_b32_e32 v1, v0
	v_mov_b32_e32 v2, v0
	v_mov_b32_e32 v3, v0
	v_mov_b32_e32 v6, v0
	s_waitcnt lgkmcnt(0)
	v_mov_b32_e32 v7, v0
	v_mov_b32_e32 v8, v0
	v_mov_b32_e32 v9, v0
	v_mov_b32_e32 v18, v0
	v_mov_b32_e32 v19, v0
	v_mov_b32_e32 v20, v0
	v_mov_b32_e32 v21, v0
	v_mov_b32_e32 v22, v0
	v_mov_b32_e32 v23, v0
	v_mov_b32_e32 v24, v0
	v_mov_b32_e32 v25, v0
	v_mov_b32_e32 v34, v0
	v_mov_b32_e32 v35, v0
	v_mov_b32_e32 v36, v0
	v_mov_b32_e32 v37, v0
	v_mov_b32_e32 v38, v0
	v_mov_b32_e32 v39, v0
	v_mov_b32_e32 v40, v0
	v_mov_b32_e32 v41, v0
	v_mov_b32_e32 v50, v0
	v_mov_b32_e32 v51, v0
	v_mov_b32_e32 v52, v0
	v_mov_b32_e32 v53, v0
	v_mov_b32_e32 v54, v0
	v_mov_b32_e32 v55, v0
	v_mov_b32_e32 v56, v0
	v_mov_b32_e32 v57, v0
	v_mov_b32_e32 v10, v0
	v_mov_b32_e32 v11, v0
	v_mov_b32_e32 v12, v0
	v_mov_b32_e32 v13, v0
	v_mov_b32_e32 v14, v0
	v_mov_b32_e32 v15, v0
	v_mov_b32_e32 v16, v0
	v_mov_b32_e32 v17, v0
	v_mov_b32_e32 v26, v0
	v_mov_b32_e32 v27, v0
	v_mov_b32_e32 v28, v0
	v_mov_b32_e32 v29, v0
	v_mov_b32_e32 v30, v0
	v_mov_b32_e32 v31, v0
	v_mov_b32_e32 v32, v0
	v_mov_b32_e32 v33, v0
	v_mov_b32_e32 v42, v0
	v_mov_b32_e32 v43, v0
	v_mov_b32_e32 v44, v0
	v_mov_b32_e32 v45, v0
	v_mov_b32_e32 v46, v0
	v_mov_b32_e32 v47, v0
	v_mov_b32_e32 v48, v0
	v_mov_b32_e32 v49, v0
	v_mov_b32_e32 v58, v0
	v_mov_b32_e32 v59, v0
	v_mov_b32_e32 v60, v0
	v_mov_b32_e32 v61, v0
	v_mov_b32_e32 v62, v0
	v_mov_b32_e32 v63, v0
	v_mov_b32_e32 v64, v0
	v_mov_b32_e32 v65, v0
	v_mov_b32_e32 v66, v0
	v_mov_b32_e32 v67, v0
	v_mov_b32_e32 v68, v0
	v_mov_b32_e32 v69, v0
	v_mov_b32_e32 v70, v0
	v_mov_b32_e32 v71, v0
	v_mov_b32_e32 v72, v0
	v_mov_b32_e32 v73, v0
	v_mov_b32_e32 v82, v0
	v_mov_b32_e32 v83, v0
	v_mov_b32_e32 v84, v0
	v_mov_b32_e32 v85, v0
	v_mov_b32_e32 v86, v0
	v_mov_b32_e32 v87, v0
	v_mov_b32_e32 v88, v0
	v_mov_b32_e32 v89, v0
	v_mov_b32_e32 v98, v0
	v_mov_b32_e32 v99, v0
	v_mov_b32_e32 v100, v0
	v_mov_b32_e32 v101, v0
	v_mov_b32_e32 v102, v0
	v_mov_b32_e32 v103, v0
	v_mov_b32_e32 v104, v0
	v_mov_b32_e32 v105, v0
	v_mov_b32_e32 v114, v0
	v_mov_b32_e32 v115, v0
	v_mov_b32_e32 v116, v0
	v_mov_b32_e32 v117, v0
	v_mov_b32_e32 v118, v0
	v_mov_b32_e32 v119, v0
	v_mov_b32_e32 v120, v0
	v_mov_b32_e32 v121, v0
	v_mov_b32_e32 v74, v0
	v_mov_b32_e32 v75, v0
	v_mov_b32_e32 v76, v0
	v_mov_b32_e32 v77, v0
	v_mov_b32_e32 v78, v0
	v_mov_b32_e32 v79, v0
	v_mov_b32_e32 v80, v0
	v_mov_b32_e32 v81, v0
	v_mov_b32_e32 v90, v0
	v_mov_b32_e32 v91, v0
	v_mov_b32_e32 v92, v0
	v_mov_b32_e32 v93, v0
	v_mov_b32_e32 v94, v0
	v_mov_b32_e32 v95, v0
	v_mov_b32_e32 v96, v0
	v_mov_b32_e32 v97, v0
	v_mov_b32_e32 v106, v0
	v_mov_b32_e32 v107, v0
	v_mov_b32_e32 v108, v0
	v_mov_b32_e32 v109, v0
	v_mov_b32_e32 v110, v0
	v_mov_b32_e32 v111, v0
	v_mov_b32_e32 v112, v0
	v_mov_b32_e32 v113, v0
	v_mov_b32_e32 v122, v0
	v_mov_b32_e32 v123, v0
	v_mov_b32_e32 v124, v0
	v_mov_b32_e32 v125, v0
	v_mov_b32_e32 v126, v0
	v_mov_b32_e32 v127, v0
	v_mov_b32_e32 v128, v0
	v_mov_b32_e32 v129, v0
	s_cmp_eq_u32 s36, 1
	s_cbranch_scc1 .LBB0_81
	s_add_u32 s14, s0, 0x100
	s_addc_u32 s15, s1, 0
	s_add_i32 s3, 0, 0x10000
	s_cmpk_eq_i32 s9, 0x7c
	s_cselect_b32 s27, s43, s15
	s_cselect_b32 s26, s42, s14
	v_add_u32_e32 v162, s3, v145
	s_cselect_b32 s23, s79, s8
	s_cselect_b32 s22, s78, s2
	s_add_i32 s4, 0, 0x14000
	ds_read_b128 v[140:143], v162
	ds_read_b128 v[148:151], v162 offset:1024
	ds_read_b128 v[172:175], v162 offset:2048
	ds_read_b128 v[190:193], v162 offset:3072
	v_add_u32_e32 v162, s4, v145
	ds_read_b128 v[194:197], v162
	ds_read_b128 v[198:201], v162 offset:1024
	ds_read_b128 v[202:205], v162 offset:2048
	ds_read_b128 v[206:209], v162 offset:3072
	v_lshl_add_u64 v[162:163], s[0:1], 0, v[136:137]
	s_add_i32 m0, s30, 0xc000
	ds_read_b128 v[210:213], v147
	ds_read_b128 v[214:217], v147 offset:1024
	ds_read_b128 v[218:221], v147 offset:2048
	ds_read_b128 v[222:225], v147 offset:3072
	ds_read_b128 v[226:229], v147 offset:4096
	ds_read_b128 v[230:233], v147 offset:5120
	ds_read_b128 v[234:237], v147 offset:6144
	ds_read_b128 v[238:241], v147 offset:7168
	global_load_lds_dwordx4 v[162:163], off
	v_lshl_add_u64 v[162:163], s[0:1], 0, v[138:139]
	s_add_i32 m0, s30, 0xe000
	s_nop 0
	global_load_lds_dwordx4 v[162:163], off
	s_waitcnt vmcnt(24)
	s_waitcnt lgkmcnt(0)
	s_barrier
	s_waitcnt lgkmcnt(0)
	v_mfma_f32_16x16x32_bf16 v[126:129], v[140:143], v[210:213], v[126:129]
	v_mfma_f32_16x16x32_bf16 v[122:125], v[172:175], v[210:213], v[122:125]
	v_mfma_f32_16x16x32_bf16 v[110:113], v[140:143], v[218:221], v[110:113]
	v_mfma_f32_16x16x32_bf16 v[106:109], v[172:175], v[218:221], v[106:109]
	v_mfma_f32_16x16x32_bf16 v[94:97], v[140:143], v[226:229], v[94:97]
	v_mfma_f32_16x16x32_bf16 v[90:93], v[172:175], v[226:229], v[90:93]
	v_mfma_f32_16x16x32_bf16 v[78:81], v[140:143], v[234:237], v[78:81]
	v_mfma_f32_16x16x32_bf16 v[74:77], v[172:175], v[234:237], v[74:77]
	v_mfma_f32_16x16x32_bf16 v[126:129], v[148:151], v[214:217], v[126:129]
	v_mfma_f32_16x16x32_bf16 v[122:125], v[190:193], v[214:217], v[122:125]
	v_mfma_f32_16x16x32_bf16 v[110:113], v[148:151], v[222:225], v[110:113]
	v_mfma_f32_16x16x32_bf16 v[106:109], v[190:193], v[222:225], v[106:109]
	v_mfma_f32_16x16x32_bf16 v[94:97], v[148:151], v[230:233], v[94:97]
	v_mfma_f32_16x16x32_bf16 v[90:93], v[190:193], v[230:233], v[90:93]
	v_mfma_f32_16x16x32_bf16 v[78:81], v[148:151], v[238:241], v[78:81]
	v_mfma_f32_16x16x32_bf16 v[74:77], v[190:193], v[238:241], v[74:77]
	v_mfma_f32_16x16x32_bf16 v[118:121], v[194:197], v[210:213], v[118:121]
	v_mfma_f32_16x16x32_bf16 v[114:117], v[202:205], v[210:213], v[114:117]
	v_mfma_f32_16x16x32_bf16 v[102:105], v[194:197], v[218:221], v[102:105]
	v_mfma_f32_16x16x32_bf16 v[98:101], v[202:205], v[218:221], v[98:101]
	v_mfma_f32_16x16x32_bf16 v[86:89], v[194:197], v[226:229], v[86:89]
	v_mfma_f32_16x16x32_bf16 v[82:85], v[202:205], v[226:229], v[82:85]
	v_mfma_f32_16x16x32_bf16 v[70:73], v[194:197], v[234:237], v[70:73]
	v_mfma_f32_16x16x32_bf16 v[66:69], v[202:205], v[234:237], v[66:69]
	v_mfma_f32_16x16x32_bf16 v[118:121], v[198:201], v[214:217], v[118:121]
	v_mfma_f32_16x16x32_bf16 v[114:117], v[206:209], v[214:217], v[114:117]
	v_mfma_f32_16x16x32_bf16 v[102:105], v[198:201], v[222:225], v[102:105]
	v_mfma_f32_16x16x32_bf16 v[98:101], v[206:209], v[222:225], v[98:101]
	v_mfma_f32_16x16x32_bf16 v[86:89], v[198:201], v[230:233], v[86:89]
	v_mfma_f32_16x16x32_bf16 v[82:85], v[206:209], v[230:233], v[82:85]
	v_mfma_f32_16x16x32_bf16 v[70:73], v[198:201], v[238:241], v[70:73]
	v_mfma_f32_16x16x32_bf16 v[66:69], v[206:209], v[238:241], v[66:69]
	s_barrier
	s_add_i32 s0, s3, s11
	v_lshl_add_u64 v[162:163], s[22:23], 0, v[4:5]
	s_mov_b32 m0, s0
	ds_read_b128 v[210:213], v147 offset:16384
	ds_read_b128 v[214:217], v147 offset:17408
	ds_read_b128 v[218:221], v147 offset:18432
	ds_read_b128 v[222:225], v147 offset:19456
	ds_read_b128 v[226:229], v147 offset:20480
	ds_read_b128 v[230:233], v147 offset:21504
	ds_read_b128 v[234:237], v147 offset:22528
	ds_read_b128 v[238:241], v147 offset:23552
	global_load_lds_dwordx4 v[162:163], off
	s_add_i32 m0, s0, 0x2000
	s_add_u32 s0, s22, 0x208000
	v_lshl_add_u64 v[166:167], s[22:23], 0, v[130:131]
	s_addc_u32 s1, s23, 0
	s_add_i32 s3, s4, s11
	global_load_lds_dwordx4 v[166:167], off
	v_lshl_add_u64 v[176:177], s[0:1], 0, v[4:5]
	s_mov_b32 m0, s3
	v_lshl_add_u64 v[180:181], s[26:27], 0, v[132:133]
	global_load_lds_dwordx4 v[176:177], off
	v_lshl_add_u64 v[176:177], s[0:1], 0, v[130:131]
	s_add_i32 m0, s3, 0x2000
	s_nop 0
	global_load_lds_dwordx4 v[176:177], off
	v_lshl_add_u64 v[176:177], s[26:27], 0, v[134:135]
	s_mov_b32 m0, s30
	s_nop 0
	global_load_lds_dwordx4 v[176:177], off
	s_mov_b32 m0, s31
	s_nop 0
	global_load_lds_dwordx4 v[180:181], off
	s_waitcnt vmcnt(24)
	s_waitcnt lgkmcnt(0)
	s_barrier
	s_waitcnt lgkmcnt(0)
	v_mfma_f32_16x16x32_bf16 v[62:65], v[140:143], v[210:213], v[62:65]
	v_mfma_f32_16x16x32_bf16 v[58:61], v[172:175], v[210:213], v[58:61]
	v_mfma_f32_16x16x32_bf16 v[46:49], v[140:143], v[218:221], v[46:49]
	v_mfma_f32_16x16x32_bf16 v[42:45], v[172:175], v[218:221], v[42:45]
	v_mfma_f32_16x16x32_bf16 v[30:33], v[140:143], v[226:229], v[30:33]
	v_mfma_f32_16x16x32_bf16 v[26:29], v[172:175], v[226:229], v[26:29]
	v_mfma_f32_16x16x32_bf16 v[14:17], v[140:143], v[234:237], v[14:17]
	v_mfma_f32_16x16x32_bf16 v[10:13], v[172:175], v[234:237], v[10:13]
	v_mfma_f32_16x16x32_bf16 v[62:65], v[148:151], v[214:217], v[62:65]
	v_mfma_f32_16x16x32_bf16 v[58:61], v[190:193], v[214:217], v[58:61]
	v_mfma_f32_16x16x32_bf16 v[46:49], v[148:151], v[222:225], v[46:49]
	v_mfma_f32_16x16x32_bf16 v[42:45], v[190:193], v[222:225], v[42:45]
	v_mfma_f32_16x16x32_bf16 v[30:33], v[148:151], v[230:233], v[30:33]
	v_mfma_f32_16x16x32_bf16 v[26:29], v[190:193], v[230:233], v[26:29]
	v_mfma_f32_16x16x32_bf16 v[14:17], v[148:151], v[238:241], v[14:17]
	v_mfma_f32_16x16x32_bf16 v[10:13], v[190:193], v[238:241], v[10:13]
	v_mfma_f32_16x16x32_bf16 v[54:57], v[194:197], v[210:213], v[54:57]
	v_mfma_f32_16x16x32_bf16 v[50:53], v[202:205], v[210:213], v[50:53]
	v_mfma_f32_16x16x32_bf16 v[38:41], v[194:197], v[218:221], v[38:41]
	v_mfma_f32_16x16x32_bf16 v[34:37], v[202:205], v[218:221], v[34:37]
	v_mfma_f32_16x16x32_bf16 v[22:25], v[194:197], v[226:229], v[22:25]
	v_mfma_f32_16x16x32_bf16 v[18:21], v[202:205], v[226:229], v[18:21]
	v_mfma_f32_16x16x32_bf16 v[6:9], v[194:197], v[234:237], v[6:9]
	v_mfma_f32_16x16x32_bf16 v[0:3], v[202:205], v[234:237], v[0:3]
	v_mfma_f32_16x16x32_bf16 v[54:57], v[198:201], v[214:217], v[54:57]
	v_mfma_f32_16x16x32_bf16 v[50:53], v[206:209], v[214:217], v[50:53]
	v_mfma_f32_16x16x32_bf16 v[38:41], v[198:201], v[222:225], v[38:41]
	v_mfma_f32_16x16x32_bf16 v[34:37], v[206:209], v[222:225], v[34:37]
	v_mfma_f32_16x16x32_bf16 v[22:25], v[198:201], v[230:233], v[22:25]
	v_mfma_f32_16x16x32_bf16 v[18:21], v[206:209], v[230:233], v[18:21]
	v_mfma_f32_16x16x32_bf16 v[6:9], v[198:201], v[238:241], v[6:9]
	v_mfma_f32_16x16x32_bf16 v[0:3], v[206:209], v[238:241], v[0:3]
	s_barrier
	s_branch .Lpeelmid_81
.LBB0_81:
	s_add_u32 s14, s0, 0x100
	s_addc_u32 s15, s1, 0
	s_add_i32 s3, 0, 0x10000
	s_cmpk_eq_i32 s9, 0x7c
	s_cselect_b32 s27, s43, s15
	s_cselect_b32 s26, s42, s14
	v_add_u32_e32 v162, s3, v145
	s_cselect_b32 s23, s79, s8
	s_cselect_b32 s22, s78, s2
	s_add_i32 s4, 0, 0x14000
	ds_read_b128 v[140:143], v162
	ds_read_b128 v[148:151], v162 offset:1024
	ds_read_b128 v[172:175], v162 offset:2048
	ds_read_b128 v[190:193], v162 offset:3072
	v_add_u32_e32 v162, s4, v145
	ds_read_b128 v[194:197], v162
	ds_read_b128 v[198:201], v162 offset:1024
	ds_read_b128 v[202:205], v162 offset:2048
	ds_read_b128 v[206:209], v162 offset:3072
	v_lshl_add_u64 v[162:163], s[0:1], 0, v[136:137]
	s_add_i32 m0, s30, 0xc000
	ds_read_b128 v[210:213], v147
	ds_read_b128 v[214:217], v147 offset:1024
	ds_read_b128 v[218:221], v147 offset:2048
	ds_read_b128 v[222:225], v147 offset:3072
	ds_read_b128 v[226:229], v147 offset:4096
	ds_read_b128 v[230:233], v147 offset:5120
	ds_read_b128 v[234:237], v147 offset:6144
	ds_read_b128 v[238:241], v147 offset:7168
	global_load_lds_dwordx4 v[162:163], off
	v_lshl_add_u64 v[162:163], s[0:1], 0, v[138:139]
	s_add_i32 m0, s30, 0xe000
	s_nop 0
	global_load_lds_dwordx4 v[162:163], off
	s_waitcnt vmcnt(8)
	s_waitcnt lgkmcnt(0)
	s_barrier
	s_waitcnt lgkmcnt(0)
	v_mfma_f32_16x16x32_bf16 v[126:129], v[140:143], v[210:213], v[126:129]
	v_mfma_f32_16x16x32_bf16 v[122:125], v[172:175], v[210:213], v[122:125]
	v_mfma_f32_16x16x32_bf16 v[110:113], v[140:143], v[218:221], v[110:113]
	v_mfma_f32_16x16x32_bf16 v[106:109], v[172:175], v[218:221], v[106:109]
	v_mfma_f32_16x16x32_bf16 v[94:97], v[140:143], v[226:229], v[94:97]
	v_mfma_f32_16x16x32_bf16 v[90:93], v[172:175], v[226:229], v[90:93]
	v_mfma_f32_16x16x32_bf16 v[78:81], v[140:143], v[234:237], v[78:81]
	v_mfma_f32_16x16x32_bf16 v[74:77], v[172:175], v[234:237], v[74:77]
	v_mfma_f32_16x16x32_bf16 v[126:129], v[148:151], v[214:217], v[126:129]
	v_mfma_f32_16x16x32_bf16 v[122:125], v[190:193], v[214:217], v[122:125]
	v_mfma_f32_16x16x32_bf16 v[110:113], v[148:151], v[222:225], v[110:113]
	v_mfma_f32_16x16x32_bf16 v[106:109], v[190:193], v[222:225], v[106:109]
	v_mfma_f32_16x16x32_bf16 v[94:97], v[148:151], v[230:233], v[94:97]
	v_mfma_f32_16x16x32_bf16 v[90:93], v[190:193], v[230:233], v[90:93]
	v_mfma_f32_16x16x32_bf16 v[78:81], v[148:151], v[238:241], v[78:81]
	v_mfma_f32_16x16x32_bf16 v[74:77], v[190:193], v[238:241], v[74:77]
	v_mfma_f32_16x16x32_bf16 v[118:121], v[194:197], v[210:213], v[118:121]
	v_mfma_f32_16x16x32_bf16 v[114:117], v[202:205], v[210:213], v[114:117]
	v_mfma_f32_16x16x32_bf16 v[102:105], v[194:197], v[218:221], v[102:105]
	v_mfma_f32_16x16x32_bf16 v[98:101], v[202:205], v[218:221], v[98:101]
	v_mfma_f32_16x16x32_bf16 v[86:89], v[194:197], v[226:229], v[86:89]
	v_mfma_f32_16x16x32_bf16 v[82:85], v[202:205], v[226:229], v[82:85]
	v_mfma_f32_16x16x32_bf16 v[70:73], v[194:197], v[234:237], v[70:73]
	v_mfma_f32_16x16x32_bf16 v[66:69], v[202:205], v[234:237], v[66:69]
	v_mfma_f32_16x16x32_bf16 v[118:121], v[198:201], v[214:217], v[118:121]
	v_mfma_f32_16x16x32_bf16 v[114:117], v[206:209], v[214:217], v[114:117]
	v_mfma_f32_16x16x32_bf16 v[102:105], v[198:201], v[222:225], v[102:105]
	v_mfma_f32_16x16x32_bf16 v[98:101], v[206:209], v[222:225], v[98:101]
	v_mfma_f32_16x16x32_bf16 v[86:89], v[198:201], v[230:233], v[86:89]
	v_mfma_f32_16x16x32_bf16 v[82:85], v[206:209], v[230:233], v[82:85]
	v_mfma_f32_16x16x32_bf16 v[70:73], v[198:201], v[238:241], v[70:73]
	v_mfma_f32_16x16x32_bf16 v[66:69], v[206:209], v[238:241], v[66:69]
	s_barrier
	s_add_i32 s0, s3, s11
	v_lshl_add_u64 v[162:163], s[22:23], 0, v[4:5]
	s_mov_b32 m0, s0
	ds_read_b128 v[210:213], v147 offset:16384
	ds_read_b128 v[214:217], v147 offset:17408
	ds_read_b128 v[218:221], v147 offset:18432
	ds_read_b128 v[222:225], v147 offset:19456
	ds_read_b128 v[226:229], v147 offset:20480
	ds_read_b128 v[230:233], v147 offset:21504
	ds_read_b128 v[234:237], v147 offset:22528
	ds_read_b128 v[238:241], v147 offset:23552
	global_load_lds_dwordx4 v[162:163], off
	s_add_i32 m0, s0, 0x2000
	s_add_u32 s0, s22, 0x208000
	v_lshl_add_u64 v[166:167], s[22:23], 0, v[130:131]
	s_addc_u32 s1, s23, 0
	s_add_i32 s3, s4, s11
	global_load_lds_dwordx4 v[166:167], off
	v_lshl_add_u64 v[176:177], s[0:1], 0, v[4:5]
	s_mov_b32 m0, s3
	v_lshl_add_u64 v[180:181], s[26:27], 0, v[132:133]
	global_load_lds_dwordx4 v[176:177], off
	v_lshl_add_u64 v[176:177], s[0:1], 0, v[130:131]
	s_add_i32 m0, s3, 0x2000
	s_nop 0
	global_load_lds_dwordx4 v[176:177], off
	v_lshl_add_u64 v[176:177], s[26:27], 0, v[134:135]
	s_mov_b32 m0, s30
	s_nop 0
	global_load_lds_dwordx4 v[176:177], off
	s_mov_b32 m0, s31
	s_nop 0
	global_load_lds_dwordx4 v[180:181], off
	s_waitcnt vmcnt(8)
	s_waitcnt lgkmcnt(0)
	s_barrier
	s_waitcnt lgkmcnt(0)
	v_mfma_f32_16x16x32_bf16 v[62:65], v[140:143], v[210:213], v[62:65]
	v_mfma_f32_16x16x32_bf16 v[58:61], v[172:175], v[210:213], v[58:61]
	v_mfma_f32_16x16x32_bf16 v[46:49], v[140:143], v[218:221], v[46:49]
	v_mfma_f32_16x16x32_bf16 v[42:45], v[172:175], v[218:221], v[42:45]
	v_mfma_f32_16x16x32_bf16 v[30:33], v[140:143], v[226:229], v[30:33]
	v_mfma_f32_16x16x32_bf16 v[26:29], v[172:175], v[226:229], v[26:29]
	v_mfma_f32_16x16x32_bf16 v[14:17], v[140:143], v[234:237], v[14:17]
	v_mfma_f32_16x16x32_bf16 v[10:13], v[172:175], v[234:237], v[10:13]
	v_mfma_f32_16x16x32_bf16 v[62:65], v[148:151], v[214:217], v[62:65]
	v_mfma_f32_16x16x32_bf16 v[58:61], v[190:193], v[214:217], v[58:61]
	v_mfma_f32_16x16x32_bf16 v[46:49], v[148:151], v[222:225], v[46:49]
	v_mfma_f32_16x16x32_bf16 v[42:45], v[190:193], v[222:225], v[42:45]
	v_mfma_f32_16x16x32_bf16 v[30:33], v[148:151], v[230:233], v[30:33]
	v_mfma_f32_16x16x32_bf16 v[26:29], v[190:193], v[230:233], v[26:29]
	v_mfma_f32_16x16x32_bf16 v[14:17], v[148:151], v[238:241], v[14:17]
	v_mfma_f32_16x16x32_bf16 v[10:13], v[190:193], v[238:241], v[10:13]
	v_mfma_f32_16x16x32_bf16 v[54:57], v[194:197], v[210:213], v[54:57]
	v_mfma_f32_16x16x32_bf16 v[50:53], v[202:205], v[210:213], v[50:53]
	v_mfma_f32_16x16x32_bf16 v[38:41], v[194:197], v[218:221], v[38:41]
	v_mfma_f32_16x16x32_bf16 v[34:37], v[202:205], v[218:221], v[34:37]
	v_mfma_f32_16x16x32_bf16 v[22:25], v[194:197], v[226:229], v[22:25]
	v_mfma_f32_16x16x32_bf16 v[18:21], v[202:205], v[226:229], v[18:21]
	v_mfma_f32_16x16x32_bf16 v[6:9], v[194:197], v[234:237], v[6:9]
	v_mfma_f32_16x16x32_bf16 v[0:3], v[202:205], v[234:237], v[0:3]
	v_mfma_f32_16x16x32_bf16 v[54:57], v[198:201], v[214:217], v[54:57]
	v_mfma_f32_16x16x32_bf16 v[50:53], v[206:209], v[214:217], v[50:53]
	v_mfma_f32_16x16x32_bf16 v[38:41], v[198:201], v[222:225], v[38:41]
	v_mfma_f32_16x16x32_bf16 v[34:37], v[206:209], v[222:225], v[34:37]
	v_mfma_f32_16x16x32_bf16 v[22:25], v[198:201], v[230:233], v[22:25]
	v_mfma_f32_16x16x32_bf16 v[18:21], v[206:209], v[230:233], v[18:21]
	v_mfma_f32_16x16x32_bf16 v[6:9], v[198:201], v[238:241], v[6:9]
	v_mfma_f32_16x16x32_bf16 v[0:3], v[206:209], v[238:241], v[0:3]
	s_barrier
.Lpeelmid_81:
	s_add_i32 s3, 0, 0x18000
	v_add_u32_e32 v164, s3, v145
	s_add_i32 s4, 0, 0x1c000
	ds_read_b128 v[140:143], v164
	ds_read_b128 v[148:151], v164 offset:1024
	ds_read_b128 v[172:175], v164 offset:2048
	ds_read_b128 v[190:193], v164 offset:3072
	v_add_u32_e32 v164, s4, v145
	ds_read_b128 v[194:197], v164
	ds_read_b128 v[198:201], v164 offset:1024
	ds_read_b128 v[202:205], v164 offset:2048
	ds_read_b128 v[206:209], v164 offset:3072
	s_add_u32 s0, s26, 0x208000
	s_addc_u32 s1, s27, 0
	s_mov_b32 m0, s34
	v_lshl_add_u64 v[242:243], s[0:1], 0, v[134:135]
	ds_read_b128 v[210:213], v147 offset:32768
	ds_read_b128 v[214:217], v147 offset:33792
	ds_read_b128 v[218:221], v147 offset:34816
	ds_read_b128 v[222:225], v147 offset:35840
	ds_read_b128 v[226:229], v147 offset:36864
	ds_read_b128 v[230:233], v147 offset:37888
	ds_read_b128 v[234:237], v147 offset:38912
	ds_read_b128 v[238:241], v147 offset:39936
	global_load_lds_dwordx4 v[242:243], off
	v_lshl_add_u64 v[242:243], s[0:1], 0, v[132:133]
	s_mov_b32 m0, s35
	s_nop 0
	global_load_lds_dwordx4 v[242:243], off
	s_waitcnt vmcnt(8)
	s_waitcnt lgkmcnt(0)
	s_barrier
	s_waitcnt lgkmcnt(0)
	v_mfma_f32_16x16x32_bf16 v[126:129], v[140:143], v[210:213], v[126:129]
	v_mfma_f32_16x16x32_bf16 v[122:125], v[172:175], v[210:213], v[122:125]
	v_mfma_f32_16x16x32_bf16 v[110:113], v[140:143], v[218:221], v[110:113]
	v_mfma_f32_16x16x32_bf16 v[106:109], v[172:175], v[218:221], v[106:109]
	v_mfma_f32_16x16x32_bf16 v[94:97], v[140:143], v[226:229], v[94:97]
	v_mfma_f32_16x16x32_bf16 v[90:93], v[172:175], v[226:229], v[90:93]
	v_mfma_f32_16x16x32_bf16 v[78:81], v[140:143], v[234:237], v[78:81]
	v_mfma_f32_16x16x32_bf16 v[74:77], v[172:175], v[234:237], v[74:77]
	v_mfma_f32_16x16x32_bf16 v[126:129], v[148:151], v[214:217], v[126:129]
	v_mfma_f32_16x16x32_bf16 v[122:125], v[190:193], v[214:217], v[122:125]
	v_mfma_f32_16x16x32_bf16 v[110:113], v[148:151], v[222:225], v[110:113]
	v_mfma_f32_16x16x32_bf16 v[106:109], v[190:193], v[222:225], v[106:109]
	v_mfma_f32_16x16x32_bf16 v[94:97], v[148:151], v[230:233], v[94:97]
	v_mfma_f32_16x16x32_bf16 v[90:93], v[190:193], v[230:233], v[90:93]
	v_mfma_f32_16x16x32_bf16 v[78:81], v[148:151], v[238:241], v[78:81]
	v_mfma_f32_16x16x32_bf16 v[74:77], v[190:193], v[238:241], v[74:77]
	v_mfma_f32_16x16x32_bf16 v[118:121], v[194:197], v[210:213], v[118:121]
	v_mfma_f32_16x16x32_bf16 v[114:117], v[202:205], v[210:213], v[114:117]
	v_mfma_f32_16x16x32_bf16 v[102:105], v[194:197], v[218:221], v[102:105]
	v_mfma_f32_16x16x32_bf16 v[98:101], v[202:205], v[218:221], v[98:101]
	v_mfma_f32_16x16x32_bf16 v[86:89], v[194:197], v[226:229], v[86:89]
	v_mfma_f32_16x16x32_bf16 v[82:85], v[202:205], v[226:229], v[82:85]
	v_mfma_f32_16x16x32_bf16 v[70:73], v[194:197], v[234:237], v[70:73]
	v_mfma_f32_16x16x32_bf16 v[66:69], v[202:205], v[234:237], v[66:69]
	v_mfma_f32_16x16x32_bf16 v[118:121], v[198:201], v[214:217], v[118:121]
	v_mfma_f32_16x16x32_bf16 v[114:117], v[206:209], v[214:217], v[114:117]
	v_mfma_f32_16x16x32_bf16 v[102:105], v[198:201], v[222:225], v[102:105]
	v_mfma_f32_16x16x32_bf16 v[98:101], v[206:209], v[222:225], v[98:101]
	v_mfma_f32_16x16x32_bf16 v[86:89], v[198:201], v[230:233], v[86:89]
	v_mfma_f32_16x16x32_bf16 v[82:85], v[206:209], v[230:233], v[82:85]
	v_mfma_f32_16x16x32_bf16 v[70:73], v[198:201], v[238:241], v[70:73]
	v_mfma_f32_16x16x32_bf16 v[66:69], v[206:209], v[238:241], v[66:69]
	s_barrier
	s_add_i32 s0, s3, s11
	v_lshl_add_u64 v[162:163], v[162:163], 0, s[70:71]
	s_mov_b32 m0, s0
	ds_read_b128 v[210:213], v147 offset:49152
	ds_read_b128 v[214:217], v147 offset:50176
	ds_read_b128 v[218:221], v147 offset:51200
	ds_read_b128 v[222:225], v147 offset:52224
	ds_read_b128 v[226:229], v147 offset:53248
	ds_read_b128 v[230:233], v147 offset:54272
	ds_read_b128 v[234:237], v147 offset:55296
	ds_read_b128 v[238:241], v147 offset:56320
	global_load_lds_dwordx4 v[162:163], off
	s_add_i32 m0, s0, 0x2000
	s_add_u32 s0, s22, 0x208080
	v_lshl_add_u64 v[162:163], v[166:167], 0, s[70:71]
	s_addc_u32 s1, s23, 0
	s_add_i32 s3, s4, s11
	global_load_lds_dwordx4 v[162:163], off
	v_lshl_add_u64 v[162:163], s[0:1], 0, v[4:5]
	s_mov_b32 m0, s3
	s_nop 0
	global_load_lds_dwordx4 v[162:163], off
	v_lshl_add_u64 v[162:163], s[0:1], 0, v[130:131]
	s_add_i32 m0, s3, 0x2000
	s_nop 0
	global_load_lds_dwordx4 v[162:163], off
	v_lshl_add_u64 v[162:163], v[176:177], 0, s[70:71]
	s_mov_b32 m0, s51
	s_nop 0
	global_load_lds_dwordx4 v[162:163], off
	v_lshl_add_u64 v[162:163], v[180:181], 0, s[70:71]
	s_mov_b32 m0, s52
	s_nop 0
	global_load_lds_dwordx4 v[162:163], off
	s_waitcnt vmcnt(8)
	s_waitcnt lgkmcnt(0)
	s_barrier
	s_waitcnt lgkmcnt(0)
	v_mfma_f32_16x16x32_bf16 v[62:65], v[140:143], v[210:213], v[62:65]
	v_mfma_f32_16x16x32_bf16 v[58:61], v[172:175], v[210:213], v[58:61]
	v_mfma_f32_16x16x32_bf16 v[46:49], v[140:143], v[218:221], v[46:49]
	v_mfma_f32_16x16x32_bf16 v[42:45], v[172:175], v[218:221], v[42:45]
	v_mfma_f32_16x16x32_bf16 v[30:33], v[140:143], v[226:229], v[30:33]
	v_mfma_f32_16x16x32_bf16 v[26:29], v[172:175], v[226:229], v[26:29]
	v_mfma_f32_16x16x32_bf16 v[14:17], v[140:143], v[234:237], v[14:17]
	v_mfma_f32_16x16x32_bf16 v[10:13], v[172:175], v[234:237], v[10:13]
	v_mfma_f32_16x16x32_bf16 v[62:65], v[148:151], v[214:217], v[62:65]
	v_mfma_f32_16x16x32_bf16 v[58:61], v[190:193], v[214:217], v[58:61]
	v_mfma_f32_16x16x32_bf16 v[46:49], v[148:151], v[222:225], v[46:49]
	v_mfma_f32_16x16x32_bf16 v[42:45], v[190:193], v[222:225], v[42:45]
	v_mfma_f32_16x16x32_bf16 v[30:33], v[148:151], v[230:233], v[30:33]
	v_mfma_f32_16x16x32_bf16 v[26:29], v[190:193], v[230:233], v[26:29]
	v_mfma_f32_16x16x32_bf16 v[14:17], v[148:151], v[238:241], v[14:17]
	v_mfma_f32_16x16x32_bf16 v[10:13], v[190:193], v[238:241], v[10:13]
	v_mfma_f32_16x16x32_bf16 v[54:57], v[194:197], v[210:213], v[54:57]
	v_mfma_f32_16x16x32_bf16 v[50:53], v[202:205], v[210:213], v[50:53]
	v_mfma_f32_16x16x32_bf16 v[38:41], v[194:197], v[218:221], v[38:41]
	v_mfma_f32_16x16x32_bf16 v[34:37], v[202:205], v[218:221], v[34:37]
	v_mfma_f32_16x16x32_bf16 v[22:25], v[194:197], v[226:229], v[22:25]
	v_mfma_f32_16x16x32_bf16 v[18:21], v[202:205], v[226:229], v[18:21]
	v_mfma_f32_16x16x32_bf16 v[6:9], v[194:197], v[234:237], v[6:9]
	v_mfma_f32_16x16x32_bf16 v[0:3], v[202:205], v[234:237], v[0:3]
	v_mfma_f32_16x16x32_bf16 v[54:57], v[198:201], v[214:217], v[54:57]
	v_mfma_f32_16x16x32_bf16 v[50:53], v[206:209], v[214:217], v[50:53]
	v_mfma_f32_16x16x32_bf16 v[38:41], v[198:201], v[222:225], v[38:41]
	v_mfma_f32_16x16x32_bf16 v[34:37], v[206:209], v[222:225], v[34:37]
	v_mfma_f32_16x16x32_bf16 v[22:25], v[198:201], v[230:233], v[22:25]
	v_mfma_f32_16x16x32_bf16 v[18:21], v[206:209], v[230:233], v[18:21]
	v_mfma_f32_16x16x32_bf16 v[6:9], v[198:201], v[238:241], v[6:9]
	v_mfma_f32_16x16x32_bf16 v[0:3], v[206:209], v[238:241], v[0:3]
	s_barrier
	s_add_i32 s9, s9, 2
	s_add_u32 s2, s2, 0x100
	s_addc_u32 s8, s8, 0
	s_cmpk_gt_u32 s9, 0x7d
	s_mov_b64 s[0:1], s[14:15]
	s_cbranch_scc0 .LBB0_81
	s_and_b64 vcc, exec, s[48:49]
	s_cbranch_vccz .LBB0_84
	s_barrier

.LBB0_123:
	s_ashr_i32 s3, s51, 24
	s_lshl_b32 s2, s51, 8
	s_andn2_b32 s3, s3, 63
	s_add_i32 s2, s3, s2
	s_ashr_i32 s3, s2, 31
	s_lshl_b64 s[2:3], s[2:3], 12
	s_add_u32 s48, s11, s2
	s_addc_u32 s49, s26, s3
	s_and_b64 s[2:3], s[38:39], exec
	s_cselect_b32 s2, s49, s1
	s_cselect_b32 s8, s48, s0
	s_ashr_i32 s47, s46, 31
	s_lshl_b64 s[4:5], s[46:47], 20
	v_readlane_b32 s6, v254, 1
	v_readlane_b32 s7, v254, 2
	s_add_u32 s78, s6, s4
	s_addc_u32 s79, s7, s5
	s_and_b64 s[4:5], s[38:39], exec
	s_cselect_b32 s10, s79, s15
	s_cselect_b32 s24, s78, s14
	s_add_u32 s22, s0, 0x80080
	s_addc_u32 s23, s1, 0
	s_add_u32 s9, s14, 0x100
	v_mov_b32_e32 v0, 0
	s_addc_u32 s25, s15, 0
	s_mov_b32 s28, -2
	v_mov_b32_e32 v1, v0
	v_mov_b32_e32 v2, v0
	v_mov_b32_e32 v3, v0
	v_mov_b32_e32 v6, v0
	v_mov_b32_e32 v7, v0
	v_mov_b32_e32 v8, v0
	v_mov_b32_e32 v9, v0
	v_mov_b32_e32 v10, v0
	v_mov_b32_e32 v11, v0
	v_mov_b32_e32 v12, v0
	v_mov_b32_e32 v13, v0
	v_mov_b32_e32 v14, v0
	v_mov_b32_e32 v15, v0
	v_mov_b32_e32 v16, v0
	v_mov_b32_e32 v17, v0
	v_mov_b32_e32 v18, v0
	v_mov_b32_e32 v19, v0
	v_mov_b32_e32 v20, v0
	v_mov_b32_e32 v21, v0
	v_mov_b32_e32 v22, v0
	v_mov_b32_e32 v23, v0
	v_mov_b32_e32 v24, v0
	v_mov_b32_e32 v25, v0
	v_mov_b32_e32 v26, v0
	v_mov_b32_e32 v27, v0
	v_mov_b32_e32 v28, v0
	v_mov_b32_e32 v29, v0
	v_mov_b32_e32 v30, v0
	v_mov_b32_e32 v31, v0
	v_mov_b32_e32 v32, v0
	v_mov_b32_e32 v33, v0
	v_mov_b32_e32 v58, v0
	v_mov_b32_e32 v59, v0
	v_mov_b32_e32 v60, v0
	v_mov_b32_e32 v61, v0
	v_mov_b32_e32 v62, v0
	v_mov_b32_e32 v63, v0
	v_mov_b32_e32 v64, v0
	v_mov_b32_e32 v65, v0
	v_mov_b32_e32 v74, v0
	v_mov_b32_e32 v75, v0
	v_mov_b32_e32 v76, v0
	v_mov_b32_e32 v77, v0
	v_mov_b32_e32 v78, v0
	v_mov_b32_e32 v79, v0
	v_mov_b32_e32 v80, v0
	v_mov_b32_e32 v81, v0
	v_mov_b32_e32 v82, v0
	v_mov_b32_e32 v83, v0
	v_mov_b32_e32 v84, v0
	v_mov_b32_e32 v85, v0
	v_mov_b32_e32 v86, v0
	v_mov_b32_e32 v87, v0
	v_mov_b32_e32 v88, v0
	v_mov_b32_e32 v89, v0
	v_mov_b32_e32 v90, v0
	v_mov_b32_e32 v91, v0
	v_mov_b32_e32 v92, v0
	v_mov_b32_e32 v93, v0
	v_mov_b32_e32 v94, v0
	v_mov_b32_e32 v95, v0
	v_mov_b32_e32 v96, v0
	v_mov_b32_e32 v97, v0
	v_mov_b32_e32 v34, v0
	v_mov_b32_e32 v35, v0
	v_mov_b32_e32 v36, v0
	v_mov_b32_e32 v37, v0
	v_mov_b32_e32 v38, v0
	v_mov_b32_e32 v39, v0
	v_mov_b32_e32 v40, v0
	v_mov_b32_e32 v41, v0
	v_mov_b32_e32 v42, v0
	v_mov_b32_e32 v43, v0
	v_mov_b32_e32 v44, v0
	v_mov_b32_e32 v45, v0
	v_mov_b32_e32 v46, v0
	v_mov_b32_e32 v47, v0
	v_mov_b32_e32 v48, v0
	v_mov_b32_e32 v49, v0
	v_mov_b32_e32 v50, v0
	v_mov_b32_e32 v51, v0
	v_mov_b32_e32 v52, v0
	v_mov_b32_e32 v53, v0
	v_mov_b32_e32 v54, v0
	v_mov_b32_e32 v55, v0
	v_mov_b32_e32 v56, v0
	v_mov_b32_e32 v57, v0
	v_mov_b32_e32 v66, v0
	v_mov_b32_e32 v67, v0
	v_mov_b32_e32 v68, v0
	v_mov_b32_e32 v69, v0
	v_mov_b32_e32 v70, v0
	v_mov_b32_e32 v71, v0
	v_mov_b32_e32 v72, v0
	v_mov_b32_e32 v73, v0
	v_mov_b32_e32 v98, v0
	v_mov_b32_e32 v99, v0
	v_mov_b32_e32 v100, v0
	v_mov_b32_e32 v101, v0
	v_mov_b32_e32 v102, v0
	v_mov_b32_e32 v103, v0
	v_mov_b32_e32 v104, v0
	v_mov_b32_e32 v105, v0
	v_mov_b32_e32 v106, v0
	v_mov_b32_e32 v107, v0
	v_mov_b32_e32 v108, v0
	v_mov_b32_e32 v109, v0
	v_mov_b32_e32 v110, v0
	v_mov_b32_e32 v111, v0
	v_mov_b32_e32 v112, v0
	v_mov_b32_e32 v113, v0
	v_mov_b32_e32 v114, v0
	v_mov_b32_e32 v115, v0
	v_mov_b32_e32 v116, v0
	v_mov_b32_e32 v117, v0
	v_mov_b32_e32 v118, v0
	v_mov_b32_e32 v119, v0
	v_mov_b32_e32 v120, v0
	v_mov_b32_e32 v121, v0
	v_mov_b32_e32 v122, v0
	v_mov_b32_e32 v123, v0
	v_mov_b32_e32 v124, v0
	v_mov_b32_e32 v125, v0
	v_mov_b32_e32 v126, v0
	v_mov_b32_e32 v127, v0
	v_mov_b32_e32 v128, v0
	v_mov_b32_e32 v129, v0
	s_cmp_eq_u32 s50, 1
	s_cbranch_scc1 .LBB0_124
	s_add_u32 s0, s22, 0xfff80080
	s_addc_u32 s1, s23, -1
	s_add_i32 s3, 0, 0x10000
	s_cmp_eq_u32 s28, 28
	s_cselect_b32 s15, s2, s1
	s_cselect_b32 s14, s8, s0
	v_add_u32_e32 v162, s3, v141
	s_cselect_b32 s1, s10, s25
	s_cselect_b32 s0, s24, s9
	s_add_i32 s6, 0, 0x14000
	ds_read_b128 v[144:147], v162
	ds_read_b128 v[148:151], v162 offset:1024
	ds_read_b128 v[172:175], v162 offset:2048
	ds_read_b128 v[190:193], v162 offset:3072
	v_add_u32_e32 v162, s6, v141
	ds_read_b128 v[194:197], v162
	ds_read_b128 v[198:201], v162 offset:1024
	ds_read_b128 v[202:205], v162 offset:2048
	ds_read_b128 v[206:209], v162 offset:3072
	v_lshl_add_u64 v[162:163], s[22:23], 0, v[136:137]
	s_add_i32 m0, s30, 0xc000
	ds_read_b128 v[210:213], v143
	ds_read_b128 v[214:217], v143 offset:1024
	ds_read_b128 v[218:221], v143 offset:2048
	ds_read_b128 v[222:225], v143 offset:3072
	ds_read_b128 v[226:229], v143 offset:4096
	ds_read_b128 v[230:233], v143 offset:5120
	ds_read_b128 v[234:237], v143 offset:6144
	ds_read_b128 v[238:241], v143 offset:7168
	global_load_lds_dwordx4 v[162:163], off
	v_lshl_add_u64 v[162:163], s[22:23], 0, v[138:139]
	s_add_i32 m0, s30, 0xe000
	s_nop 0
	global_load_lds_dwordx4 v[162:163], off
	s_waitcnt vmcnt(24)
	s_waitcnt lgkmcnt(0)
	s_barrier
	s_waitcnt lgkmcnt(0)
	v_mfma_f32_16x16x32_bf16 v[126:129], v[144:147], v[210:213], v[126:129]
	v_mfma_f32_16x16x32_bf16 v[122:125], v[172:175], v[210:213], v[122:125]
	v_mfma_f32_16x16x32_bf16 v[118:121], v[144:147], v[218:221], v[118:121]
	v_mfma_f32_16x16x32_bf16 v[114:117], v[172:175], v[218:221], v[114:117]
	v_mfma_f32_16x16x32_bf16 v[110:113], v[144:147], v[226:229], v[110:113]
	v_mfma_f32_16x16x32_bf16 v[106:109], v[172:175], v[226:229], v[106:109]
	v_mfma_f32_16x16x32_bf16 v[102:105], v[144:147], v[234:237], v[102:105]
	v_mfma_f32_16x16x32_bf16 v[98:101], v[172:175], v[234:237], v[98:101]
	v_mfma_f32_16x16x32_bf16 v[126:129], v[148:151], v[214:217], v[126:129]
	v_mfma_f32_16x16x32_bf16 v[122:125], v[190:193], v[214:217], v[122:125]
	v_mfma_f32_16x16x32_bf16 v[118:121], v[148:151], v[222:225], v[118:121]
	v_mfma_f32_16x16x32_bf16 v[114:117], v[190:193], v[222:225], v[114:117]
	v_mfma_f32_16x16x32_bf16 v[110:113], v[148:151], v[230:233], v[110:113]
	v_mfma_f32_16x16x32_bf16 v[106:109], v[190:193], v[230:233], v[106:109]
	v_mfma_f32_16x16x32_bf16 v[102:105], v[148:151], v[238:241], v[102:105]
	v_mfma_f32_16x16x32_bf16 v[98:101], v[190:193], v[238:241], v[98:101]
	v_mfma_f32_16x16x32_bf16 v[70:73], v[194:197], v[210:213], v[70:73]
	v_mfma_f32_16x16x32_bf16 v[66:69], v[202:205], v[210:213], v[66:69]
	v_mfma_f32_16x16x32_bf16 v[54:57], v[194:197], v[218:221], v[54:57]
	v_mfma_f32_16x16x32_bf16 v[50:53], v[202:205], v[218:221], v[50:53]
	v_mfma_f32_16x16x32_bf16 v[46:49], v[194:197], v[226:229], v[46:49]
	v_mfma_f32_16x16x32_bf16 v[42:45], v[202:205], v[226:229], v[42:45]
	v_mfma_f32_16x16x32_bf16 v[38:41], v[194:197], v[234:237], v[38:41]
	v_mfma_f32_16x16x32_bf16 v[34:37], v[202:205], v[234:237], v[34:37]
	v_mfma_f32_16x16x32_bf16 v[70:73], v[198:201], v[214:217], v[70:73]
	v_mfma_f32_16x16x32_bf16 v[66:69], v[206:209], v[214:217], v[66:69]
	v_mfma_f32_16x16x32_bf16 v[54:57], v[198:201], v[222:225], v[54:57]
	v_mfma_f32_16x16x32_bf16 v[50:53], v[206:209], v[222:225], v[50:53]
	v_mfma_f32_16x16x32_bf16 v[46:49], v[198:201], v[230:233], v[46:49]
	v_mfma_f32_16x16x32_bf16 v[42:45], v[206:209], v[230:233], v[42:45]
	v_mfma_f32_16x16x32_bf16 v[38:41], v[198:201], v[238:241], v[38:41]
	v_mfma_f32_16x16x32_bf16 v[34:37], v[206:209], v[238:241], v[34:37]
	s_barrier
	s_add_i32 s3, s3, s27
	v_lshl_add_u64 v[162:163], s[0:1], 0, v[4:5]
	s_mov_b32 m0, s3
	ds_read_b128 v[210:213], v143 offset:16384
	ds_read_b128 v[214:217], v143 offset:17408
	ds_read_b128 v[218:221], v143 offset:18432
	ds_read_b128 v[222:225], v143 offset:19456
	ds_read_b128 v[226:229], v143 offset:20480
	ds_read_b128 v[230:233], v143 offset:21504
	ds_read_b128 v[234:237], v143 offset:22528
	ds_read_b128 v[238:241], v143 offset:23552
	global_load_lds_dwordx4 v[162:163], off
	s_add_i32 m0, s3, 0x2000
	s_add_u32 s4, s0, 0x80000
	v_lshl_add_u64 v[166:167], s[0:1], 0, v[130:131]
	s_addc_u32 s5, s1, 0
	s_add_i32 s3, s6, s27
	global_load_lds_dwordx4 v[166:167], off
	v_lshl_add_u64 v[176:177], s[4:5], 0, v[4:5]
	s_mov_b32 m0, s3
	v_lshl_add_u64 v[180:181], s[14:15], 0, v[132:133]
	global_load_lds_dwordx4 v[176:177], off
	v_lshl_add_u64 v[176:177], s[4:5], 0, v[130:131]
	s_add_i32 m0, s3, 0x2000
	s_nop 0
	global_load_lds_dwordx4 v[176:177], off
	v_lshl_add_u64 v[176:177], s[14:15], 0, v[134:135]
	s_mov_b32 m0, s30
	s_nop 0
	global_load_lds_dwordx4 v[176:177], off
	s_mov_b32 m0, s31
	s_nop 0
	global_load_lds_dwordx4 v[180:181], off
	s_waitcnt vmcnt(24)
	s_waitcnt lgkmcnt(0)
	s_barrier
	s_waitcnt lgkmcnt(0)
	v_mfma_f32_16x16x32_bf16 v[94:97], v[144:147], v[210:213], v[94:97]
	v_mfma_f32_16x16x32_bf16 v[90:93], v[172:175], v[210:213], v[90:93]
	v_mfma_f32_16x16x32_bf16 v[86:89], v[144:147], v[218:221], v[86:89]
	v_mfma_f32_16x16x32_bf16 v[82:85], v[172:175], v[218:221], v[82:85]
	v_mfma_f32_16x16x32_bf16 v[78:81], v[144:147], v[226:229], v[78:81]
	v_mfma_f32_16x16x32_bf16 v[74:77], v[172:175], v[226:229], v[74:77]
	v_mfma_f32_16x16x32_bf16 v[62:65], v[144:147], v[234:237], v[62:65]
	v_mfma_f32_16x16x32_bf16 v[58:61], v[172:175], v[234:237], v[58:61]
	v_mfma_f32_16x16x32_bf16 v[94:97], v[148:151], v[214:217], v[94:97]
	v_mfma_f32_16x16x32_bf16 v[90:93], v[190:193], v[214:217], v[90:93]
	v_mfma_f32_16x16x32_bf16 v[86:89], v[148:151], v[222:225], v[86:89]
	v_mfma_f32_16x16x32_bf16 v[82:85], v[190:193], v[222:225], v[82:85]
	v_mfma_f32_16x16x32_bf16 v[78:81], v[148:151], v[230:233], v[78:81]
	v_mfma_f32_16x16x32_bf16 v[74:77], v[190:193], v[230:233], v[74:77]
	v_mfma_f32_16x16x32_bf16 v[62:65], v[148:151], v[238:241], v[62:65]
	v_mfma_f32_16x16x32_bf16 v[58:61], v[190:193], v[238:241], v[58:61]
	v_mfma_f32_16x16x32_bf16 v[30:33], v[194:197], v[210:213], v[30:33]
	v_mfma_f32_16x16x32_bf16 v[26:29], v[202:205], v[210:213], v[26:29]
	v_mfma_f32_16x16x32_bf16 v[22:25], v[194:197], v[218:221], v[22:25]
	v_mfma_f32_16x16x32_bf16 v[18:21], v[202:205], v[218:221], v[18:21]
	v_mfma_f32_16x16x32_bf16 v[14:17], v[194:197], v[226:229], v[14:17]
	v_mfma_f32_16x16x32_bf16 v[10:13], v[202:205], v[226:229], v[10:13]
	v_mfma_f32_16x16x32_bf16 v[6:9], v[194:197], v[234:237], v[6:9]
	v_mfma_f32_16x16x32_bf16 v[0:3], v[202:205], v[234:237], v[0:3]
	v_mfma_f32_16x16x32_bf16 v[30:33], v[198:201], v[214:217], v[30:33]
	v_mfma_f32_16x16x32_bf16 v[26:29], v[206:209], v[214:217], v[26:29]
	v_mfma_f32_16x16x32_bf16 v[22:25], v[198:201], v[222:225], v[22:25]
	v_mfma_f32_16x16x32_bf16 v[18:21], v[206:209], v[222:225], v[18:21]
	v_mfma_f32_16x16x32_bf16 v[14:17], v[198:201], v[230:233], v[14:17]
	v_mfma_f32_16x16x32_bf16 v[10:13], v[206:209], v[230:233], v[10:13]
	v_mfma_f32_16x16x32_bf16 v[6:9], v[198:201], v[238:241], v[6:9]
	v_mfma_f32_16x16x32_bf16 v[0:3], v[206:209], v[238:241], v[0:3]
	s_barrier
	s_branch .Lpeelmid_124
.LBB0_124:
	s_add_u32 s0, s22, 0xfff80080
	s_addc_u32 s1, s23, -1
	s_add_i32 s3, 0, 0x10000
	s_cmp_eq_u32 s28, 28
	s_cselect_b32 s15, s2, s1
	s_cselect_b32 s14, s8, s0
	v_add_u32_e32 v162, s3, v141
	s_cselect_b32 s1, s10, s25
	s_cselect_b32 s0, s24, s9
	s_add_i32 s6, 0, 0x14000
	ds_read_b128 v[144:147], v162
	ds_read_b128 v[148:151], v162 offset:1024
	ds_read_b128 v[172:175], v162 offset:2048
	ds_read_b128 v[190:193], v162 offset:3072
	v_add_u32_e32 v162, s6, v141
	ds_read_b128 v[194:197], v162
	ds_read_b128 v[198:201], v162 offset:1024
	ds_read_b128 v[202:205], v162 offset:2048
	ds_read_b128 v[206:209], v162 offset:3072
	v_lshl_add_u64 v[162:163], s[22:23], 0, v[136:137]
	s_add_i32 m0, s30, 0xc000
	ds_read_b128 v[210:213], v143
	ds_read_b128 v[214:217], v143 offset:1024
	ds_read_b128 v[218:221], v143 offset:2048
	ds_read_b128 v[222:225], v143 offset:3072
	ds_read_b128 v[226:229], v143 offset:4096
	ds_read_b128 v[230:233], v143 offset:5120
	ds_read_b128 v[234:237], v143 offset:6144
	ds_read_b128 v[238:241], v143 offset:7168
	global_load_lds_dwordx4 v[162:163], off
	v_lshl_add_u64 v[162:163], s[22:23], 0, v[138:139]
	s_add_i32 m0, s30, 0xe000
	s_nop 0
	global_load_lds_dwordx4 v[162:163], off
	s_waitcnt vmcnt(8)
	s_waitcnt lgkmcnt(0)
	s_barrier
	s_waitcnt lgkmcnt(0)
	v_mfma_f32_16x16x32_bf16 v[126:129], v[144:147], v[210:213], v[126:129]
	v_mfma_f32_16x16x32_bf16 v[122:125], v[172:175], v[210:213], v[122:125]
	v_mfma_f32_16x16x32_bf16 v[118:121], v[144:147], v[218:221], v[118:121]
	v_mfma_f32_16x16x32_bf16 v[114:117], v[172:175], v[218:221], v[114:117]
	v_mfma_f32_16x16x32_bf16 v[110:113], v[144:147], v[226:229], v[110:113]
	v_mfma_f32_16x16x32_bf16 v[106:109], v[172:175], v[226:229], v[106:109]
	v_mfma_f32_16x16x32_bf16 v[102:105], v[144:147], v[234:237], v[102:105]
	v_mfma_f32_16x16x32_bf16 v[98:101], v[172:175], v[234:237], v[98:101]
	v_mfma_f32_16x16x32_bf16 v[126:129], v[148:151], v[214:217], v[126:129]
	v_mfma_f32_16x16x32_bf16 v[122:125], v[190:193], v[214:217], v[122:125]
	v_mfma_f32_16x16x32_bf16 v[118:121], v[148:151], v[222:225], v[118:121]
	v_mfma_f32_16x16x32_bf16 v[114:117], v[190:193], v[222:225], v[114:117]
	v_mfma_f32_16x16x32_bf16 v[110:113], v[148:151], v[230:233], v[110:113]
	v_mfma_f32_16x16x32_bf16 v[106:109], v[190:193], v[230:233], v[106:109]
	v_mfma_f32_16x16x32_bf16 v[102:105], v[148:151], v[238:241], v[102:105]
	v_mfma_f32_16x16x32_bf16 v[98:101], v[190:193], v[238:241], v[98:101]
	v_mfma_f32_16x16x32_bf16 v[70:73], v[194:197], v[210:213], v[70:73]
	v_mfma_f32_16x16x32_bf16 v[66:69], v[202:205], v[210:213], v[66:69]
	v_mfma_f32_16x16x32_bf16 v[54:57], v[194:197], v[218:221], v[54:57]
	v_mfma_f32_16x16x32_bf16 v[50:53], v[202:205], v[218:221], v[50:53]
	v_mfma_f32_16x16x32_bf16 v[46:49], v[194:197], v[226:229], v[46:49]
	v_mfma_f32_16x16x32_bf16 v[42:45], v[202:205], v[226:229], v[42:45]
	v_mfma_f32_16x16x32_bf16 v[38:41], v[194:197], v[234:237], v[38:41]
	v_mfma_f32_16x16x32_bf16 v[34:37], v[202:205], v[234:237], v[34:37]
	v_mfma_f32_16x16x32_bf16 v[70:73], v[198:201], v[214:217], v[70:73]
	v_mfma_f32_16x16x32_bf16 v[66:69], v[206:209], v[214:217], v[66:69]
	v_mfma_f32_16x16x32_bf16 v[54:57], v[198:201], v[222:225], v[54:57]
	v_mfma_f32_16x16x32_bf16 v[50:53], v[206:209], v[222:225], v[50:53]
	v_mfma_f32_16x16x32_bf16 v[46:49], v[198:201], v[230:233], v[46:49]
	v_mfma_f32_16x16x32_bf16 v[42:45], v[206:209], v[230:233], v[42:45]
	v_mfma_f32_16x16x32_bf16 v[38:41], v[198:201], v[238:241], v[38:41]
	v_mfma_f32_16x16x32_bf16 v[34:37], v[206:209], v[238:241], v[34:37]
	s_barrier
	s_add_i32 s3, s3, s27
	v_lshl_add_u64 v[162:163], s[0:1], 0, v[4:5]
	s_mov_b32 m0, s3
	ds_read_b128 v[210:213], v143 offset:16384
	ds_read_b128 v[214:217], v143 offset:17408
	ds_read_b128 v[218:221], v143 offset:18432
	ds_read_b128 v[222:225], v143 offset:19456
	ds_read_b128 v[226:229], v143 offset:20480
	ds_read_b128 v[230:233], v143 offset:21504
	ds_read_b128 v[234:237], v143 offset:22528
	ds_read_b128 v[238:241], v143 offset:23552
	global_load_lds_dwordx4 v[162:163], off
	s_add_i32 m0, s3, 0x2000
	s_add_u32 s4, s0, 0x80000
	v_lshl_add_u64 v[166:167], s[0:1], 0, v[130:131]
	s_addc_u32 s5, s1, 0
	s_add_i32 s3, s6, s27
	global_load_lds_dwordx4 v[166:167], off
	v_lshl_add_u64 v[176:177], s[4:5], 0, v[4:5]
	s_mov_b32 m0, s3
	v_lshl_add_u64 v[180:181], s[14:15], 0, v[132:133]
	global_load_lds_dwordx4 v[176:177], off
	v_lshl_add_u64 v[176:177], s[4:5], 0, v[130:131]
	s_add_i32 m0, s3, 0x2000
	s_nop 0
	global_load_lds_dwordx4 v[176:177], off
	v_lshl_add_u64 v[176:177], s[14:15], 0, v[134:135]
	s_mov_b32 m0, s30
	s_nop 0
	global_load_lds_dwordx4 v[176:177], off
	s_mov_b32 m0, s31
	s_nop 0
	global_load_lds_dwordx4 v[180:181], off
	s_waitcnt vmcnt(8)
	s_waitcnt lgkmcnt(0)
	s_barrier
	s_waitcnt lgkmcnt(0)
	v_mfma_f32_16x16x32_bf16 v[94:97], v[144:147], v[210:213], v[94:97]
	v_mfma_f32_16x16x32_bf16 v[90:93], v[172:175], v[210:213], v[90:93]
	v_mfma_f32_16x16x32_bf16 v[86:89], v[144:147], v[218:221], v[86:89]
	v_mfma_f32_16x16x32_bf16 v[82:85], v[172:175], v[218:221], v[82:85]
	v_mfma_f32_16x16x32_bf16 v[78:81], v[144:147], v[226:229], v[78:81]
	v_mfma_f32_16x16x32_bf16 v[74:77], v[172:175], v[226:229], v[74:77]
	v_mfma_f32_16x16x32_bf16 v[62:65], v[144:147], v[234:237], v[62:65]
	v_mfma_f32_16x16x32_bf16 v[58:61], v[172:175], v[234:237], v[58:61]
	v_mfma_f32_16x16x32_bf16 v[94:97], v[148:151], v[214:217], v[94:97]
	v_mfma_f32_16x16x32_bf16 v[90:93], v[190:193], v[214:217], v[90:93]
	v_mfma_f32_16x16x32_bf16 v[86:89], v[148:151], v[222:225], v[86:89]
	v_mfma_f32_16x16x32_bf16 v[82:85], v[190:193], v[222:225], v[82:85]
	v_mfma_f32_16x16x32_bf16 v[78:81], v[148:151], v[230:233], v[78:81]
	v_mfma_f32_16x16x32_bf16 v[74:77], v[190:193], v[230:233], v[74:77]
	v_mfma_f32_16x16x32_bf16 v[62:65], v[148:151], v[238:241], v[62:65]
	v_mfma_f32_16x16x32_bf16 v[58:61], v[190:193], v[238:241], v[58:61]
	v_mfma_f32_16x16x32_bf16 v[30:33], v[194:197], v[210:213], v[30:33]
	v_mfma_f32_16x16x32_bf16 v[26:29], v[202:205], v[210:213], v[26:29]
	v_mfma_f32_16x16x32_bf16 v[22:25], v[194:197], v[218:221], v[22:25]
	v_mfma_f32_16x16x32_bf16 v[18:21], v[202:205], v[218:221], v[18:21]
	v_mfma_f32_16x16x32_bf16 v[14:17], v[194:197], v[226:229], v[14:17]
	v_mfma_f32_16x16x32_bf16 v[10:13], v[202:205], v[226:229], v[10:13]
	v_mfma_f32_16x16x32_bf16 v[6:9], v[194:197], v[234:237], v[6:9]
	v_mfma_f32_16x16x32_bf16 v[0:3], v[202:205], v[234:237], v[0:3]
	v_mfma_f32_16x16x32_bf16 v[30:33], v[198:201], v[214:217], v[30:33]
	v_mfma_f32_16x16x32_bf16 v[26:29], v[206:209], v[214:217], v[26:29]
	v_mfma_f32_16x16x32_bf16 v[22:25], v[198:201], v[222:225], v[22:25]
	v_mfma_f32_16x16x32_bf16 v[18:21], v[206:209], v[222:225], v[18:21]
	v_mfma_f32_16x16x32_bf16 v[14:17], v[198:201], v[230:233], v[14:17]
	v_mfma_f32_16x16x32_bf16 v[10:13], v[206:209], v[230:233], v[10:13]
	v_mfma_f32_16x16x32_bf16 v[6:9], v[198:201], v[238:241], v[6:9]
	v_mfma_f32_16x16x32_bf16 v[0:3], v[206:209], v[238:241], v[0:3]
	s_barrier
.Lpeelmid_124:
	s_add_i32 s3, 0, 0x18000
	v_add_u32_e32 v164, s3, v141
	s_add_i32 s6, 0, 0x1c000
	ds_read_b128 v[144:147], v164
	ds_read_b128 v[148:151], v164 offset:1024
	ds_read_b128 v[172:175], v164 offset:2048
	ds_read_b128 v[190:193], v164 offset:3072
	v_add_u32_e32 v164, s6, v141
	ds_read_b128 v[194:197], v164
	ds_read_b128 v[198:201], v164 offset:1024
	ds_read_b128 v[202:205], v164 offset:2048
	ds_read_b128 v[206:209], v164 offset:3072
	s_add_u32 s4, s14, 0x80000
	s_addc_u32 s5, s15, 0
	s_mov_b32 m0, s34
	v_lshl_add_u64 v[242:243], s[4:5], 0, v[134:135]
	ds_read_b128 v[210:213], v143 offset:32768
	ds_read_b128 v[214:217], v143 offset:33792
	ds_read_b128 v[218:221], v143 offset:34816
	ds_read_b128 v[222:225], v143 offset:35840
	ds_read_b128 v[226:229], v143 offset:36864
	ds_read_b128 v[230:233], v143 offset:37888
	ds_read_b128 v[234:237], v143 offset:38912
	ds_read_b128 v[238:241], v143 offset:39936
	global_load_lds_dwordx4 v[242:243], off
	v_lshl_add_u64 v[242:243], s[4:5], 0, v[132:133]
	s_mov_b32 m0, s35
	s_nop 0
	global_load_lds_dwordx4 v[242:243], off
	s_waitcnt vmcnt(8)
	s_waitcnt lgkmcnt(0)
	s_barrier
	s_waitcnt lgkmcnt(0)
	v_mfma_f32_16x16x32_bf16 v[126:129], v[144:147], v[210:213], v[126:129]
	v_mfma_f32_16x16x32_bf16 v[122:125], v[172:175], v[210:213], v[122:125]
	v_mfma_f32_16x16x32_bf16 v[118:121], v[144:147], v[218:221], v[118:121]
	v_mfma_f32_16x16x32_bf16 v[114:117], v[172:175], v[218:221], v[114:117]
	v_mfma_f32_16x16x32_bf16 v[110:113], v[144:147], v[226:229], v[110:113]
	v_mfma_f32_16x16x32_bf16 v[106:109], v[172:175], v[226:229], v[106:109]
	v_mfma_f32_16x16x32_bf16 v[102:105], v[144:147], v[234:237], v[102:105]
	v_mfma_f32_16x16x32_bf16 v[98:101], v[172:175], v[234:237], v[98:101]
	v_mfma_f32_16x16x32_bf16 v[126:129], v[148:151], v[214:217], v[126:129]
	v_mfma_f32_16x16x32_bf16 v[122:125], v[190:193], v[214:217], v[122:125]
	v_mfma_f32_16x16x32_bf16 v[118:121], v[148:151], v[222:225], v[118:121]
	v_mfma_f32_16x16x32_bf16 v[114:117], v[190:193], v[222:225], v[114:117]
	v_mfma_f32_16x16x32_bf16 v[110:113], v[148:151], v[230:233], v[110:113]
	v_mfma_f32_16x16x32_bf16 v[106:109], v[190:193], v[230:233], v[106:109]
	v_mfma_f32_16x16x32_bf16 v[102:105], v[148:151], v[238:241], v[102:105]
	v_mfma_f32_16x16x32_bf16 v[98:101], v[190:193], v[238:241], v[98:101]
	v_mfma_f32_16x16x32_bf16 v[70:73], v[194:197], v[210:213], v[70:73]
	v_mfma_f32_16x16x32_bf16 v[66:69], v[202:205], v[210:213], v[66:69]
	v_mfma_f32_16x16x32_bf16 v[54:57], v[194:197], v[218:221], v[54:57]
	v_mfma_f32_16x16x32_bf16 v[50:53], v[202:205], v[218:221], v[50:53]
	v_mfma_f32_16x16x32_bf16 v[46:49], v[194:197], v[226:229], v[46:49]
	v_mfma_f32_16x16x32_bf16 v[42:45], v[202:205], v[226:229], v[42:45]
	v_mfma_f32_16x16x32_bf16 v[38:41], v[194:197], v[234:237], v[38:41]
	v_mfma_f32_16x16x32_bf16 v[34:37], v[202:205], v[234:237], v[34:37]
	v_mfma_f32_16x16x32_bf16 v[70:73], v[198:201], v[214:217], v[70:73]
	v_mfma_f32_16x16x32_bf16 v[66:69], v[206:209], v[214:217], v[66:69]
	v_mfma_f32_16x16x32_bf16 v[54:57], v[198:201], v[222:225], v[54:57]
	v_mfma_f32_16x16x32_bf16 v[50:53], v[206:209], v[222:225], v[50:53]
	v_mfma_f32_16x16x32_bf16 v[46:49], v[198:201], v[230:233], v[46:49]
	v_mfma_f32_16x16x32_bf16 v[42:45], v[206:209], v[230:233], v[42:45]
	v_mfma_f32_16x16x32_bf16 v[38:41], v[198:201], v[238:241], v[38:41]
	v_mfma_f32_16x16x32_bf16 v[34:37], v[206:209], v[238:241], v[34:37]
	s_barrier
	s_add_i32 s3, s3, s27
	v_lshl_add_u64 v[162:163], v[162:163], 0, s[70:71]
	s_mov_b32 m0, s3
	ds_read_b128 v[210:213], v143 offset:49152
	ds_read_b128 v[214:217], v143 offset:50176
	ds_read_b128 v[218:221], v143 offset:51200
	ds_read_b128 v[222:225], v143 offset:52224
	ds_read_b128 v[226:229], v143 offset:53248
	ds_read_b128 v[230:233], v143 offset:54272
	ds_read_b128 v[234:237], v143 offset:55296
	ds_read_b128 v[238:241], v143 offset:56320
	global_load_lds_dwordx4 v[162:163], off
	s_add_i32 m0, s3, 0x2000
	s_add_u32 s0, s0, 0x80080
	v_lshl_add_u64 v[162:163], v[166:167], 0, s[70:71]
	s_addc_u32 s1, s1, 0
	s_add_i32 s3, s6, s27
	global_load_lds_dwordx4 v[162:163], off
	v_lshl_add_u64 v[162:163], s[0:1], 0, v[4:5]
	s_mov_b32 m0, s3
	s_nop 0
	global_load_lds_dwordx4 v[162:163], off
	v_lshl_add_u64 v[162:163], s[0:1], 0, v[130:131]
	s_add_i32 m0, s3, 0x2000
	s_nop 0
	global_load_lds_dwordx4 v[162:163], off
	v_lshl_add_u64 v[162:163], v[176:177], 0, s[70:71]
	s_mov_b32 m0, s36
	s_nop 0
	global_load_lds_dwordx4 v[162:163], off
	v_lshl_add_u64 v[162:163], v[180:181], 0, s[70:71]
	s_mov_b32 m0, s37
	s_nop 0
	global_load_lds_dwordx4 v[162:163], off
	s_waitcnt vmcnt(8)
	s_waitcnt lgkmcnt(0)
	s_barrier
	s_waitcnt lgkmcnt(0)
	v_mfma_f32_16x16x32_bf16 v[94:97], v[144:147], v[210:213], v[94:97]
	v_mfma_f32_16x16x32_bf16 v[90:93], v[172:175], v[210:213], v[90:93]
	v_mfma_f32_16x16x32_bf16 v[86:89], v[144:147], v[218:221], v[86:89]
	v_mfma_f32_16x16x32_bf16 v[82:85], v[172:175], v[218:221], v[82:85]
	v_mfma_f32_16x16x32_bf16 v[78:81], v[144:147], v[226:229], v[78:81]
	v_mfma_f32_16x16x32_bf16 v[74:77], v[172:175], v[226:229], v[74:77]
	v_mfma_f32_16x16x32_bf16 v[62:65], v[144:147], v[234:237], v[62:65]
	v_mfma_f32_16x16x32_bf16 v[58:61], v[172:175], v[234:237], v[58:61]
	v_mfma_f32_16x16x32_bf16 v[94:97], v[148:151], v[214:217], v[94:97]
	v_mfma_f32_16x16x32_bf16 v[90:93], v[190:193], v[214:217], v[90:93]
	v_mfma_f32_16x16x32_bf16 v[86:89], v[148:151], v[222:225], v[86:89]
	v_mfma_f32_16x16x32_bf16 v[82:85], v[190:193], v[222:225], v[82:85]
	v_mfma_f32_16x16x32_bf16 v[78:81], v[148:151], v[230:233], v[78:81]
	v_mfma_f32_16x16x32_bf16 v[74:77], v[190:193], v[230:233], v[74:77]
	v_mfma_f32_16x16x32_bf16 v[62:65], v[148:151], v[238:241], v[62:65]
	v_mfma_f32_16x16x32_bf16 v[58:61], v[190:193], v[238:241], v[58:61]
	v_mfma_f32_16x16x32_bf16 v[30:33], v[194:197], v[210:213], v[30:33]
	v_mfma_f32_16x16x32_bf16 v[26:29], v[202:205], v[210:213], v[26:29]
	v_mfma_f32_16x16x32_bf16 v[22:25], v[194:197], v[218:221], v[22:25]
	v_mfma_f32_16x16x32_bf16 v[18:21], v[202:205], v[218:221], v[18:21]
	v_mfma_f32_16x16x32_bf16 v[14:17], v[194:197], v[226:229], v[14:17]
	v_mfma_f32_16x16x32_bf16 v[10:13], v[202:205], v[226:229], v[10:13]
	v_mfma_f32_16x16x32_bf16 v[6:9], v[194:197], v[234:237], v[6:9]
	v_mfma_f32_16x16x32_bf16 v[0:3], v[202:205], v[234:237], v[0:3]
	v_mfma_f32_16x16x32_bf16 v[30:33], v[198:201], v[214:217], v[30:33]
	v_mfma_f32_16x16x32_bf16 v[26:29], v[206:209], v[214:217], v[26:29]
	v_mfma_f32_16x16x32_bf16 v[22:25], v[198:201], v[222:225], v[22:25]
	v_mfma_f32_16x16x32_bf16 v[18:21], v[206:209], v[222:225], v[18:21]
	v_mfma_f32_16x16x32_bf16 v[14:17], v[198:201], v[230:233], v[14:17]
	v_mfma_f32_16x16x32_bf16 v[10:13], v[206:209], v[230:233], v[10:13]
	v_mfma_f32_16x16x32_bf16 v[6:9], v[198:201], v[238:241], v[6:9]
	v_mfma_f32_16x16x32_bf16 v[0:3], v[206:209], v[238:241], v[0:3]
	s_barrier
	s_add_i32 s28, s28, 2
	s_add_u32 s22, s22, 0x100
	s_addc_u32 s23, s23, 0
	s_add_u32 s9, s9, 0x100
	s_addc_u32 s25, s25, 0
	s_cmp_gt_u32 s28, 29
	s_cbranch_scc0 .LBB0_124
	s_and_b64 vcc, exec, s[42:43]
	s_cbranch_vccz .LBB0_127
	s_barrier

.LBB0_162:
	s_ashr_i32 s49, s48, 31
	s_lshl_b64 s[2:3], s[48:49], 20
	v_readlane_b32 s4, v253, 61
	v_readlane_b32 s5, v253, 62
	s_add_u32 s82, s4, s2
	s_addc_u32 s83, s5, s3
	s_and_b64 s[2:3], s[42:43], exec
	s_cselect_b32 s2, s83, s1
	s_cselect_b32 s8, s82, s0
	s_add_u32 s22, s14, 0x80080
	s_addc_u32 s23, s15, 0
	s_add_u32 s9, s0, 0x100
	v_mov_b32_e32 v0, 0
	s_addc_u32 s10, s1, 0
	s_mov_b32 s24, -2
	v_mov_b32_e32 v1, v0
	v_mov_b32_e32 v2, v0
	v_mov_b32_e32 v3, v0
	v_mov_b32_e32 v6, v0
	s_waitcnt lgkmcnt(0)
	v_mov_b32_e32 v7, v0
	v_mov_b32_e32 v8, v0
	v_mov_b32_e32 v9, v0
	v_mov_b32_e32 v18, v0
	v_mov_b32_e32 v19, v0
	v_mov_b32_e32 v20, v0
	v_mov_b32_e32 v21, v0
	v_mov_b32_e32 v22, v0
	v_mov_b32_e32 v23, v0
	v_mov_b32_e32 v24, v0
	v_mov_b32_e32 v25, v0
	v_mov_b32_e32 v34, v0
	v_mov_b32_e32 v35, v0
	v_mov_b32_e32 v36, v0
	v_mov_b32_e32 v37, v0
	v_mov_b32_e32 v38, v0
	v_mov_b32_e32 v39, v0
	v_mov_b32_e32 v40, v0
	v_mov_b32_e32 v41, v0
	v_mov_b32_e32 v50, v0
	v_mov_b32_e32 v51, v0
	v_mov_b32_e32 v52, v0
	v_mov_b32_e32 v53, v0
	v_mov_b32_e32 v54, v0
	v_mov_b32_e32 v55, v0
	v_mov_b32_e32 v56, v0
	v_mov_b32_e32 v57, v0
	v_mov_b32_e32 v10, v0
	v_mov_b32_e32 v11, v0
	v_mov_b32_e32 v12, v0
	v_mov_b32_e32 v13, v0
	v_mov_b32_e32 v14, v0
	v_mov_b32_e32 v15, v0
	v_mov_b32_e32 v16, v0
	v_mov_b32_e32 v17, v0
	v_mov_b32_e32 v26, v0
	v_mov_b32_e32 v27, v0
	v_mov_b32_e32 v28, v0
	v_mov_b32_e32 v29, v0
	v_mov_b32_e32 v30, v0
	v_mov_b32_e32 v31, v0
	v_mov_b32_e32 v32, v0
	v_mov_b32_e32 v33, v0
	v_mov_b32_e32 v42, v0
	v_mov_b32_e32 v43, v0
	v_mov_b32_e32 v44, v0
	v_mov_b32_e32 v45, v0
	v_mov_b32_e32 v46, v0
	v_mov_b32_e32 v47, v0
	v_mov_b32_e32 v48, v0
	v_mov_b32_e32 v49, v0
	v_mov_b32_e32 v58, v0
	v_mov_b32_e32 v59, v0
	v_mov_b32_e32 v60, v0
	v_mov_b32_e32 v61, v0
	v_mov_b32_e32 v62, v0
	v_mov_b32_e32 v63, v0
	v_mov_b32_e32 v64, v0
	v_mov_b32_e32 v65, v0
	v_mov_b32_e32 v66, v0
	v_mov_b32_e32 v67, v0
	v_mov_b32_e32 v68, v0
	v_mov_b32_e32 v69, v0
	v_mov_b32_e32 v70, v0
	v_mov_b32_e32 v71, v0
	v_mov_b32_e32 v72, v0
	v_mov_b32_e32 v73, v0
	v_mov_b32_e32 v82, v0
	v_mov_b32_e32 v83, v0
	v_mov_b32_e32 v84, v0
	v_mov_b32_e32 v85, v0
	v_mov_b32_e32 v86, v0
	v_mov_b32_e32 v87, v0
	v_mov_b32_e32 v88, v0
	v_mov_b32_e32 v89, v0
	v_mov_b32_e32 v98, v0
	v_mov_b32_e32 v99, v0
	v_mov_b32_e32 v100, v0
	v_mov_b32_e32 v101, v0
	v_mov_b32_e32 v102, v0
	v_mov_b32_e32 v103, v0
	v_mov_b32_e32 v104, v0
	v_mov_b32_e32 v105, v0
	v_mov_b32_e32 v114, v0
	v_mov_b32_e32 v115, v0
	v_mov_b32_e32 v116, v0
	v_mov_b32_e32 v117, v0
	v_mov_b32_e32 v118, v0
	v_mov_b32_e32 v119, v0
	v_mov_b32_e32 v120, v0
	v_mov_b32_e32 v121, v0
	v_mov_b32_e32 v74, v0
	v_mov_b32_e32 v75, v0
	v_mov_b32_e32 v76, v0
	v_mov_b32_e32 v77, v0
	v_mov_b32_e32 v78, v0
	v_mov_b32_e32 v79, v0
	v_mov_b32_e32 v80, v0
	v_mov_b32_e32 v81, v0
	v_mov_b32_e32 v90, v0
	v_mov_b32_e32 v91, v0
	v_mov_b32_e32 v92, v0
	v_mov_b32_e32 v93, v0
	v_mov_b32_e32 v94, v0
	v_mov_b32_e32 v95, v0
	v_mov_b32_e32 v96, v0
	v_mov_b32_e32 v97, v0
	v_mov_b32_e32 v106, v0
	v_mov_b32_e32 v107, v0
	v_mov_b32_e32 v108, v0
	v_mov_b32_e32 v109, v0
	v_mov_b32_e32 v110, v0
	v_mov_b32_e32 v111, v0
	v_mov_b32_e32 v112, v0
	v_mov_b32_e32 v113, v0
	v_mov_b32_e32 v122, v0
	v_mov_b32_e32 v123, v0
	v_mov_b32_e32 v124, v0
	v_mov_b32_e32 v125, v0
	v_mov_b32_e32 v126, v0
	v_mov_b32_e32 v127, v0
	v_mov_b32_e32 v128, v0
	v_mov_b32_e32 v129, v0
	s_cmp_eq_u32 s37, 1
	s_cbranch_scc1 .LBB0_163
	s_add_u32 s0, s22, 0xfff80080
	s_addc_u32 s1, s23, -1
	s_add_i32 s3, 0, 0x10000
	s_cmp_eq_u32 s24, 28
	s_cselect_b32 s15, s79, s1
	s_cselect_b32 s14, s78, s0
	v_add_u32_e32 v162, s3, v145
	s_cselect_b32 s1, s2, s10
	s_cselect_b32 s0, s8, s9
	s_add_i32 s6, 0, 0x14000
	ds_read_b128 v[140:143], v162
	ds_read_b128 v[148:151], v162 offset:1024
	ds_read_b128 v[172:175], v162 offset:2048
	ds_read_b128 v[190:193], v162 offset:3072
	v_add_u32_e32 v162, s6, v145
	ds_read_b128 v[194:197], v162
	ds_read_b128 v[198:201], v162 offset:1024
	ds_read_b128 v[202:205], v162 offset:2048
	ds_read_b128 v[206:209], v162 offset:3072
	v_lshl_add_u64 v[162:163], s[22:23], 0, v[136:137]
	s_add_i32 m0, s26, 0xc000
	ds_read_b128 v[210:213], v147
	ds_read_b128 v[214:217], v147 offset:1024
	ds_read_b128 v[218:221], v147 offset:2048
	ds_read_b128 v[222:225], v147 offset:3072
	ds_read_b128 v[226:229], v147 offset:4096
	ds_read_b128 v[230:233], v147 offset:5120
	ds_read_b128 v[234:237], v147 offset:6144
	ds_read_b128 v[238:241], v147 offset:7168
	global_load_lds_dwordx4 v[162:163], off
	v_lshl_add_u64 v[162:163], s[22:23], 0, v[138:139]
	s_add_i32 m0, s26, 0xe000
	s_nop 0
	global_load_lds_dwordx4 v[162:163], off
	s_waitcnt vmcnt(24)
	s_waitcnt lgkmcnt(0)
	s_barrier
	s_waitcnt lgkmcnt(0)
	v_mfma_f32_16x16x32_bf16 v[126:129], v[140:143], v[210:213], v[126:129]
	v_mfma_f32_16x16x32_bf16 v[122:125], v[172:175], v[210:213], v[122:125]
	v_mfma_f32_16x16x32_bf16 v[110:113], v[140:143], v[218:221], v[110:113]
	v_mfma_f32_16x16x32_bf16 v[106:109], v[172:175], v[218:221], v[106:109]
	v_mfma_f32_16x16x32_bf16 v[94:97], v[140:143], v[226:229], v[94:97]
	v_mfma_f32_16x16x32_bf16 v[90:93], v[172:175], v[226:229], v[90:93]
	v_mfma_f32_16x16x32_bf16 v[78:81], v[140:143], v[234:237], v[78:81]
	v_mfma_f32_16x16x32_bf16 v[74:77], v[172:175], v[234:237], v[74:77]
	v_mfma_f32_16x16x32_bf16 v[126:129], v[148:151], v[214:217], v[126:129]
	v_mfma_f32_16x16x32_bf16 v[122:125], v[190:193], v[214:217], v[122:125]
	v_mfma_f32_16x16x32_bf16 v[110:113], v[148:151], v[222:225], v[110:113]
	v_mfma_f32_16x16x32_bf16 v[106:109], v[190:193], v[222:225], v[106:109]
	v_mfma_f32_16x16x32_bf16 v[94:97], v[148:151], v[230:233], v[94:97]
	v_mfma_f32_16x16x32_bf16 v[90:93], v[190:193], v[230:233], v[90:93]
	v_mfma_f32_16x16x32_bf16 v[78:81], v[148:151], v[238:241], v[78:81]
	v_mfma_f32_16x16x32_bf16 v[74:77], v[190:193], v[238:241], v[74:77]
	v_mfma_f32_16x16x32_bf16 v[118:121], v[194:197], v[210:213], v[118:121]
	v_mfma_f32_16x16x32_bf16 v[114:117], v[202:205], v[210:213], v[114:117]
	v_mfma_f32_16x16x32_bf16 v[102:105], v[194:197], v[218:221], v[102:105]
	v_mfma_f32_16x16x32_bf16 v[98:101], v[202:205], v[218:221], v[98:101]
	v_mfma_f32_16x16x32_bf16 v[86:89], v[194:197], v[226:229], v[86:89]
	v_mfma_f32_16x16x32_bf16 v[82:85], v[202:205], v[226:229], v[82:85]
	v_mfma_f32_16x16x32_bf16 v[70:73], v[194:197], v[234:237], v[70:73]
	v_mfma_f32_16x16x32_bf16 v[66:69], v[202:205], v[234:237], v[66:69]
	v_mfma_f32_16x16x32_bf16 v[118:121], v[198:201], v[214:217], v[118:121]
	v_mfma_f32_16x16x32_bf16 v[114:117], v[206:209], v[214:217], v[114:117]
	v_mfma_f32_16x16x32_bf16 v[102:105], v[198:201], v[222:225], v[102:105]
	v_mfma_f32_16x16x32_bf16 v[98:101], v[206:209], v[222:225], v[98:101]
	v_mfma_f32_16x16x32_bf16 v[86:89], v[198:201], v[230:233], v[86:89]
	v_mfma_f32_16x16x32_bf16 v[82:85], v[206:209], v[230:233], v[82:85]
	v_mfma_f32_16x16x32_bf16 v[70:73], v[198:201], v[238:241], v[70:73]
	v_mfma_f32_16x16x32_bf16 v[66:69], v[206:209], v[238:241], v[66:69]
	s_barrier
	s_add_i32 s3, s3, s11
	v_lshl_add_u64 v[162:163], s[0:1], 0, v[4:5]
	s_mov_b32 m0, s3
	ds_read_b128 v[210:213], v147 offset:16384
	ds_read_b128 v[214:217], v147 offset:17408
	ds_read_b128 v[218:221], v147 offset:18432
	ds_read_b128 v[222:225], v147 offset:19456
	ds_read_b128 v[226:229], v147 offset:20480
	ds_read_b128 v[230:233], v147 offset:21504
	ds_read_b128 v[234:237], v147 offset:22528
	ds_read_b128 v[238:241], v147 offset:23552
	global_load_lds_dwordx4 v[162:163], off
	s_add_i32 m0, s3, 0x2000
	s_add_u32 s4, s0, 0x80000
	v_lshl_add_u64 v[166:167], s[0:1], 0, v[130:131]
	s_addc_u32 s5, s1, 0
	s_add_i32 s3, s6, s11
	global_load_lds_dwordx4 v[166:167], off
	v_lshl_add_u64 v[176:177], s[4:5], 0, v[4:5]
	s_mov_b32 m0, s3
	v_lshl_add_u64 v[180:181], s[14:15], 0, v[132:133]
	global_load_lds_dwordx4 v[176:177], off
	v_lshl_add_u64 v[176:177], s[4:5], 0, v[130:131]
	s_add_i32 m0, s3, 0x2000
	s_nop 0
	global_load_lds_dwordx4 v[176:177], off
	v_lshl_add_u64 v[176:177], s[14:15], 0, v[134:135]
	s_mov_b32 m0, s26
	s_nop 0
	global_load_lds_dwordx4 v[176:177], off
	s_mov_b32 m0, s27
	s_nop 0
	global_load_lds_dwordx4 v[180:181], off
	s_waitcnt vmcnt(24)
	s_waitcnt lgkmcnt(0)
	s_barrier
	s_waitcnt lgkmcnt(0)
	v_mfma_f32_16x16x32_bf16 v[62:65], v[140:143], v[210:213], v[62:65]
	v_mfma_f32_16x16x32_bf16 v[58:61], v[172:175], v[210:213], v[58:61]
	v_mfma_f32_16x16x32_bf16 v[46:49], v[140:143], v[218:221], v[46:49]
	v_mfma_f32_16x16x32_bf16 v[42:45], v[172:175], v[218:221], v[42:45]
	v_mfma_f32_16x16x32_bf16 v[30:33], v[140:143], v[226:229], v[30:33]
	v_mfma_f32_16x16x32_bf16 v[26:29], v[172:175], v[226:229], v[26:29]
	v_mfma_f32_16x16x32_bf16 v[14:17], v[140:143], v[234:237], v[14:17]
	v_mfma_f32_16x16x32_bf16 v[10:13], v[172:175], v[234:237], v[10:13]
	v_mfma_f32_16x16x32_bf16 v[62:65], v[148:151], v[214:217], v[62:65]
	v_mfma_f32_16x16x32_bf16 v[58:61], v[190:193], v[214:217], v[58:61]
	v_mfma_f32_16x16x32_bf16 v[46:49], v[148:151], v[222:225], v[46:49]
	v_mfma_f32_16x16x32_bf16 v[42:45], v[190:193], v[222:225], v[42:45]
	v_mfma_f32_16x16x32_bf16 v[30:33], v[148:151], v[230:233], v[30:33]
	v_mfma_f32_16x16x32_bf16 v[26:29], v[190:193], v[230:233], v[26:29]
	v_mfma_f32_16x16x32_bf16 v[14:17], v[148:151], v[238:241], v[14:17]
	v_mfma_f32_16x16x32_bf16 v[10:13], v[190:193], v[238:241], v[10:13]
	v_mfma_f32_16x16x32_bf16 v[54:57], v[194:197], v[210:213], v[54:57]
	v_mfma_f32_16x16x32_bf16 v[50:53], v[202:205], v[210:213], v[50:53]
	v_mfma_f32_16x16x32_bf16 v[38:41], v[194:197], v[218:221], v[38:41]
	v_mfma_f32_16x16x32_bf16 v[34:37], v[202:205], v[218:221], v[34:37]
	v_mfma_f32_16x16x32_bf16 v[22:25], v[194:197], v[226:229], v[22:25]
	v_mfma_f32_16x16x32_bf16 v[18:21], v[202:205], v[226:229], v[18:21]
	v_mfma_f32_16x16x32_bf16 v[6:9], v[194:197], v[234:237], v[6:9]
	v_mfma_f32_16x16x32_bf16 v[0:3], v[202:205], v[234:237], v[0:3]
	v_mfma_f32_16x16x32_bf16 v[54:57], v[198:201], v[214:217], v[54:57]
	v_mfma_f32_16x16x32_bf16 v[50:53], v[206:209], v[214:217], v[50:53]
	v_mfma_f32_16x16x32_bf16 v[38:41], v[198:201], v[222:225], v[38:41]
	v_mfma_f32_16x16x32_bf16 v[34:37], v[206:209], v[222:225], v[34:37]
	v_mfma_f32_16x16x32_bf16 v[22:25], v[198:201], v[230:233], v[22:25]
	v_mfma_f32_16x16x32_bf16 v[18:21], v[206:209], v[230:233], v[18:21]
	v_mfma_f32_16x16x32_bf16 v[6:9], v[198:201], v[238:241], v[6:9]
	v_mfma_f32_16x16x32_bf16 v[0:3], v[206:209], v[238:241], v[0:3]
	s_barrier
	s_branch .Lpeelmid_163
.LBB0_163:
	s_add_u32 s0, s22, 0xfff80080
	s_addc_u32 s1, s23, -1
	s_add_i32 s3, 0, 0x10000
	s_cmp_eq_u32 s24, 28
	s_cselect_b32 s15, s79, s1
	s_cselect_b32 s14, s78, s0
	v_add_u32_e32 v162, s3, v145
	s_cselect_b32 s1, s2, s10
	s_cselect_b32 s0, s8, s9
	s_add_i32 s6, 0, 0x14000
	ds_read_b128 v[140:143], v162
	ds_read_b128 v[148:151], v162 offset:1024
	ds_read_b128 v[172:175], v162 offset:2048
	ds_read_b128 v[190:193], v162 offset:3072
	v_add_u32_e32 v162, s6, v145
	ds_read_b128 v[194:197], v162
	ds_read_b128 v[198:201], v162 offset:1024
	ds_read_b128 v[202:205], v162 offset:2048
	ds_read_b128 v[206:209], v162 offset:3072
	v_lshl_add_u64 v[162:163], s[22:23], 0, v[136:137]
	s_add_i32 m0, s26, 0xc000
	ds_read_b128 v[210:213], v147
	ds_read_b128 v[214:217], v147 offset:1024
	ds_read_b128 v[218:221], v147 offset:2048
	ds_read_b128 v[222:225], v147 offset:3072
	ds_read_b128 v[226:229], v147 offset:4096
	ds_read_b128 v[230:233], v147 offset:5120
	ds_read_b128 v[234:237], v147 offset:6144
	ds_read_b128 v[238:241], v147 offset:7168
	global_load_lds_dwordx4 v[162:163], off
	v_lshl_add_u64 v[162:163], s[22:23], 0, v[138:139]
	s_add_i32 m0, s26, 0xe000
	s_nop 0
	global_load_lds_dwordx4 v[162:163], off
	s_waitcnt vmcnt(8)
	s_waitcnt lgkmcnt(0)
	s_barrier
	s_waitcnt lgkmcnt(0)
	v_mfma_f32_16x16x32_bf16 v[126:129], v[140:143], v[210:213], v[126:129]
	v_mfma_f32_16x16x32_bf16 v[122:125], v[172:175], v[210:213], v[122:125]
	v_mfma_f32_16x16x32_bf16 v[110:113], v[140:143], v[218:221], v[110:113]
	v_mfma_f32_16x16x32_bf16 v[106:109], v[172:175], v[218:221], v[106:109]
	v_mfma_f32_16x16x32_bf16 v[94:97], v[140:143], v[226:229], v[94:97]
	v_mfma_f32_16x16x32_bf16 v[90:93], v[172:175], v[226:229], v[90:93]
	v_mfma_f32_16x16x32_bf16 v[78:81], v[140:143], v[234:237], v[78:81]
	v_mfma_f32_16x16x32_bf16 v[74:77], v[172:175], v[234:237], v[74:77]
	v_mfma_f32_16x16x32_bf16 v[126:129], v[148:151], v[214:217], v[126:129]
	v_mfma_f32_16x16x32_bf16 v[122:125], v[190:193], v[214:217], v[122:125]
	v_mfma_f32_16x16x32_bf16 v[110:113], v[148:151], v[222:225], v[110:113]
	v_mfma_f32_16x16x32_bf16 v[106:109], v[190:193], v[222:225], v[106:109]
	v_mfma_f32_16x16x32_bf16 v[94:97], v[148:151], v[230:233], v[94:97]
	v_mfma_f32_16x16x32_bf16 v[90:93], v[190:193], v[230:233], v[90:93]
	v_mfma_f32_16x16x32_bf16 v[78:81], v[148:151], v[238:241], v[78:81]
	v_mfma_f32_16x16x32_bf16 v[74:77], v[190:193], v[238:241], v[74:77]
	v_mfma_f32_16x16x32_bf16 v[118:121], v[194:197], v[210:213], v[118:121]
	v_mfma_f32_16x16x32_bf16 v[114:117], v[202:205], v[210:213], v[114:117]
	v_mfma_f32_16x16x32_bf16 v[102:105], v[194:197], v[218:221], v[102:105]
	v_mfma_f32_16x16x32_bf16 v[98:101], v[202:205], v[218:221], v[98:101]
	v_mfma_f32_16x16x32_bf16 v[86:89], v[194:197], v[226:229], v[86:89]
	v_mfma_f32_16x16x32_bf16 v[82:85], v[202:205], v[226:229], v[82:85]
	v_mfma_f32_16x16x32_bf16 v[70:73], v[194:197], v[234:237], v[70:73]
	v_mfma_f32_16x16x32_bf16 v[66:69], v[202:205], v[234:237], v[66:69]
	v_mfma_f32_16x16x32_bf16 v[118:121], v[198:201], v[214:217], v[118:121]
	v_mfma_f32_16x16x32_bf16 v[114:117], v[206:209], v[214:217], v[114:117]
	v_mfma_f32_16x16x32_bf16 v[102:105], v[198:201], v[222:225], v[102:105]
	v_mfma_f32_16x16x32_bf16 v[98:101], v[206:209], v[222:225], v[98:101]
	v_mfma_f32_16x16x32_bf16 v[86:89], v[198:201], v[230:233], v[86:89]
	v_mfma_f32_16x16x32_bf16 v[82:85], v[206:209], v[230:233], v[82:85]
	v_mfma_f32_16x16x32_bf16 v[70:73], v[198:201], v[238:241], v[70:73]
	v_mfma_f32_16x16x32_bf16 v[66:69], v[206:209], v[238:241], v[66:69]
	s_barrier
	s_add_i32 s3, s3, s11
	v_lshl_add_u64 v[162:163], s[0:1], 0, v[4:5]
	s_mov_b32 m0, s3
	ds_read_b128 v[210:213], v147 offset:16384
	ds_read_b128 v[214:217], v147 offset:17408
	ds_read_b128 v[218:221], v147 offset:18432
	ds_read_b128 v[222:225], v147 offset:19456
	ds_read_b128 v[226:229], v147 offset:20480
	ds_read_b128 v[230:233], v147 offset:21504
	ds_read_b128 v[234:237], v147 offset:22528
	ds_read_b128 v[238:241], v147 offset:23552
	global_load_lds_dwordx4 v[162:163], off
	s_add_i32 m0, s3, 0x2000
	s_add_u32 s4, s0, 0x80000
	v_lshl_add_u64 v[166:167], s[0:1], 0, v[130:131]
	s_addc_u32 s5, s1, 0
	s_add_i32 s3, s6, s11
	global_load_lds_dwordx4 v[166:167], off
	v_lshl_add_u64 v[176:177], s[4:5], 0, v[4:5]
	s_mov_b32 m0, s3
	v_lshl_add_u64 v[180:181], s[14:15], 0, v[132:133]
	global_load_lds_dwordx4 v[176:177], off
	v_lshl_add_u64 v[176:177], s[4:5], 0, v[130:131]
	s_add_i32 m0, s3, 0x2000
	s_nop 0
	global_load_lds_dwordx4 v[176:177], off
	v_lshl_add_u64 v[176:177], s[14:15], 0, v[134:135]
	s_mov_b32 m0, s26
	s_nop 0
	global_load_lds_dwordx4 v[176:177], off
	s_mov_b32 m0, s27
	s_nop 0
	global_load_lds_dwordx4 v[180:181], off
	s_waitcnt vmcnt(8)
	s_waitcnt lgkmcnt(0)
	s_barrier
	s_waitcnt lgkmcnt(0)
	v_mfma_f32_16x16x32_bf16 v[62:65], v[140:143], v[210:213], v[62:65]
	v_mfma_f32_16x16x32_bf16 v[58:61], v[172:175], v[210:213], v[58:61]
	v_mfma_f32_16x16x32_bf16 v[46:49], v[140:143], v[218:221], v[46:49]
	v_mfma_f32_16x16x32_bf16 v[42:45], v[172:175], v[218:221], v[42:45]
	v_mfma_f32_16x16x32_bf16 v[30:33], v[140:143], v[226:229], v[30:33]
	v_mfma_f32_16x16x32_bf16 v[26:29], v[172:175], v[226:229], v[26:29]
	v_mfma_f32_16x16x32_bf16 v[14:17], v[140:143], v[234:237], v[14:17]
	v_mfma_f32_16x16x32_bf16 v[10:13], v[172:175], v[234:237], v[10:13]
	v_mfma_f32_16x16x32_bf16 v[62:65], v[148:151], v[214:217], v[62:65]
	v_mfma_f32_16x16x32_bf16 v[58:61], v[190:193], v[214:217], v[58:61]
	v_mfma_f32_16x16x32_bf16 v[46:49], v[148:151], v[222:225], v[46:49]
	v_mfma_f32_16x16x32_bf16 v[42:45], v[190:193], v[222:225], v[42:45]
	v_mfma_f32_16x16x32_bf16 v[30:33], v[148:151], v[230:233], v[30:33]
	v_mfma_f32_16x16x32_bf16 v[26:29], v[190:193], v[230:233], v[26:29]
	v_mfma_f32_16x16x32_bf16 v[14:17], v[148:151], v[238:241], v[14:17]
	v_mfma_f32_16x16x32_bf16 v[10:13], v[190:193], v[238:241], v[10:13]
	v_mfma_f32_16x16x32_bf16 v[54:57], v[194:197], v[210:213], v[54:57]
	v_mfma_f32_16x16x32_bf16 v[50:53], v[202:205], v[210:213], v[50:53]
	v_mfma_f32_16x16x32_bf16 v[38:41], v[194:197], v[218:221], v[38:41]
	v_mfma_f32_16x16x32_bf16 v[34:37], v[202:205], v[218:221], v[34:37]
	v_mfma_f32_16x16x32_bf16 v[22:25], v[194:197], v[226:229], v[22:25]
	v_mfma_f32_16x16x32_bf16 v[18:21], v[202:205], v[226:229], v[18:21]
	v_mfma_f32_16x16x32_bf16 v[6:9], v[194:197], v[234:237], v[6:9]
	v_mfma_f32_16x16x32_bf16 v[0:3], v[202:205], v[234:237], v[0:3]
	v_mfma_f32_16x16x32_bf16 v[54:57], v[198:201], v[214:217], v[54:57]
	v_mfma_f32_16x16x32_bf16 v[50:53], v[206:209], v[214:217], v[50:53]
	v_mfma_f32_16x16x32_bf16 v[38:41], v[198:201], v[222:225], v[38:41]
	v_mfma_f32_16x16x32_bf16 v[34:37], v[206:209], v[222:225], v[34:37]
	v_mfma_f32_16x16x32_bf16 v[22:25], v[198:201], v[230:233], v[22:25]
	v_mfma_f32_16x16x32_bf16 v[18:21], v[206:209], v[230:233], v[18:21]
	v_mfma_f32_16x16x32_bf16 v[6:9], v[198:201], v[238:241], v[6:9]
	v_mfma_f32_16x16x32_bf16 v[0:3], v[206:209], v[238:241], v[0:3]
	s_barrier
.Lpeelmid_163:
	s_add_i32 s3, 0, 0x18000
	v_add_u32_e32 v164, s3, v145
	s_add_i32 s6, 0, 0x1c000
	ds_read_b128 v[140:143], v164
	ds_read_b128 v[148:151], v164 offset:1024
	ds_read_b128 v[172:175], v164 offset:2048
	ds_read_b128 v[190:193], v164 offset:3072
	v_add_u32_e32 v164, s6, v145
	ds_read_b128 v[194:197], v164
	ds_read_b128 v[198:201], v164 offset:1024
	ds_read_b128 v[202:205], v164 offset:2048
	ds_read_b128 v[206:209], v164 offset:3072
	s_add_u32 s4, s14, 0x80000
	s_addc_u32 s5, s15, 0
	s_mov_b32 m0, s30
	v_lshl_add_u64 v[242:243], s[4:5], 0, v[134:135]
	ds_read_b128 v[210:213], v147 offset:32768
	ds_read_b128 v[214:217], v147 offset:33792
	ds_read_b128 v[218:221], v147 offset:34816
	ds_read_b128 v[222:225], v147 offset:35840
	ds_read_b128 v[226:229], v147 offset:36864
	ds_read_b128 v[230:233], v147 offset:37888
	ds_read_b128 v[234:237], v147 offset:38912
	ds_read_b128 v[238:241], v147 offset:39936
	global_load_lds_dwordx4 v[242:243], off
	v_lshl_add_u64 v[242:243], s[4:5], 0, v[132:133]
	s_mov_b32 m0, s31
	s_nop 0
	global_load_lds_dwordx4 v[242:243], off
	s_waitcnt vmcnt(8)
	s_waitcnt lgkmcnt(0)
	s_barrier
	s_waitcnt lgkmcnt(0)
	v_mfma_f32_16x16x32_bf16 v[126:129], v[140:143], v[210:213], v[126:129]
	v_mfma_f32_16x16x32_bf16 v[122:125], v[172:175], v[210:213], v[122:125]
	v_mfma_f32_16x16x32_bf16 v[110:113], v[140:143], v[218:221], v[110:113]
	v_mfma_f32_16x16x32_bf16 v[106:109], v[172:175], v[218:221], v[106:109]
	v_mfma_f32_16x16x32_bf16 v[94:97], v[140:143], v[226:229], v[94:97]
	v_mfma_f32_16x16x32_bf16 v[90:93], v[172:175], v[226:229], v[90:93]
	v_mfma_f32_16x16x32_bf16 v[78:81], v[140:143], v[234:237], v[78:81]
	v_mfma_f32_16x16x32_bf16 v[74:77], v[172:175], v[234:237], v[74:77]
	v_mfma_f32_16x16x32_bf16 v[126:129], v[148:151], v[214:217], v[126:129]
	v_mfma_f32_16x16x32_bf16 v[122:125], v[190:193], v[214:217], v[122:125]
	v_mfma_f32_16x16x32_bf16 v[110:113], v[148:151], v[222:225], v[110:113]
	v_mfma_f32_16x16x32_bf16 v[106:109], v[190:193], v[222:225], v[106:109]
	v_mfma_f32_16x16x32_bf16 v[94:97], v[148:151], v[230:233], v[94:97]
	v_mfma_f32_16x16x32_bf16 v[90:93], v[190:193], v[230:233], v[90:93]
	v_mfma_f32_16x16x32_bf16 v[78:81], v[148:151], v[238:241], v[78:81]
	v_mfma_f32_16x16x32_bf16 v[74:77], v[190:193], v[238:241], v[74:77]
	v_mfma_f32_16x16x32_bf16 v[118:121], v[194:197], v[210:213], v[118:121]
	v_mfma_f32_16x16x32_bf16 v[114:117], v[202:205], v[210:213], v[114:117]
	v_mfma_f32_16x16x32_bf16 v[102:105], v[194:197], v[218:221], v[102:105]
	v_mfma_f32_16x16x32_bf16 v[98:101], v[202:205], v[218:221], v[98:101]
	v_mfma_f32_16x16x32_bf16 v[86:89], v[194:197], v[226:229], v[86:89]
	v_mfma_f32_16x16x32_bf16 v[82:85], v[202:205], v[226:229], v[82:85]
	v_mfma_f32_16x16x32_bf16 v[70:73], v[194:197], v[234:237], v[70:73]
	v_mfma_f32_16x16x32_bf16 v[66:69], v[202:205], v[234:237], v[66:69]
	v_mfma_f32_16x16x32_bf16 v[118:121], v[198:201], v[214:217], v[118:121]
	v_mfma_f32_16x16x32_bf16 v[114:117], v[206:209], v[214:217], v[114:117]
	v_mfma_f32_16x16x32_bf16 v[102:105], v[198:201], v[222:225], v[102:105]
	v_mfma_f32_16x16x32_bf16 v[98:101], v[206:209], v[222:225], v[98:101]
	v_mfma_f32_16x16x32_bf16 v[86:89], v[198:201], v[230:233], v[86:89]
	v_mfma_f32_16x16x32_bf16 v[82:85], v[206:209], v[230:233], v[82:85]
	v_mfma_f32_16x16x32_bf16 v[70:73], v[198:201], v[238:241], v[70:73]
	v_mfma_f32_16x16x32_bf16 v[66:69], v[206:209], v[238:241], v[66:69]
	s_barrier
	s_add_i32 s3, s3, s11
	v_lshl_add_u64 v[162:163], v[162:163], 0, s[70:71]
	s_mov_b32 m0, s3
	ds_read_b128 v[210:213], v147 offset:49152
	ds_read_b128 v[214:217], v147 offset:50176
	ds_read_b128 v[218:221], v147 offset:51200
	ds_read_b128 v[222:225], v147 offset:52224
	ds_read_b128 v[226:229], v147 offset:53248
	ds_read_b128 v[230:233], v147 offset:54272
	ds_read_b128 v[234:237], v147 offset:55296
	ds_read_b128 v[238:241], v147 offset:56320
	global_load_lds_dwordx4 v[162:163], off
	s_add_i32 m0, s3, 0x2000
	s_add_u32 s0, s0, 0x80080
	v_lshl_add_u64 v[162:163], v[166:167], 0, s[70:71]
	s_addc_u32 s1, s1, 0
	s_add_i32 s3, s6, s11
	global_load_lds_dwordx4 v[162:163], off
	v_lshl_add_u64 v[162:163], s[0:1], 0, v[4:5]
	s_mov_b32 m0, s3
	s_nop 0
	global_load_lds_dwordx4 v[162:163], off
	v_lshl_add_u64 v[162:163], s[0:1], 0, v[130:131]
	s_add_i32 m0, s3, 0x2000
	s_nop 0
	global_load_lds_dwordx4 v[162:163], off
	v_lshl_add_u64 v[162:163], v[176:177], 0, s[70:71]
	s_mov_b32 m0, s35
	s_nop 0
	global_load_lds_dwordx4 v[162:163], off
	v_lshl_add_u64 v[162:163], v[180:181], 0, s[70:71]
	s_mov_b32 m0, s36
	s_nop 0
	global_load_lds_dwordx4 v[162:163], off
	s_waitcnt vmcnt(8)
	s_waitcnt lgkmcnt(0)
	s_barrier
	s_waitcnt lgkmcnt(0)
	v_mfma_f32_16x16x32_bf16 v[62:65], v[140:143], v[210:213], v[62:65]
	v_mfma_f32_16x16x32_bf16 v[58:61], v[172:175], v[210:213], v[58:61]
	v_mfma_f32_16x16x32_bf16 v[46:49], v[140:143], v[218:221], v[46:49]
	v_mfma_f32_16x16x32_bf16 v[42:45], v[172:175], v[218:221], v[42:45]
	v_mfma_f32_16x16x32_bf16 v[30:33], v[140:143], v[226:229], v[30:33]
	v_mfma_f32_16x16x32_bf16 v[26:29], v[172:175], v[226:229], v[26:29]
	v_mfma_f32_16x16x32_bf16 v[14:17], v[140:143], v[234:237], v[14:17]
	v_mfma_f32_16x16x32_bf16 v[10:13], v[172:175], v[234:237], v[10:13]
	v_mfma_f32_16x16x32_bf16 v[62:65], v[148:151], v[214:217], v[62:65]
	v_mfma_f32_16x16x32_bf16 v[58:61], v[190:193], v[214:217], v[58:61]
	v_mfma_f32_16x16x32_bf16 v[46:49], v[148:151], v[222:225], v[46:49]
	v_mfma_f32_16x16x32_bf16 v[42:45], v[190:193], v[222:225], v[42:45]
	v_mfma_f32_16x16x32_bf16 v[30:33], v[148:151], v[230:233], v[30:33]
	v_mfma_f32_16x16x32_bf16 v[26:29], v[190:193], v[230:233], v[26:29]
	v_mfma_f32_16x16x32_bf16 v[14:17], v[148:151], v[238:241], v[14:17]
	v_mfma_f32_16x16x32_bf16 v[10:13], v[190:193], v[238:241], v[10:13]
	v_mfma_f32_16x16x32_bf16 v[54:57], v[194:197], v[210:213], v[54:57]
	v_mfma_f32_16x16x32_bf16 v[50:53], v[202:205], v[210:213], v[50:53]
	v_mfma_f32_16x16x32_bf16 v[38:41], v[194:197], v[218:221], v[38:41]
	v_mfma_f32_16x16x32_bf16 v[34:37], v[202:205], v[218:221], v[34:37]
	v_mfma_f32_16x16x32_bf16 v[22:25], v[194:197], v[226:229], v[22:25]
	v_mfma_f32_16x16x32_bf16 v[18:21], v[202:205], v[226:229], v[18:21]
	v_mfma_f32_16x16x32_bf16 v[6:9], v[194:197], v[234:237], v[6:9]
	v_mfma_f32_16x16x32_bf16 v[0:3], v[202:205], v[234:237], v[0:3]
	v_mfma_f32_16x16x32_bf16 v[54:57], v[198:201], v[214:217], v[54:57]
	v_mfma_f32_16x16x32_bf16 v[50:53], v[206:209], v[214:217], v[50:53]
	v_mfma_f32_16x16x32_bf16 v[38:41], v[198:201], v[222:225], v[38:41]
	v_mfma_f32_16x16x32_bf16 v[34:37], v[206:209], v[222:225], v[34:37]
	v_mfma_f32_16x16x32_bf16 v[22:25], v[198:201], v[230:233], v[22:25]
	v_mfma_f32_16x16x32_bf16 v[18:21], v[206:209], v[230:233], v[18:21]
	v_mfma_f32_16x16x32_bf16 v[6:9], v[198:201], v[238:241], v[6:9]
	v_mfma_f32_16x16x32_bf16 v[0:3], v[206:209], v[238:241], v[0:3]
	s_barrier
	s_add_i32 s24, s24, 2
	s_add_u32 s22, s22, 0x100
	s_addc_u32 s23, s23, 0
	s_add_u32 s9, s9, 0x100
	s_addc_u32 s10, s10, 0
	s_cmp_gt_u32 s24, 29
	s_cbranch_scc0 .LBB0_163
	s_and_b64 vcc, exec, s[46:47]
	s_cbranch_vccz .LBB0_166
	s_barrier

.LBB0_204:
	s_ashr_i32 s49, s48, 31
	s_lshl_b64 s[2:3], s[48:49], 19
	v_readlane_b32 s4, v253, 17
	v_readlane_b32 s5, v253, 18
	s_add_u32 s84, s4, s2
	s_addc_u32 s85, s5, s3
	s_and_b64 s[2:3], s[42:43], exec
	s_cselect_b32 s2, s85, s15
	s_cselect_b32 s8, s84, s14
	s_add_u32 s22, s0, 0x40080
	s_addc_u32 s23, s1, 0
	s_add_u32 s9, s14, 0x100
	v_mov_b32_e32 v0, 0
	s_addc_u32 s10, s15, 0
	s_mov_b32 s24, -2
	v_mov_b32_e32 v1, v0
	v_mov_b32_e32 v2, v0
	v_mov_b32_e32 v3, v0
	v_mov_b32_e32 v6, v0
	v_mov_b32_e32 v7, v0
	v_mov_b32_e32 v8, v0
	v_mov_b32_e32 v9, v0
	v_mov_b32_e32 v10, v0
	v_mov_b32_e32 v11, v0
	v_mov_b32_e32 v12, v0
	v_mov_b32_e32 v13, v0
	v_mov_b32_e32 v14, v0
	v_mov_b32_e32 v15, v0
	v_mov_b32_e32 v16, v0
	v_mov_b32_e32 v17, v0
	v_mov_b32_e32 v18, v0
	v_mov_b32_e32 v19, v0
	v_mov_b32_e32 v20, v0
	v_mov_b32_e32 v21, v0
	v_mov_b32_e32 v22, v0
	v_mov_b32_e32 v23, v0
	v_mov_b32_e32 v24, v0
	v_mov_b32_e32 v25, v0
	v_mov_b32_e32 v26, v0
	v_mov_b32_e32 v27, v0
	v_mov_b32_e32 v28, v0
	v_mov_b32_e32 v29, v0
	v_mov_b32_e32 v30, v0
	v_mov_b32_e32 v31, v0
	v_mov_b32_e32 v32, v0
	v_mov_b32_e32 v33, v0
	v_mov_b32_e32 v66, v0
	v_mov_b32_e32 v67, v0
	v_mov_b32_e32 v68, v0
	v_mov_b32_e32 v69, v0
	v_mov_b32_e32 v70, v0
	v_mov_b32_e32 v71, v0
	v_mov_b32_e32 v72, v0
	v_mov_b32_e32 v73, v0
	v_mov_b32_e32 v74, v0
	v_mov_b32_e32 v75, v0
	v_mov_b32_e32 v76, v0
	v_mov_b32_e32 v77, v0
	v_mov_b32_e32 v78, v0
	v_mov_b32_e32 v79, v0
	v_mov_b32_e32 v80, v0
	v_mov_b32_e32 v81, v0
	v_mov_b32_e32 v82, v0
	v_mov_b32_e32 v83, v0
	v_mov_b32_e32 v84, v0
	v_mov_b32_e32 v85, v0
	v_mov_b32_e32 v86, v0
	v_mov_b32_e32 v87, v0
	v_mov_b32_e32 v88, v0
	v_mov_b32_e32 v89, v0
	v_mov_b32_e32 v90, v0
	v_mov_b32_e32 v91, v0
	v_mov_b32_e32 v92, v0
	v_mov_b32_e32 v93, v0
	v_mov_b32_e32 v94, v0
	v_mov_b32_e32 v95, v0
	v_mov_b32_e32 v96, v0
	v_mov_b32_e32 v97, v0
	v_mov_b32_e32 v34, v0
	v_mov_b32_e32 v35, v0
	v_mov_b32_e32 v36, v0
	v_mov_b32_e32 v37, v0
	v_mov_b32_e32 v38, v0
	v_mov_b32_e32 v39, v0
	v_mov_b32_e32 v40, v0
	v_mov_b32_e32 v41, v0
	v_mov_b32_e32 v42, v0
	v_mov_b32_e32 v43, v0
	v_mov_b32_e32 v44, v0
	v_mov_b32_e32 v45, v0
	v_mov_b32_e32 v46, v0
	v_mov_b32_e32 v47, v0
	v_mov_b32_e32 v48, v0
	v_mov_b32_e32 v49, v0
	v_mov_b32_e32 v50, v0
	v_mov_b32_e32 v51, v0
	v_mov_b32_e32 v52, v0
	v_mov_b32_e32 v53, v0
	v_mov_b32_e32 v54, v0
	v_mov_b32_e32 v55, v0
	v_mov_b32_e32 v56, v0
	v_mov_b32_e32 v57, v0
	v_mov_b32_e32 v58, v0
	v_mov_b32_e32 v59, v0
	v_mov_b32_e32 v60, v0
	v_mov_b32_e32 v61, v0
	v_mov_b32_e32 v62, v0
	v_mov_b32_e32 v63, v0
	v_mov_b32_e32 v64, v0
	v_mov_b32_e32 v65, v0
	v_mov_b32_e32 v98, v0
	v_mov_b32_e32 v99, v0
	v_mov_b32_e32 v100, v0
	v_mov_b32_e32 v101, v0
	v_mov_b32_e32 v102, v0
	v_mov_b32_e32 v103, v0
	v_mov_b32_e32 v104, v0
	v_mov_b32_e32 v105, v0
	v_mov_b32_e32 v106, v0
	v_mov_b32_e32 v107, v0
	v_mov_b32_e32 v108, v0
	v_mov_b32_e32 v109, v0
	v_mov_b32_e32 v110, v0
	v_mov_b32_e32 v111, v0
	v_mov_b32_e32 v112, v0
	v_mov_b32_e32 v113, v0
	v_mov_b32_e32 v114, v0
	v_mov_b32_e32 v115, v0
	v_mov_b32_e32 v116, v0
	v_mov_b32_e32 v117, v0
	v_mov_b32_e32 v118, v0
	v_mov_b32_e32 v119, v0
	v_mov_b32_e32 v120, v0
	v_mov_b32_e32 v121, v0
	v_mov_b32_e32 v122, v0
	v_mov_b32_e32 v123, v0
	v_mov_b32_e32 v124, v0
	v_mov_b32_e32 v125, v0
	v_mov_b32_e32 v126, v0
	v_mov_b32_e32 v127, v0
	v_mov_b32_e32 v128, v0
	v_mov_b32_e32 v129, v0
	s_cmp_eq_u32 s37, 1
	s_cbranch_scc1 .LBB0_205
	s_add_u32 s0, s22, 0xfffc0080
	s_addc_u32 s1, s23, -1
	s_add_i32 s3, 0, 0x10000
	s_cmp_eq_u32 s24, 12
	s_cselect_b32 s15, s83, s1
	s_cselect_b32 s14, s82, s0
	v_add_u32_e32 v144, s3, v168
	s_cselect_b32 s1, s2, s10
	s_cselect_b32 s0, s8, s9
	s_add_i32 s6, 0, 0x14000
	ds_read_b128 v[140:143], v144
	ds_read_b128 v[174:177], v144 offset:1024
	ds_read_b128 v[190:193], v144 offset:2048
	ds_read_b128 v[194:197], v144 offset:3072
	v_add_u32_e32 v144, s6, v168
	ds_read_b128 v[198:201], v144
	ds_read_b128 v[202:205], v144 offset:1024
	ds_read_b128 v[206:209], v144 offset:2048
	ds_read_b128 v[210:213], v144 offset:3072
	v_lshl_add_u64 v[144:145], s[22:23], 0, v[136:137]
	s_add_i32 m0, s27, 0xc000
	ds_read_b128 v[214:217], v172
	ds_read_b128 v[218:221], v172 offset:1024
	ds_read_b128 v[222:225], v172 offset:2048
	ds_read_b128 v[226:229], v172 offset:3072
	ds_read_b128 v[230:233], v172 offset:4096
	ds_read_b128 v[234:237], v172 offset:5120
	ds_read_b128 v[238:241], v172 offset:6144
	ds_read_b128 v[242:245], v172 offset:7168
	global_load_lds_dwordx4 v[144:145], off
	v_lshl_add_u64 v[144:145], s[22:23], 0, v[138:139]
	s_add_i32 m0, s27, 0xe000
	s_nop 0
	global_load_lds_dwordx4 v[144:145], off
	s_waitcnt vmcnt(24)
	s_waitcnt lgkmcnt(0)
	s_barrier
	s_waitcnt lgkmcnt(0)
	v_mfma_f32_16x16x32_bf16 v[126:129], v[140:143], v[214:217], v[126:129]
	v_mfma_f32_16x16x32_bf16 v[122:125], v[190:193], v[214:217], v[122:125]
	v_mfma_f32_16x16x32_bf16 v[118:121], v[140:143], v[222:225], v[118:121]
	v_mfma_f32_16x16x32_bf16 v[114:117], v[190:193], v[222:225], v[114:117]
	v_mfma_f32_16x16x32_bf16 v[110:113], v[140:143], v[230:233], v[110:113]
	v_mfma_f32_16x16x32_bf16 v[106:109], v[190:193], v[230:233], v[106:109]
	v_mfma_f32_16x16x32_bf16 v[102:105], v[140:143], v[238:241], v[102:105]
	v_mfma_f32_16x16x32_bf16 v[98:101], v[190:193], v[238:241], v[98:101]
	v_mfma_f32_16x16x32_bf16 v[126:129], v[174:177], v[218:221], v[126:129]
	v_mfma_f32_16x16x32_bf16 v[122:125], v[194:197], v[218:221], v[122:125]
	v_mfma_f32_16x16x32_bf16 v[118:121], v[174:177], v[226:229], v[118:121]
	v_mfma_f32_16x16x32_bf16 v[114:117], v[194:197], v[226:229], v[114:117]
	v_mfma_f32_16x16x32_bf16 v[110:113], v[174:177], v[234:237], v[110:113]
	v_mfma_f32_16x16x32_bf16 v[106:109], v[194:197], v[234:237], v[106:109]
	v_mfma_f32_16x16x32_bf16 v[102:105], v[174:177], v[242:245], v[102:105]
	v_mfma_f32_16x16x32_bf16 v[98:101], v[194:197], v[242:245], v[98:101]
	v_mfma_f32_16x16x32_bf16 v[62:65], v[198:201], v[214:217], v[62:65]
	v_mfma_f32_16x16x32_bf16 v[58:61], v[206:209], v[214:217], v[58:61]
	v_mfma_f32_16x16x32_bf16 v[54:57], v[198:201], v[222:225], v[54:57]
	v_mfma_f32_16x16x32_bf16 v[50:53], v[206:209], v[222:225], v[50:53]
	v_mfma_f32_16x16x32_bf16 v[46:49], v[198:201], v[230:233], v[46:49]
	v_mfma_f32_16x16x32_bf16 v[42:45], v[206:209], v[230:233], v[42:45]
	v_mfma_f32_16x16x32_bf16 v[38:41], v[198:201], v[238:241], v[38:41]
	v_mfma_f32_16x16x32_bf16 v[34:37], v[206:209], v[238:241], v[34:37]
	v_mfma_f32_16x16x32_bf16 v[62:65], v[202:205], v[218:221], v[62:65]
	v_mfma_f32_16x16x32_bf16 v[58:61], v[210:213], v[218:221], v[58:61]
	v_mfma_f32_16x16x32_bf16 v[54:57], v[202:205], v[226:229], v[54:57]
	v_mfma_f32_16x16x32_bf16 v[50:53], v[210:213], v[226:229], v[50:53]
	v_mfma_f32_16x16x32_bf16 v[46:49], v[202:205], v[234:237], v[46:49]
	v_mfma_f32_16x16x32_bf16 v[42:45], v[210:213], v[234:237], v[42:45]
	v_mfma_f32_16x16x32_bf16 v[38:41], v[202:205], v[242:245], v[38:41]
	v_mfma_f32_16x16x32_bf16 v[34:37], v[210:213], v[242:245], v[34:37]
	s_barrier
	s_add_i32 s3, s3, s26
	v_lshl_add_u64 v[144:145], s[0:1], 0, v[4:5]
	s_mov_b32 m0, s3
	ds_read_b128 v[214:217], v172 offset:16384
	ds_read_b128 v[218:221], v172 offset:17408
	ds_read_b128 v[222:225], v172 offset:18432
	ds_read_b128 v[226:229], v172 offset:19456
	ds_read_b128 v[230:233], v172 offset:20480
	ds_read_b128 v[234:237], v172 offset:21504
	ds_read_b128 v[238:241], v172 offset:22528
	ds_read_b128 v[242:245], v172 offset:23552
	global_load_lds_dwordx4 v[144:145], off
	s_add_i32 m0, s3, 0x2000
	s_add_u32 s4, s0, 0x40000
	v_lshl_add_u64 v[246:247], s[0:1], 0, v[134:135]
	s_addc_u32 s5, s1, 0
	s_add_i32 s3, s6, s26
	global_load_lds_dwordx4 v[246:247], off
	v_lshl_add_u64 v[248:249], s[4:5], 0, v[4:5]
	s_mov_b32 m0, s3
	v_lshl_add_u64 v[250:251], s[14:15], 0, v[132:133]
	global_load_lds_dwordx4 v[248:249], off
	v_lshl_add_u64 v[248:249], s[4:5], 0, v[134:135]
	s_add_i32 m0, s3, 0x2000
	s_nop 0
	global_load_lds_dwordx4 v[248:249], off
	v_lshl_add_u64 v[248:249], s[14:15], 0, v[130:131]
	s_mov_b32 m0, s27
	s_nop 0
	global_load_lds_dwordx4 v[248:249], off
	s_mov_b32 m0, s30
	s_nop 0
	global_load_lds_dwordx4 v[250:251], off
	s_waitcnt vmcnt(24)
	s_waitcnt lgkmcnt(0)
	s_barrier
	s_waitcnt lgkmcnt(0)
	v_mfma_f32_16x16x32_bf16 v[94:97], v[140:143], v[214:217], v[94:97]
	v_mfma_f32_16x16x32_bf16 v[90:93], v[190:193], v[214:217], v[90:93]
	v_mfma_f32_16x16x32_bf16 v[86:89], v[140:143], v[222:225], v[86:89]
	v_mfma_f32_16x16x32_bf16 v[82:85], v[190:193], v[222:225], v[82:85]
	v_mfma_f32_16x16x32_bf16 v[78:81], v[140:143], v[230:233], v[78:81]
	v_mfma_f32_16x16x32_bf16 v[74:77], v[190:193], v[230:233], v[74:77]
	v_mfma_f32_16x16x32_bf16 v[70:73], v[140:143], v[238:241], v[70:73]
	v_mfma_f32_16x16x32_bf16 v[66:69], v[190:193], v[238:241], v[66:69]
	v_mfma_f32_16x16x32_bf16 v[94:97], v[174:177], v[218:221], v[94:97]
	v_mfma_f32_16x16x32_bf16 v[90:93], v[194:197], v[218:221], v[90:93]
	v_mfma_f32_16x16x32_bf16 v[86:89], v[174:177], v[226:229], v[86:89]
	v_mfma_f32_16x16x32_bf16 v[82:85], v[194:197], v[226:229], v[82:85]
	v_mfma_f32_16x16x32_bf16 v[78:81], v[174:177], v[234:237], v[78:81]
	v_mfma_f32_16x16x32_bf16 v[74:77], v[194:197], v[234:237], v[74:77]
	v_mfma_f32_16x16x32_bf16 v[70:73], v[174:177], v[242:245], v[70:73]
	v_mfma_f32_16x16x32_bf16 v[66:69], v[194:197], v[242:245], v[66:69]
	v_mfma_f32_16x16x32_bf16 v[30:33], v[198:201], v[214:217], v[30:33]
	v_mfma_f32_16x16x32_bf16 v[26:29], v[206:209], v[214:217], v[26:29]
	v_mfma_f32_16x16x32_bf16 v[22:25], v[198:201], v[222:225], v[22:25]
	v_mfma_f32_16x16x32_bf16 v[18:21], v[206:209], v[222:225], v[18:21]
	v_mfma_f32_16x16x32_bf16 v[14:17], v[198:201], v[230:233], v[14:17]
	v_mfma_f32_16x16x32_bf16 v[10:13], v[206:209], v[230:233], v[10:13]
	v_mfma_f32_16x16x32_bf16 v[6:9], v[198:201], v[238:241], v[6:9]
	v_mfma_f32_16x16x32_bf16 v[0:3], v[206:209], v[238:241], v[0:3]
	v_mfma_f32_16x16x32_bf16 v[30:33], v[202:205], v[218:221], v[30:33]
	v_mfma_f32_16x16x32_bf16 v[26:29], v[210:213], v[218:221], v[26:29]
	v_mfma_f32_16x16x32_bf16 v[22:25], v[202:205], v[226:229], v[22:25]
	v_mfma_f32_16x16x32_bf16 v[18:21], v[210:213], v[226:229], v[18:21]
	v_mfma_f32_16x16x32_bf16 v[14:17], v[202:205], v[234:237], v[14:17]
	v_mfma_f32_16x16x32_bf16 v[10:13], v[210:213], v[234:237], v[10:13]
	v_mfma_f32_16x16x32_bf16 v[6:9], v[202:205], v[242:245], v[6:9]
	v_mfma_f32_16x16x32_bf16 v[0:3], v[210:213], v[242:245], v[0:3]
	s_barrier
	s_branch .Lpeelmid_205
.LBB0_205:
	s_add_u32 s0, s22, 0xfffc0080
	s_addc_u32 s1, s23, -1
	s_add_i32 s3, 0, 0x10000
	s_cmp_eq_u32 s24, 12
	s_cselect_b32 s15, s83, s1
	s_cselect_b32 s14, s82, s0
	v_add_u32_e32 v144, s3, v168
	s_cselect_b32 s1, s2, s10
	s_cselect_b32 s0, s8, s9
	s_add_i32 s6, 0, 0x14000
	ds_read_b128 v[140:143], v144
	ds_read_b128 v[174:177], v144 offset:1024
	ds_read_b128 v[190:193], v144 offset:2048
	ds_read_b128 v[194:197], v144 offset:3072
	v_add_u32_e32 v144, s6, v168
	ds_read_b128 v[198:201], v144
	ds_read_b128 v[202:205], v144 offset:1024
	ds_read_b128 v[206:209], v144 offset:2048
	ds_read_b128 v[210:213], v144 offset:3072
	v_lshl_add_u64 v[144:145], s[22:23], 0, v[136:137]
	s_add_i32 m0, s27, 0xc000
	ds_read_b128 v[214:217], v172
	ds_read_b128 v[218:221], v172 offset:1024
	ds_read_b128 v[222:225], v172 offset:2048
	ds_read_b128 v[226:229], v172 offset:3072
	ds_read_b128 v[230:233], v172 offset:4096
	ds_read_b128 v[234:237], v172 offset:5120
	ds_read_b128 v[238:241], v172 offset:6144
	ds_read_b128 v[242:245], v172 offset:7168
	global_load_lds_dwordx4 v[144:145], off
	v_lshl_add_u64 v[144:145], s[22:23], 0, v[138:139]
	s_add_i32 m0, s27, 0xe000
	s_nop 0
	global_load_lds_dwordx4 v[144:145], off
	s_waitcnt vmcnt(8)
	s_waitcnt lgkmcnt(0)
	s_barrier
	s_waitcnt lgkmcnt(0)
	v_mfma_f32_16x16x32_bf16 v[126:129], v[140:143], v[214:217], v[126:129]
	v_mfma_f32_16x16x32_bf16 v[122:125], v[190:193], v[214:217], v[122:125]
	v_mfma_f32_16x16x32_bf16 v[118:121], v[140:143], v[222:225], v[118:121]
	v_mfma_f32_16x16x32_bf16 v[114:117], v[190:193], v[222:225], v[114:117]
	v_mfma_f32_16x16x32_bf16 v[110:113], v[140:143], v[230:233], v[110:113]
	v_mfma_f32_16x16x32_bf16 v[106:109], v[190:193], v[230:233], v[106:109]
	v_mfma_f32_16x16x32_bf16 v[102:105], v[140:143], v[238:241], v[102:105]
	v_mfma_f32_16x16x32_bf16 v[98:101], v[190:193], v[238:241], v[98:101]
	v_mfma_f32_16x16x32_bf16 v[126:129], v[174:177], v[218:221], v[126:129]
	v_mfma_f32_16x16x32_bf16 v[122:125], v[194:197], v[218:221], v[122:125]
	v_mfma_f32_16x16x32_bf16 v[118:121], v[174:177], v[226:229], v[118:121]
	v_mfma_f32_16x16x32_bf16 v[114:117], v[194:197], v[226:229], v[114:117]
	v_mfma_f32_16x16x32_bf16 v[110:113], v[174:177], v[234:237], v[110:113]
	v_mfma_f32_16x16x32_bf16 v[106:109], v[194:197], v[234:237], v[106:109]
	v_mfma_f32_16x16x32_bf16 v[102:105], v[174:177], v[242:245], v[102:105]
	v_mfma_f32_16x16x32_bf16 v[98:101], v[194:197], v[242:245], v[98:101]
	v_mfma_f32_16x16x32_bf16 v[62:65], v[198:201], v[214:217], v[62:65]
	v_mfma_f32_16x16x32_bf16 v[58:61], v[206:209], v[214:217], v[58:61]
	v_mfma_f32_16x16x32_bf16 v[54:57], v[198:201], v[222:225], v[54:57]
	v_mfma_f32_16x16x32_bf16 v[50:53], v[206:209], v[222:225], v[50:53]
	v_mfma_f32_16x16x32_bf16 v[46:49], v[198:201], v[230:233], v[46:49]
	v_mfma_f32_16x16x32_bf16 v[42:45], v[206:209], v[230:233], v[42:45]
	v_mfma_f32_16x16x32_bf16 v[38:41], v[198:201], v[238:241], v[38:41]
	v_mfma_f32_16x16x32_bf16 v[34:37], v[206:209], v[238:241], v[34:37]
	v_mfma_f32_16x16x32_bf16 v[62:65], v[202:205], v[218:221], v[62:65]
	v_mfma_f32_16x16x32_bf16 v[58:61], v[210:213], v[218:221], v[58:61]
	v_mfma_f32_16x16x32_bf16 v[54:57], v[202:205], v[226:229], v[54:57]
	v_mfma_f32_16x16x32_bf16 v[50:53], v[210:213], v[226:229], v[50:53]
	v_mfma_f32_16x16x32_bf16 v[46:49], v[202:205], v[234:237], v[46:49]
	v_mfma_f32_16x16x32_bf16 v[42:45], v[210:213], v[234:237], v[42:45]
	v_mfma_f32_16x16x32_bf16 v[38:41], v[202:205], v[242:245], v[38:41]
	v_mfma_f32_16x16x32_bf16 v[34:37], v[210:213], v[242:245], v[34:37]
	s_barrier
	s_add_i32 s3, s3, s26
	v_lshl_add_u64 v[144:145], s[0:1], 0, v[4:5]
	s_mov_b32 m0, s3
	ds_read_b128 v[214:217], v172 offset:16384
	ds_read_b128 v[218:221], v172 offset:17408
	ds_read_b128 v[222:225], v172 offset:18432
	ds_read_b128 v[226:229], v172 offset:19456
	ds_read_b128 v[230:233], v172 offset:20480
	ds_read_b128 v[234:237], v172 offset:21504
	ds_read_b128 v[238:241], v172 offset:22528
	ds_read_b128 v[242:245], v172 offset:23552
	global_load_lds_dwordx4 v[144:145], off
	s_add_i32 m0, s3, 0x2000
	s_add_u32 s4, s0, 0x40000
	v_lshl_add_u64 v[246:247], s[0:1], 0, v[134:135]
	s_addc_u32 s5, s1, 0
	s_add_i32 s3, s6, s26
	global_load_lds_dwordx4 v[246:247], off
	v_lshl_add_u64 v[248:249], s[4:5], 0, v[4:5]
	s_mov_b32 m0, s3
	v_lshl_add_u64 v[250:251], s[14:15], 0, v[132:133]
	global_load_lds_dwordx4 v[248:249], off
	v_lshl_add_u64 v[248:249], s[4:5], 0, v[134:135]
	s_add_i32 m0, s3, 0x2000
	s_nop 0
	global_load_lds_dwordx4 v[248:249], off
	v_lshl_add_u64 v[248:249], s[14:15], 0, v[130:131]
	s_mov_b32 m0, s27
	s_nop 0
	global_load_lds_dwordx4 v[248:249], off
	s_mov_b32 m0, s30
	s_nop 0
	global_load_lds_dwordx4 v[250:251], off
	s_waitcnt vmcnt(8)
	s_waitcnt lgkmcnt(0)
	s_barrier
	s_waitcnt lgkmcnt(0)
	v_mfma_f32_16x16x32_bf16 v[94:97], v[140:143], v[214:217], v[94:97]
	v_mfma_f32_16x16x32_bf16 v[90:93], v[190:193], v[214:217], v[90:93]
	v_mfma_f32_16x16x32_bf16 v[86:89], v[140:143], v[222:225], v[86:89]
	v_mfma_f32_16x16x32_bf16 v[82:85], v[190:193], v[222:225], v[82:85]
	v_mfma_f32_16x16x32_bf16 v[78:81], v[140:143], v[230:233], v[78:81]
	v_mfma_f32_16x16x32_bf16 v[74:77], v[190:193], v[230:233], v[74:77]
	v_mfma_f32_16x16x32_bf16 v[70:73], v[140:143], v[238:241], v[70:73]
	v_mfma_f32_16x16x32_bf16 v[66:69], v[190:193], v[238:241], v[66:69]
	v_mfma_f32_16x16x32_bf16 v[94:97], v[174:177], v[218:221], v[94:97]
	v_mfma_f32_16x16x32_bf16 v[90:93], v[194:197], v[218:221], v[90:93]
	v_mfma_f32_16x16x32_bf16 v[86:89], v[174:177], v[226:229], v[86:89]
	v_mfma_f32_16x16x32_bf16 v[82:85], v[194:197], v[226:229], v[82:85]
	v_mfma_f32_16x16x32_bf16 v[78:81], v[174:177], v[234:237], v[78:81]
	v_mfma_f32_16x16x32_bf16 v[74:77], v[194:197], v[234:237], v[74:77]
	v_mfma_f32_16x16x32_bf16 v[70:73], v[174:177], v[242:245], v[70:73]
	v_mfma_f32_16x16x32_bf16 v[66:69], v[194:197], v[242:245], v[66:69]
	v_mfma_f32_16x16x32_bf16 v[30:33], v[198:201], v[214:217], v[30:33]
	v_mfma_f32_16x16x32_bf16 v[26:29], v[206:209], v[214:217], v[26:29]
	v_mfma_f32_16x16x32_bf16 v[22:25], v[198:201], v[222:225], v[22:25]
	v_mfma_f32_16x16x32_bf16 v[18:21], v[206:209], v[222:225], v[18:21]
	v_mfma_f32_16x16x32_bf16 v[14:17], v[198:201], v[230:233], v[14:17]
	v_mfma_f32_16x16x32_bf16 v[10:13], v[206:209], v[230:233], v[10:13]
	v_mfma_f32_16x16x32_bf16 v[6:9], v[198:201], v[238:241], v[6:9]
	v_mfma_f32_16x16x32_bf16 v[0:3], v[206:209], v[238:241], v[0:3]
	v_mfma_f32_16x16x32_bf16 v[30:33], v[202:205], v[218:221], v[30:33]
	v_mfma_f32_16x16x32_bf16 v[26:29], v[210:213], v[218:221], v[26:29]
	v_mfma_f32_16x16x32_bf16 v[22:25], v[202:205], v[226:229], v[22:25]
	v_mfma_f32_16x16x32_bf16 v[18:21], v[210:213], v[226:229], v[18:21]
	v_mfma_f32_16x16x32_bf16 v[14:17], v[202:205], v[234:237], v[14:17]
	v_mfma_f32_16x16x32_bf16 v[10:13], v[210:213], v[234:237], v[10:13]
	v_mfma_f32_16x16x32_bf16 v[6:9], v[202:205], v[242:245], v[6:9]
	v_mfma_f32_16x16x32_bf16 v[0:3], v[210:213], v[242:245], v[0:3]
	s_barrier
.Lpeelmid_205:
	s_add_i32 s3, 0, 0x18000
	v_add_u32_e32 v173, s3, v168
	s_add_i32 s6, 0, 0x1c000
	ds_read_b128 v[140:143], v173
	ds_read_b128 v[174:177], v173 offset:1024
	ds_read_b128 v[190:193], v173 offset:2048
	ds_read_b128 v[194:197], v173 offset:3072
	v_add_u32_e32 v173, s6, v168
	ds_read_b128 v[198:201], v173
	ds_read_b128 v[202:205], v173 offset:1024
	ds_read_b128 v[206:209], v173 offset:2048
	ds_read_b128 v[210:213], v173 offset:3072
	s_add_u32 s4, s14, 0x40000
	s_addc_u32 s5, s15, 0
	s_mov_b32 m0, s31
	v_lshl_add_u64 v[180:181], s[4:5], 0, v[130:131]
	ds_read_b128 v[214:217], v172 offset:32768
	ds_read_b128 v[218:221], v172 offset:33792
	ds_read_b128 v[222:225], v172 offset:34816
	ds_read_b128 v[226:229], v172 offset:35840
	ds_read_b128 v[230:233], v172 offset:36864
	ds_read_b128 v[234:237], v172 offset:37888
	ds_read_b128 v[238:241], v172 offset:38912
	ds_read_b128 v[242:245], v172 offset:39936
	global_load_lds_dwordx4 v[180:181], off
	v_lshl_add_u64 v[180:181], s[4:5], 0, v[132:133]
	s_mov_b32 m0, s34
	s_nop 0
	global_load_lds_dwordx4 v[180:181], off
	s_waitcnt vmcnt(8)
	s_waitcnt lgkmcnt(0)
	s_barrier
	s_waitcnt lgkmcnt(0)
	v_mfma_f32_16x16x32_bf16 v[126:129], v[140:143], v[214:217], v[126:129]
	v_mfma_f32_16x16x32_bf16 v[122:125], v[190:193], v[214:217], v[122:125]
	v_mfma_f32_16x16x32_bf16 v[118:121], v[140:143], v[222:225], v[118:121]
	v_mfma_f32_16x16x32_bf16 v[114:117], v[190:193], v[222:225], v[114:117]
	v_mfma_f32_16x16x32_bf16 v[110:113], v[140:143], v[230:233], v[110:113]
	v_mfma_f32_16x16x32_bf16 v[106:109], v[190:193], v[230:233], v[106:109]
	v_mfma_f32_16x16x32_bf16 v[102:105], v[140:143], v[238:241], v[102:105]
	v_mfma_f32_16x16x32_bf16 v[98:101], v[190:193], v[238:241], v[98:101]
	v_mfma_f32_16x16x32_bf16 v[126:129], v[174:177], v[218:221], v[126:129]
	v_mfma_f32_16x16x32_bf16 v[122:125], v[194:197], v[218:221], v[122:125]
	v_mfma_f32_16x16x32_bf16 v[118:121], v[174:177], v[226:229], v[118:121]
	v_mfma_f32_16x16x32_bf16 v[114:117], v[194:197], v[226:229], v[114:117]
	v_mfma_f32_16x16x32_bf16 v[110:113], v[174:177], v[234:237], v[110:113]
	v_mfma_f32_16x16x32_bf16 v[106:109], v[194:197], v[234:237], v[106:109]
	v_mfma_f32_16x16x32_bf16 v[102:105], v[174:177], v[242:245], v[102:105]
	v_mfma_f32_16x16x32_bf16 v[98:101], v[194:197], v[242:245], v[98:101]
	v_mfma_f32_16x16x32_bf16 v[62:65], v[198:201], v[214:217], v[62:65]
	v_mfma_f32_16x16x32_bf16 v[58:61], v[206:209], v[214:217], v[58:61]
	v_mfma_f32_16x16x32_bf16 v[54:57], v[198:201], v[222:225], v[54:57]
	v_mfma_f32_16x16x32_bf16 v[50:53], v[206:209], v[222:225], v[50:53]
	v_mfma_f32_16x16x32_bf16 v[46:49], v[198:201], v[230:233], v[46:49]
	v_mfma_f32_16x16x32_bf16 v[42:45], v[206:209], v[230:233], v[42:45]
	v_mfma_f32_16x16x32_bf16 v[38:41], v[198:201], v[238:241], v[38:41]
	v_mfma_f32_16x16x32_bf16 v[34:37], v[206:209], v[238:241], v[34:37]
	v_mfma_f32_16x16x32_bf16 v[62:65], v[202:205], v[218:221], v[62:65]
	v_mfma_f32_16x16x32_bf16 v[58:61], v[210:213], v[218:221], v[58:61]
	v_mfma_f32_16x16x32_bf16 v[54:57], v[202:205], v[226:229], v[54:57]
	v_mfma_f32_16x16x32_bf16 v[50:53], v[210:213], v[226:229], v[50:53]
	v_mfma_f32_16x16x32_bf16 v[46:49], v[202:205], v[234:237], v[46:49]
	v_mfma_f32_16x16x32_bf16 v[42:45], v[210:213], v[234:237], v[42:45]
	v_mfma_f32_16x16x32_bf16 v[38:41], v[202:205], v[242:245], v[38:41]
	v_mfma_f32_16x16x32_bf16 v[34:37], v[210:213], v[242:245], v[34:37]
	s_barrier
	s_add_i32 s3, s3, s26
	v_lshl_add_u64 v[144:145], v[144:145], 0, s[70:71]
	s_mov_b32 m0, s3
	ds_read_b128 v[214:217], v172 offset:49152
	ds_read_b128 v[218:221], v172 offset:50176
	ds_read_b128 v[222:225], v172 offset:51200
	ds_read_b128 v[226:229], v172 offset:52224
	ds_read_b128 v[230:233], v172 offset:53248
	ds_read_b128 v[234:237], v172 offset:54272
	ds_read_b128 v[238:241], v172 offset:55296
	ds_read_b128 v[242:245], v172 offset:56320
	global_load_lds_dwordx4 v[144:145], off
	s_add_i32 m0, s3, 0x2000
	s_add_u32 s0, s0, 0x40080
	v_lshl_add_u64 v[144:145], v[246:247], 0, s[70:71]
	s_addc_u32 s1, s1, 0
	s_add_i32 s3, s6, s26
	global_load_lds_dwordx4 v[144:145], off
	v_lshl_add_u64 v[144:145], s[0:1], 0, v[4:5]
	s_mov_b32 m0, s3
	s_nop 0
	global_load_lds_dwordx4 v[144:145], off
	v_lshl_add_u64 v[144:145], s[0:1], 0, v[134:135]
	s_add_i32 m0, s3, 0x2000
	s_nop 0
	global_load_lds_dwordx4 v[144:145], off
	v_lshl_add_u64 v[144:145], v[248:249], 0, s[70:71]
	s_mov_b32 m0, s35
	s_nop 0
	global_load_lds_dwordx4 v[144:145], off
	v_lshl_add_u64 v[144:145], v[250:251], 0, s[70:71]
	s_mov_b32 m0, s36
	s_nop 0
	global_load_lds_dwordx4 v[144:145], off
	s_waitcnt vmcnt(8)
	s_waitcnt lgkmcnt(0)
	s_barrier
	s_waitcnt lgkmcnt(0)
	v_mfma_f32_16x16x32_bf16 v[94:97], v[140:143], v[214:217], v[94:97]
	v_mfma_f32_16x16x32_bf16 v[90:93], v[190:193], v[214:217], v[90:93]
	v_mfma_f32_16x16x32_bf16 v[86:89], v[140:143], v[222:225], v[86:89]
	v_mfma_f32_16x16x32_bf16 v[82:85], v[190:193], v[222:225], v[82:85]
	v_mfma_f32_16x16x32_bf16 v[78:81], v[140:143], v[230:233], v[78:81]
	v_mfma_f32_16x16x32_bf16 v[74:77], v[190:193], v[230:233], v[74:77]
	v_mfma_f32_16x16x32_bf16 v[70:73], v[140:143], v[238:241], v[70:73]
	v_mfma_f32_16x16x32_bf16 v[66:69], v[190:193], v[238:241], v[66:69]
	v_mfma_f32_16x16x32_bf16 v[94:97], v[174:177], v[218:221], v[94:97]
	v_mfma_f32_16x16x32_bf16 v[90:93], v[194:197], v[218:221], v[90:93]
	v_mfma_f32_16x16x32_bf16 v[86:89], v[174:177], v[226:229], v[86:89]
	v_mfma_f32_16x16x32_bf16 v[82:85], v[194:197], v[226:229], v[82:85]
	v_mfma_f32_16x16x32_bf16 v[78:81], v[174:177], v[234:237], v[78:81]
	v_mfma_f32_16x16x32_bf16 v[74:77], v[194:197], v[234:237], v[74:77]
	v_mfma_f32_16x16x32_bf16 v[70:73], v[174:177], v[242:245], v[70:73]
	v_mfma_f32_16x16x32_bf16 v[66:69], v[194:197], v[242:245], v[66:69]
	v_mfma_f32_16x16x32_bf16 v[30:33], v[198:201], v[214:217], v[30:33]
	v_mfma_f32_16x16x32_bf16 v[26:29], v[206:209], v[214:217], v[26:29]
	v_mfma_f32_16x16x32_bf16 v[22:25], v[198:201], v[222:225], v[22:25]
	v_mfma_f32_16x16x32_bf16 v[18:21], v[206:209], v[222:225], v[18:21]
	v_mfma_f32_16x16x32_bf16 v[14:17], v[198:201], v[230:233], v[14:17]
	v_mfma_f32_16x16x32_bf16 v[10:13], v[206:209], v[230:233], v[10:13]
	v_mfma_f32_16x16x32_bf16 v[6:9], v[198:201], v[238:241], v[6:9]
	v_mfma_f32_16x16x32_bf16 v[0:3], v[206:209], v[238:241], v[0:3]
	v_mfma_f32_16x16x32_bf16 v[30:33], v[202:205], v[218:221], v[30:33]
	v_mfma_f32_16x16x32_bf16 v[26:29], v[210:213], v[218:221], v[26:29]
	v_mfma_f32_16x16x32_bf16 v[22:25], v[202:205], v[226:229], v[22:25]
	v_mfma_f32_16x16x32_bf16 v[18:21], v[210:213], v[226:229], v[18:21]
	v_mfma_f32_16x16x32_bf16 v[14:17], v[202:205], v[234:237], v[14:17]
	v_mfma_f32_16x16x32_bf16 v[10:13], v[210:213], v[234:237], v[10:13]
	v_mfma_f32_16x16x32_bf16 v[6:9], v[202:205], v[242:245], v[6:9]
	v_mfma_f32_16x16x32_bf16 v[0:3], v[210:213], v[242:245], v[0:3]
	s_barrier
	s_add_i32 s24, s24, 2
	s_add_u32 s22, s22, 0x100
	s_addc_u32 s23, s23, 0
	s_add_u32 s9, s9, 0x100
	s_addc_u32 s10, s10, 0
	s_cmp_gt_u32 s24, 13
	s_cbranch_scc0 .LBB0_205
	s_and_b64 vcc, exec, s[46:47]
	s_cbranch_vccz .LBB0_208
	s_barrier

.LBB0_227:
	s_ashr_i32 s47, s46, 31
	s_lshl_b64 s[2:3], s[46:47], 19
	v_readlane_b32 s4, v253, 25
	v_readlane_b32 s5, v253, 26
	s_add_u32 s82, s4, s2
	s_addc_u32 s83, s5, s3
	s_and_b64 s[2:3], s[40:41], exec
	s_cselect_b32 s2, s83, s15
	s_cselect_b32 s8, s82, s14
	s_add_u32 s22, s0, 0x40080
	s_addc_u32 s23, s1, 0
	s_add_u32 s9, s14, 0x100
	v_mov_b32_e32 v0, 0
	s_addc_u32 s10, s15, 0
	s_mov_b32 s24, -2
	v_mov_b32_e32 v1, v0
	v_mov_b32_e32 v2, v0
	v_mov_b32_e32 v3, v0
	v_mov_b32_e32 v6, v0
	v_mov_b32_e32 v7, v0
	v_mov_b32_e32 v8, v0
	v_mov_b32_e32 v9, v0
	v_mov_b32_e32 v10, v0
	v_mov_b32_e32 v11, v0
	v_mov_b32_e32 v12, v0
	v_mov_b32_e32 v13, v0
	v_mov_b32_e32 v14, v0
	v_mov_b32_e32 v15, v0
	v_mov_b32_e32 v16, v0
	v_mov_b32_e32 v17, v0
	v_mov_b32_e32 v18, v0
	v_mov_b32_e32 v19, v0
	v_mov_b32_e32 v20, v0
	v_mov_b32_e32 v21, v0
	v_mov_b32_e32 v22, v0
	v_mov_b32_e32 v23, v0
	v_mov_b32_e32 v24, v0
	v_mov_b32_e32 v25, v0
	v_mov_b32_e32 v26, v0
	v_mov_b32_e32 v27, v0
	v_mov_b32_e32 v28, v0
	v_mov_b32_e32 v29, v0
	v_mov_b32_e32 v30, v0
	v_mov_b32_e32 v31, v0
	v_mov_b32_e32 v32, v0
	v_mov_b32_e32 v33, v0
	v_mov_b32_e32 v62, v0
	v_mov_b32_e32 v63, v0
	v_mov_b32_e32 v64, v0
	v_mov_b32_e32 v65, v0
	v_mov_b32_e32 v70, v0
	v_mov_b32_e32 v71, v0
	v_mov_b32_e32 v72, v0
	v_mov_b32_e32 v73, v0
	v_mov_b32_e32 v74, v0
	v_mov_b32_e32 v75, v0
	v_mov_b32_e32 v76, v0
	v_mov_b32_e32 v77, v0
	v_mov_b32_e32 v78, v0
	v_mov_b32_e32 v79, v0
	v_mov_b32_e32 v80, v0
	v_mov_b32_e32 v81, v0
	v_mov_b32_e32 v82, v0
	v_mov_b32_e32 v83, v0
	v_mov_b32_e32 v84, v0
	v_mov_b32_e32 v85, v0
	v_mov_b32_e32 v86, v0
	v_mov_b32_e32 v87, v0
	v_mov_b32_e32 v88, v0
	v_mov_b32_e32 v89, v0
	v_mov_b32_e32 v90, v0
	v_mov_b32_e32 v91, v0
	v_mov_b32_e32 v92, v0
	v_mov_b32_e32 v93, v0
	v_mov_b32_e32 v94, v0
	v_mov_b32_e32 v95, v0
	v_mov_b32_e32 v96, v0
	v_mov_b32_e32 v97, v0
	v_mov_b32_e32 v34, v0
	v_mov_b32_e32 v35, v0
	v_mov_b32_e32 v36, v0
	v_mov_b32_e32 v37, v0
	v_mov_b32_e32 v38, v0
	v_mov_b32_e32 v39, v0
	v_mov_b32_e32 v40, v0
	v_mov_b32_e32 v41, v0
	v_mov_b32_e32 v42, v0
	v_mov_b32_e32 v43, v0
	v_mov_b32_e32 v44, v0
	v_mov_b32_e32 v45, v0
	v_mov_b32_e32 v46, v0
	v_mov_b32_e32 v47, v0
	v_mov_b32_e32 v48, v0
	v_mov_b32_e32 v49, v0
	v_mov_b32_e32 v50, v0
	v_mov_b32_e32 v51, v0
	v_mov_b32_e32 v52, v0
	v_mov_b32_e32 v53, v0
	v_mov_b32_e32 v54, v0
	v_mov_b32_e32 v55, v0
	v_mov_b32_e32 v56, v0
	v_mov_b32_e32 v57, v0
	v_mov_b32_e32 v58, v0
	v_mov_b32_e32 v59, v0
	v_mov_b32_e32 v60, v0
	v_mov_b32_e32 v61, v0
	v_mov_b32_e32 v66, v0
	v_mov_b32_e32 v67, v0
	v_mov_b32_e32 v68, v0
	v_mov_b32_e32 v69, v0
	v_mov_b32_e32 v98, v0
	v_mov_b32_e32 v99, v0
	v_mov_b32_e32 v100, v0
	v_mov_b32_e32 v101, v0
	v_mov_b32_e32 v102, v0
	v_mov_b32_e32 v103, v0
	v_mov_b32_e32 v104, v0
	v_mov_b32_e32 v105, v0
	v_mov_b32_e32 v106, v0
	v_mov_b32_e32 v107, v0
	v_mov_b32_e32 v108, v0
	v_mov_b32_e32 v109, v0
	v_mov_b32_e32 v110, v0
	v_mov_b32_e32 v111, v0
	v_mov_b32_e32 v112, v0
	v_mov_b32_e32 v113, v0
	v_mov_b32_e32 v114, v0
	v_mov_b32_e32 v115, v0
	v_mov_b32_e32 v116, v0
	v_mov_b32_e32 v117, v0
	v_mov_b32_e32 v118, v0
	v_mov_b32_e32 v119, v0
	v_mov_b32_e32 v120, v0
	v_mov_b32_e32 v121, v0
	v_mov_b32_e32 v122, v0
	v_mov_b32_e32 v123, v0
	v_mov_b32_e32 v124, v0
	v_mov_b32_e32 v125, v0
	v_mov_b32_e32 v126, v0
	v_mov_b32_e32 v127, v0
	v_mov_b32_e32 v128, v0
	v_mov_b32_e32 v129, v0
	s_cmp_eq_u32 s37, 1
	s_cbranch_scc1 .LBB0_228
	s_add_u32 s0, s22, 0xfffc0080
	s_addc_u32 s1, s23, -1
	s_add_i32 s3, 0, 0x10000
	s_cmp_eq_u32 s24, 12
	s_cselect_b32 s15, s49, s1
	s_cselect_b32 s14, s48, s0
	v_add_u32_e32 v162, s3, v149
	s_cselect_b32 s1, s2, s10
	s_cselect_b32 s0, s8, s9
	s_add_i32 s6, 0, 0x14000
	ds_read_b128 v[140:143], v162
	ds_read_b128 v[144:147], v162 offset:1024
	ds_read_b128 v[172:175], v162 offset:2048
	ds_read_b128 v[190:193], v162 offset:3072
	v_add_u32_e32 v162, s6, v149
	ds_read_b128 v[194:197], v162
	ds_read_b128 v[198:201], v162 offset:1024
	ds_read_b128 v[202:205], v162 offset:2048
	ds_read_b128 v[206:209], v162 offset:3072
	v_lshl_add_u64 v[162:163], s[22:23], 0, v[136:137]
	s_add_i32 m0, s27, 0xc000
	ds_read_b128 v[210:213], v151
	ds_read_b128 v[214:217], v151 offset:1024
	ds_read_b128 v[218:221], v151 offset:2048
	ds_read_b128 v[222:225], v151 offset:3072
	ds_read_b128 v[226:229], v151 offset:4096
	ds_read_b128 v[230:233], v151 offset:5120
	ds_read_b128 v[234:237], v151 offset:6144
	ds_read_b128 v[238:241], v151 offset:7168
	global_load_lds_dwordx4 v[162:163], off
	v_lshl_add_u64 v[162:163], s[22:23], 0, v[138:139]
	s_add_i32 m0, s27, 0xe000
	s_nop 0
	global_load_lds_dwordx4 v[162:163], off
	s_waitcnt vmcnt(24)
	s_waitcnt lgkmcnt(0)
	s_barrier
	s_waitcnt lgkmcnt(0)
	v_mfma_f32_16x16x32_bf16 v[126:129], v[140:143], v[210:213], v[126:129]
	v_mfma_f32_16x16x32_bf16 v[122:125], v[172:175], v[210:213], v[122:125]
	v_mfma_f32_16x16x32_bf16 v[118:121], v[140:143], v[218:221], v[118:121]
	v_mfma_f32_16x16x32_bf16 v[114:117], v[172:175], v[218:221], v[114:117]
	v_mfma_f32_16x16x32_bf16 v[110:113], v[140:143], v[226:229], v[110:113]
	v_mfma_f32_16x16x32_bf16 v[106:109], v[172:175], v[226:229], v[106:109]
	v_mfma_f32_16x16x32_bf16 v[102:105], v[140:143], v[234:237], v[102:105]
	v_mfma_f32_16x16x32_bf16 v[98:101], v[172:175], v[234:237], v[98:101]
	v_mfma_f32_16x16x32_bf16 v[126:129], v[144:147], v[214:217], v[126:129]
	v_mfma_f32_16x16x32_bf16 v[122:125], v[190:193], v[214:217], v[122:125]
	v_mfma_f32_16x16x32_bf16 v[118:121], v[144:147], v[222:225], v[118:121]
	v_mfma_f32_16x16x32_bf16 v[114:117], v[190:193], v[222:225], v[114:117]
	v_mfma_f32_16x16x32_bf16 v[110:113], v[144:147], v[230:233], v[110:113]
	v_mfma_f32_16x16x32_bf16 v[106:109], v[190:193], v[230:233], v[106:109]
	v_mfma_f32_16x16x32_bf16 v[102:105], v[144:147], v[238:241], v[102:105]
	v_mfma_f32_16x16x32_bf16 v[98:101], v[190:193], v[238:241], v[98:101]
	v_mfma_f32_16x16x32_bf16 v[66:69], v[194:197], v[210:213], v[66:69]
	v_mfma_f32_16x16x32_bf16 v[58:61], v[202:205], v[210:213], v[58:61]
	v_mfma_f32_16x16x32_bf16 v[54:57], v[194:197], v[218:221], v[54:57]
	v_mfma_f32_16x16x32_bf16 v[50:53], v[202:205], v[218:221], v[50:53]
	v_mfma_f32_16x16x32_bf16 v[46:49], v[194:197], v[226:229], v[46:49]
	v_mfma_f32_16x16x32_bf16 v[42:45], v[202:205], v[226:229], v[42:45]
	v_mfma_f32_16x16x32_bf16 v[38:41], v[194:197], v[234:237], v[38:41]
	v_mfma_f32_16x16x32_bf16 v[34:37], v[202:205], v[234:237], v[34:37]
	v_mfma_f32_16x16x32_bf16 v[66:69], v[198:201], v[214:217], v[66:69]
	v_mfma_f32_16x16x32_bf16 v[58:61], v[206:209], v[214:217], v[58:61]
	v_mfma_f32_16x16x32_bf16 v[54:57], v[198:201], v[222:225], v[54:57]
	v_mfma_f32_16x16x32_bf16 v[50:53], v[206:209], v[222:225], v[50:53]
	v_mfma_f32_16x16x32_bf16 v[46:49], v[198:201], v[230:233], v[46:49]
	v_mfma_f32_16x16x32_bf16 v[42:45], v[206:209], v[230:233], v[42:45]
	v_mfma_f32_16x16x32_bf16 v[38:41], v[198:201], v[238:241], v[38:41]
	v_mfma_f32_16x16x32_bf16 v[34:37], v[206:209], v[238:241], v[34:37]
	s_barrier
	s_add_i32 s3, s3, s26
	v_lshl_add_u64 v[162:163], s[0:1], 0, v[4:5]
	s_mov_b32 m0, s3
	ds_read_b128 v[210:213], v151 offset:16384
	ds_read_b128 v[214:217], v151 offset:17408
	ds_read_b128 v[218:221], v151 offset:18432
	ds_read_b128 v[222:225], v151 offset:19456
	ds_read_b128 v[226:229], v151 offset:20480
	ds_read_b128 v[230:233], v151 offset:21504
	ds_read_b128 v[234:237], v151 offset:22528
	ds_read_b128 v[238:241], v151 offset:23552
	global_load_lds_dwordx4 v[162:163], off
	s_add_i32 m0, s3, 0x2000
	s_add_u32 s4, s0, 0x40000
	v_lshl_add_u64 v[166:167], s[0:1], 0, v[134:135]
	s_addc_u32 s5, s1, 0
	s_add_i32 s3, s6, s26
	global_load_lds_dwordx4 v[166:167], off
	v_lshl_add_u64 v[176:177], s[4:5], 0, v[4:5]
	s_mov_b32 m0, s3
	v_lshl_add_u64 v[180:181], s[14:15], 0, v[132:133]
	global_load_lds_dwordx4 v[176:177], off
	v_lshl_add_u64 v[176:177], s[4:5], 0, v[134:135]
	s_add_i32 m0, s3, 0x2000
	s_nop 0
	global_load_lds_dwordx4 v[176:177], off
	v_lshl_add_u64 v[176:177], s[14:15], 0, v[130:131]
	s_mov_b32 m0, s27
	s_nop 0
	global_load_lds_dwordx4 v[176:177], off
	s_mov_b32 m0, s30
	s_nop 0
	global_load_lds_dwordx4 v[180:181], off
	s_waitcnt vmcnt(24)
	s_waitcnt lgkmcnt(0)
	s_barrier
	s_waitcnt lgkmcnt(0)
	v_mfma_f32_16x16x32_bf16 v[94:97], v[140:143], v[210:213], v[94:97]
	v_mfma_f32_16x16x32_bf16 v[90:93], v[172:175], v[210:213], v[90:93]
	v_mfma_f32_16x16x32_bf16 v[86:89], v[140:143], v[218:221], v[86:89]
	v_mfma_f32_16x16x32_bf16 v[82:85], v[172:175], v[218:221], v[82:85]
	v_mfma_f32_16x16x32_bf16 v[78:81], v[140:143], v[226:229], v[78:81]
	v_mfma_f32_16x16x32_bf16 v[74:77], v[172:175], v[226:229], v[74:77]
	v_mfma_f32_16x16x32_bf16 v[70:73], v[140:143], v[234:237], v[70:73]
	v_mfma_f32_16x16x32_bf16 v[62:65], v[172:175], v[234:237], v[62:65]
	v_mfma_f32_16x16x32_bf16 v[94:97], v[144:147], v[214:217], v[94:97]
	v_mfma_f32_16x16x32_bf16 v[90:93], v[190:193], v[214:217], v[90:93]
	v_mfma_f32_16x16x32_bf16 v[86:89], v[144:147], v[222:225], v[86:89]
	v_mfma_f32_16x16x32_bf16 v[82:85], v[190:193], v[222:225], v[82:85]
	v_mfma_f32_16x16x32_bf16 v[78:81], v[144:147], v[230:233], v[78:81]
	v_mfma_f32_16x16x32_bf16 v[74:77], v[190:193], v[230:233], v[74:77]
	v_mfma_f32_16x16x32_bf16 v[70:73], v[144:147], v[238:241], v[70:73]
	v_mfma_f32_16x16x32_bf16 v[62:65], v[190:193], v[238:241], v[62:65]
	v_mfma_f32_16x16x32_bf16 v[30:33], v[194:197], v[210:213], v[30:33]
	v_mfma_f32_16x16x32_bf16 v[26:29], v[202:205], v[210:213], v[26:29]
	v_mfma_f32_16x16x32_bf16 v[22:25], v[194:197], v[218:221], v[22:25]
	v_mfma_f32_16x16x32_bf16 v[18:21], v[202:205], v[218:221], v[18:21]
	v_mfma_f32_16x16x32_bf16 v[14:17], v[194:197], v[226:229], v[14:17]
	v_mfma_f32_16x16x32_bf16 v[10:13], v[202:205], v[226:229], v[10:13]
	v_mfma_f32_16x16x32_bf16 v[6:9], v[194:197], v[234:237], v[6:9]
	v_mfma_f32_16x16x32_bf16 v[0:3], v[202:205], v[234:237], v[0:3]
	v_mfma_f32_16x16x32_bf16 v[30:33], v[198:201], v[214:217], v[30:33]
	v_mfma_f32_16x16x32_bf16 v[26:29], v[206:209], v[214:217], v[26:29]
	v_mfma_f32_16x16x32_bf16 v[22:25], v[198:201], v[222:225], v[22:25]
	v_mfma_f32_16x16x32_bf16 v[18:21], v[206:209], v[222:225], v[18:21]
	v_mfma_f32_16x16x32_bf16 v[14:17], v[198:201], v[230:233], v[14:17]
	v_mfma_f32_16x16x32_bf16 v[10:13], v[206:209], v[230:233], v[10:13]
	v_mfma_f32_16x16x32_bf16 v[6:9], v[198:201], v[238:241], v[6:9]
	v_mfma_f32_16x16x32_bf16 v[0:3], v[206:209], v[238:241], v[0:3]
	s_barrier
	s_branch .Lpeelmid_228
.LBB0_228:
	s_add_u32 s0, s22, 0xfffc0080
	s_addc_u32 s1, s23, -1
	s_add_i32 s3, 0, 0x10000
	s_cmp_eq_u32 s24, 12
	s_cselect_b32 s15, s49, s1
	s_cselect_b32 s14, s48, s0
	v_add_u32_e32 v162, s3, v149
	s_cselect_b32 s1, s2, s10
	s_cselect_b32 s0, s8, s9
	s_add_i32 s6, 0, 0x14000
	ds_read_b128 v[140:143], v162
	ds_read_b128 v[144:147], v162 offset:1024
	ds_read_b128 v[172:175], v162 offset:2048
	ds_read_b128 v[190:193], v162 offset:3072
	v_add_u32_e32 v162, s6, v149
	ds_read_b128 v[194:197], v162
	ds_read_b128 v[198:201], v162 offset:1024
	ds_read_b128 v[202:205], v162 offset:2048
	ds_read_b128 v[206:209], v162 offset:3072
	v_lshl_add_u64 v[162:163], s[22:23], 0, v[136:137]
	s_add_i32 m0, s27, 0xc000
	ds_read_b128 v[210:213], v151
	ds_read_b128 v[214:217], v151 offset:1024
	ds_read_b128 v[218:221], v151 offset:2048
	ds_read_b128 v[222:225], v151 offset:3072
	ds_read_b128 v[226:229], v151 offset:4096
	ds_read_b128 v[230:233], v151 offset:5120
	ds_read_b128 v[234:237], v151 offset:6144
	ds_read_b128 v[238:241], v151 offset:7168
	global_load_lds_dwordx4 v[162:163], off
	v_lshl_add_u64 v[162:163], s[22:23], 0, v[138:139]
	s_add_i32 m0, s27, 0xe000
	s_nop 0
	global_load_lds_dwordx4 v[162:163], off
	s_waitcnt vmcnt(8)
	s_waitcnt lgkmcnt(0)
	s_barrier
	s_waitcnt lgkmcnt(0)
	v_mfma_f32_16x16x32_bf16 v[126:129], v[140:143], v[210:213], v[126:129]
	v_mfma_f32_16x16x32_bf16 v[122:125], v[172:175], v[210:213], v[122:125]
	v_mfma_f32_16x16x32_bf16 v[118:121], v[140:143], v[218:221], v[118:121]
	v_mfma_f32_16x16x32_bf16 v[114:117], v[172:175], v[218:221], v[114:117]
	v_mfma_f32_16x16x32_bf16 v[110:113], v[140:143], v[226:229], v[110:113]
	v_mfma_f32_16x16x32_bf16 v[106:109], v[172:175], v[226:229], v[106:109]
	v_mfma_f32_16x16x32_bf16 v[102:105], v[140:143], v[234:237], v[102:105]
	v_mfma_f32_16x16x32_bf16 v[98:101], v[172:175], v[234:237], v[98:101]
	v_mfma_f32_16x16x32_bf16 v[126:129], v[144:147], v[214:217], v[126:129]
	v_mfma_f32_16x16x32_bf16 v[122:125], v[190:193], v[214:217], v[122:125]
	v_mfma_f32_16x16x32_bf16 v[118:121], v[144:147], v[222:225], v[118:121]
	v_mfma_f32_16x16x32_bf16 v[114:117], v[190:193], v[222:225], v[114:117]
	v_mfma_f32_16x16x32_bf16 v[110:113], v[144:147], v[230:233], v[110:113]
	v_mfma_f32_16x16x32_bf16 v[106:109], v[190:193], v[230:233], v[106:109]
	v_mfma_f32_16x16x32_bf16 v[102:105], v[144:147], v[238:241], v[102:105]
	v_mfma_f32_16x16x32_bf16 v[98:101], v[190:193], v[238:241], v[98:101]
	v_mfma_f32_16x16x32_bf16 v[66:69], v[194:197], v[210:213], v[66:69]
	v_mfma_f32_16x16x32_bf16 v[58:61], v[202:205], v[210:213], v[58:61]
	v_mfma_f32_16x16x32_bf16 v[54:57], v[194:197], v[218:221], v[54:57]
	v_mfma_f32_16x16x32_bf16 v[50:53], v[202:205], v[218:221], v[50:53]
	v_mfma_f32_16x16x32_bf16 v[46:49], v[194:197], v[226:229], v[46:49]
	v_mfma_f32_16x16x32_bf16 v[42:45], v[202:205], v[226:229], v[42:45]
	v_mfma_f32_16x16x32_bf16 v[38:41], v[194:197], v[234:237], v[38:41]
	v_mfma_f32_16x16x32_bf16 v[34:37], v[202:205], v[234:237], v[34:37]
	v_mfma_f32_16x16x32_bf16 v[66:69], v[198:201], v[214:217], v[66:69]
	v_mfma_f32_16x16x32_bf16 v[58:61], v[206:209], v[214:217], v[58:61]
	v_mfma_f32_16x16x32_bf16 v[54:57], v[198:201], v[222:225], v[54:57]
	v_mfma_f32_16x16x32_bf16 v[50:53], v[206:209], v[222:225], v[50:53]
	v_mfma_f32_16x16x32_bf16 v[46:49], v[198:201], v[230:233], v[46:49]
	v_mfma_f32_16x16x32_bf16 v[42:45], v[206:209], v[230:233], v[42:45]
	v_mfma_f32_16x16x32_bf16 v[38:41], v[198:201], v[238:241], v[38:41]
	v_mfma_f32_16x16x32_bf16 v[34:37], v[206:209], v[238:241], v[34:37]
	s_barrier
	s_add_i32 s3, s3, s26
	v_lshl_add_u64 v[162:163], s[0:1], 0, v[4:5]
	s_mov_b32 m0, s3
	ds_read_b128 v[210:213], v151 offset:16384
	ds_read_b128 v[214:217], v151 offset:17408
	ds_read_b128 v[218:221], v151 offset:18432
	ds_read_b128 v[222:225], v151 offset:19456
	ds_read_b128 v[226:229], v151 offset:20480
	ds_read_b128 v[230:233], v151 offset:21504
	ds_read_b128 v[234:237], v151 offset:22528
	ds_read_b128 v[238:241], v151 offset:23552
	global_load_lds_dwordx4 v[162:163], off
	s_add_i32 m0, s3, 0x2000
	s_add_u32 s4, s0, 0x40000
	v_lshl_add_u64 v[166:167], s[0:1], 0, v[134:135]
	s_addc_u32 s5, s1, 0
	s_add_i32 s3, s6, s26
	global_load_lds_dwordx4 v[166:167], off
	v_lshl_add_u64 v[176:177], s[4:5], 0, v[4:5]
	s_mov_b32 m0, s3
	v_lshl_add_u64 v[180:181], s[14:15], 0, v[132:133]
	global_load_lds_dwordx4 v[176:177], off
	v_lshl_add_u64 v[176:177], s[4:5], 0, v[134:135]
	s_add_i32 m0, s3, 0x2000
	s_nop 0
	global_load_lds_dwordx4 v[176:177], off
	v_lshl_add_u64 v[176:177], s[14:15], 0, v[130:131]
	s_mov_b32 m0, s27
	s_nop 0
	global_load_lds_dwordx4 v[176:177], off
	s_mov_b32 m0, s30
	s_nop 0
	global_load_lds_dwordx4 v[180:181], off
	s_waitcnt vmcnt(8)
	s_waitcnt lgkmcnt(0)
	s_barrier
	s_waitcnt lgkmcnt(0)
	v_mfma_f32_16x16x32_bf16 v[94:97], v[140:143], v[210:213], v[94:97]
	v_mfma_f32_16x16x32_bf16 v[90:93], v[172:175], v[210:213], v[90:93]
	v_mfma_f32_16x16x32_bf16 v[86:89], v[140:143], v[218:221], v[86:89]
	v_mfma_f32_16x16x32_bf16 v[82:85], v[172:175], v[218:221], v[82:85]
	v_mfma_f32_16x16x32_bf16 v[78:81], v[140:143], v[226:229], v[78:81]
	v_mfma_f32_16x16x32_bf16 v[74:77], v[172:175], v[226:229], v[74:77]
	v_mfma_f32_16x16x32_bf16 v[70:73], v[140:143], v[234:237], v[70:73]
	v_mfma_f32_16x16x32_bf16 v[62:65], v[172:175], v[234:237], v[62:65]
	v_mfma_f32_16x16x32_bf16 v[94:97], v[144:147], v[214:217], v[94:97]
	v_mfma_f32_16x16x32_bf16 v[90:93], v[190:193], v[214:217], v[90:93]
	v_mfma_f32_16x16x32_bf16 v[86:89], v[144:147], v[222:225], v[86:89]
	v_mfma_f32_16x16x32_bf16 v[82:85], v[190:193], v[222:225], v[82:85]
	v_mfma_f32_16x16x32_bf16 v[78:81], v[144:147], v[230:233], v[78:81]
	v_mfma_f32_16x16x32_bf16 v[74:77], v[190:193], v[230:233], v[74:77]
	v_mfma_f32_16x16x32_bf16 v[70:73], v[144:147], v[238:241], v[70:73]
	v_mfma_f32_16x16x32_bf16 v[62:65], v[190:193], v[238:241], v[62:65]
	v_mfma_f32_16x16x32_bf16 v[30:33], v[194:197], v[210:213], v[30:33]
	v_mfma_f32_16x16x32_bf16 v[26:29], v[202:205], v[210:213], v[26:29]
	v_mfma_f32_16x16x32_bf16 v[22:25], v[194:197], v[218:221], v[22:25]
	v_mfma_f32_16x16x32_bf16 v[18:21], v[202:205], v[218:221], v[18:21]
	v_mfma_f32_16x16x32_bf16 v[14:17], v[194:197], v[226:229], v[14:17]
	v_mfma_f32_16x16x32_bf16 v[10:13], v[202:205], v[226:229], v[10:13]
	v_mfma_f32_16x16x32_bf16 v[6:9], v[194:197], v[234:237], v[6:9]
	v_mfma_f32_16x16x32_bf16 v[0:3], v[202:205], v[234:237], v[0:3]
	v_mfma_f32_16x16x32_bf16 v[30:33], v[198:201], v[214:217], v[30:33]
	v_mfma_f32_16x16x32_bf16 v[26:29], v[206:209], v[214:217], v[26:29]
	v_mfma_f32_16x16x32_bf16 v[22:25], v[198:201], v[222:225], v[22:25]
	v_mfma_f32_16x16x32_bf16 v[18:21], v[206:209], v[222:225], v[18:21]
	v_mfma_f32_16x16x32_bf16 v[14:17], v[198:201], v[230:233], v[14:17]
	v_mfma_f32_16x16x32_bf16 v[10:13], v[206:209], v[230:233], v[10:13]
	v_mfma_f32_16x16x32_bf16 v[6:9], v[198:201], v[238:241], v[6:9]
	v_mfma_f32_16x16x32_bf16 v[0:3], v[206:209], v[238:241], v[0:3]
	s_barrier
.Lpeelmid_228:
	s_add_i32 s3, 0, 0x18000
	v_add_u32_e32 v164, s3, v149
	s_add_i32 s6, 0, 0x1c000
	ds_read_b128 v[140:143], v164
	ds_read_b128 v[144:147], v164 offset:1024
	ds_read_b128 v[172:175], v164 offset:2048
	ds_read_b128 v[190:193], v164 offset:3072
	v_add_u32_e32 v164, s6, v149
	ds_read_b128 v[194:197], v164
	ds_read_b128 v[198:201], v164 offset:1024
	ds_read_b128 v[202:205], v164 offset:2048
	ds_read_b128 v[206:209], v164 offset:3072
	s_add_u32 s4, s14, 0x40000
	s_addc_u32 s5, s15, 0
	s_mov_b32 m0, s31
	v_lshl_add_u64 v[242:243], s[4:5], 0, v[130:131]
	ds_read_b128 v[210:213], v151 offset:32768
	ds_read_b128 v[214:217], v151 offset:33792
	ds_read_b128 v[218:221], v151 offset:34816
	ds_read_b128 v[222:225], v151 offset:35840
	ds_read_b128 v[226:229], v151 offset:36864
	ds_read_b128 v[230:233], v151 offset:37888
	ds_read_b128 v[234:237], v151 offset:38912
	ds_read_b128 v[238:241], v151 offset:39936
	global_load_lds_dwordx4 v[242:243], off
	v_lshl_add_u64 v[242:243], s[4:5], 0, v[132:133]
	s_mov_b32 m0, s34
	s_nop 0
	global_load_lds_dwordx4 v[242:243], off
	s_waitcnt vmcnt(8)
	s_waitcnt lgkmcnt(0)
	s_barrier
	s_waitcnt lgkmcnt(0)
	v_mfma_f32_16x16x32_bf16 v[126:129], v[140:143], v[210:213], v[126:129]
	v_mfma_f32_16x16x32_bf16 v[122:125], v[172:175], v[210:213], v[122:125]
	v_mfma_f32_16x16x32_bf16 v[118:121], v[140:143], v[218:221], v[118:121]
	v_mfma_f32_16x16x32_bf16 v[114:117], v[172:175], v[218:221], v[114:117]
	v_mfma_f32_16x16x32_bf16 v[110:113], v[140:143], v[226:229], v[110:113]
	v_mfma_f32_16x16x32_bf16 v[106:109], v[172:175], v[226:229], v[106:109]
	v_mfma_f32_16x16x32_bf16 v[102:105], v[140:143], v[234:237], v[102:105]
	v_mfma_f32_16x16x32_bf16 v[98:101], v[172:175], v[234:237], v[98:101]
	v_mfma_f32_16x16x32_bf16 v[126:129], v[144:147], v[214:217], v[126:129]
	v_mfma_f32_16x16x32_bf16 v[122:125], v[190:193], v[214:217], v[122:125]
	v_mfma_f32_16x16x32_bf16 v[118:121], v[144:147], v[222:225], v[118:121]
	v_mfma_f32_16x16x32_bf16 v[114:117], v[190:193], v[222:225], v[114:117]
	v_mfma_f32_16x16x32_bf16 v[110:113], v[144:147], v[230:233], v[110:113]
	v_mfma_f32_16x16x32_bf16 v[106:109], v[190:193], v[230:233], v[106:109]
	v_mfma_f32_16x16x32_bf16 v[102:105], v[144:147], v[238:241], v[102:105]
	v_mfma_f32_16x16x32_bf16 v[98:101], v[190:193], v[238:241], v[98:101]
	v_mfma_f32_16x16x32_bf16 v[66:69], v[194:197], v[210:213], v[66:69]
	v_mfma_f32_16x16x32_bf16 v[58:61], v[202:205], v[210:213], v[58:61]
	v_mfma_f32_16x16x32_bf16 v[54:57], v[194:197], v[218:221], v[54:57]
	v_mfma_f32_16x16x32_bf16 v[50:53], v[202:205], v[218:221], v[50:53]
	v_mfma_f32_16x16x32_bf16 v[46:49], v[194:197], v[226:229], v[46:49]
	v_mfma_f32_16x16x32_bf16 v[42:45], v[202:205], v[226:229], v[42:45]
	v_mfma_f32_16x16x32_bf16 v[38:41], v[194:197], v[234:237], v[38:41]
	v_mfma_f32_16x16x32_bf16 v[34:37], v[202:205], v[234:237], v[34:37]
	v_mfma_f32_16x16x32_bf16 v[66:69], v[198:201], v[214:217], v[66:69]
	v_mfma_f32_16x16x32_bf16 v[58:61], v[206:209], v[214:217], v[58:61]
	v_mfma_f32_16x16x32_bf16 v[54:57], v[198:201], v[222:225], v[54:57]
	v_mfma_f32_16x16x32_bf16 v[50:53], v[206:209], v[222:225], v[50:53]
	v_mfma_f32_16x16x32_bf16 v[46:49], v[198:201], v[230:233], v[46:49]
	v_mfma_f32_16x16x32_bf16 v[42:45], v[206:209], v[230:233], v[42:45]
	v_mfma_f32_16x16x32_bf16 v[38:41], v[198:201], v[238:241], v[38:41]
	v_mfma_f32_16x16x32_bf16 v[34:37], v[206:209], v[238:241], v[34:37]
	s_barrier
	s_add_i32 s3, s3, s26
	v_lshl_add_u64 v[162:163], v[162:163], 0, s[70:71]
	s_mov_b32 m0, s3
	ds_read_b128 v[210:213], v151 offset:49152
	ds_read_b128 v[214:217], v151 offset:50176
	ds_read_b128 v[218:221], v151 offset:51200
	ds_read_b128 v[222:225], v151 offset:52224
	ds_read_b128 v[226:229], v151 offset:53248
	ds_read_b128 v[230:233], v151 offset:54272
	ds_read_b128 v[234:237], v151 offset:55296
	ds_read_b128 v[238:241], v151 offset:56320
	global_load_lds_dwordx4 v[162:163], off
	s_add_i32 m0, s3, 0x2000
	s_add_u32 s0, s0, 0x40080
	v_lshl_add_u64 v[162:163], v[166:167], 0, s[70:71]
	s_addc_u32 s1, s1, 0
	s_add_i32 s3, s6, s26
	global_load_lds_dwordx4 v[162:163], off
	v_lshl_add_u64 v[162:163], s[0:1], 0, v[4:5]
	s_mov_b32 m0, s3
	s_nop 0
	global_load_lds_dwordx4 v[162:163], off
	v_lshl_add_u64 v[162:163], s[0:1], 0, v[134:135]
	s_add_i32 m0, s3, 0x2000
	s_nop 0
	global_load_lds_dwordx4 v[162:163], off
	v_lshl_add_u64 v[162:163], v[176:177], 0, s[70:71]
	s_mov_b32 m0, s35
	s_nop 0
	global_load_lds_dwordx4 v[162:163], off
	v_lshl_add_u64 v[162:163], v[180:181], 0, s[70:71]
	s_mov_b32 m0, s36
	s_nop 0
	global_load_lds_dwordx4 v[162:163], off
	s_waitcnt vmcnt(8)
	s_waitcnt lgkmcnt(0)
	s_barrier
	s_waitcnt lgkmcnt(0)
	v_mfma_f32_16x16x32_bf16 v[94:97], v[140:143], v[210:213], v[94:97]
	v_mfma_f32_16x16x32_bf16 v[90:93], v[172:175], v[210:213], v[90:93]
	v_mfma_f32_16x16x32_bf16 v[86:89], v[140:143], v[218:221], v[86:89]
	v_mfma_f32_16x16x32_bf16 v[82:85], v[172:175], v[218:221], v[82:85]
	v_mfma_f32_16x16x32_bf16 v[78:81], v[140:143], v[226:229], v[78:81]
	v_mfma_f32_16x16x32_bf16 v[74:77], v[172:175], v[226:229], v[74:77]
	v_mfma_f32_16x16x32_bf16 v[70:73], v[140:143], v[234:237], v[70:73]
	v_mfma_f32_16x16x32_bf16 v[62:65], v[172:175], v[234:237], v[62:65]
	v_mfma_f32_16x16x32_bf16 v[94:97], v[144:147], v[214:217], v[94:97]
	v_mfma_f32_16x16x32_bf16 v[90:93], v[190:193], v[214:217], v[90:93]
	v_mfma_f32_16x16x32_bf16 v[86:89], v[144:147], v[222:225], v[86:89]
	v_mfma_f32_16x16x32_bf16 v[82:85], v[190:193], v[222:225], v[82:85]
	v_mfma_f32_16x16x32_bf16 v[78:81], v[144:147], v[230:233], v[78:81]
	v_mfma_f32_16x16x32_bf16 v[74:77], v[190:193], v[230:233], v[74:77]
	v_mfma_f32_16x16x32_bf16 v[70:73], v[144:147], v[238:241], v[70:73]
	v_mfma_f32_16x16x32_bf16 v[62:65], v[190:193], v[238:241], v[62:65]
	v_mfma_f32_16x16x32_bf16 v[30:33], v[194:197], v[210:213], v[30:33]
	v_mfma_f32_16x16x32_bf16 v[26:29], v[202:205], v[210:213], v[26:29]
	v_mfma_f32_16x16x32_bf16 v[22:25], v[194:197], v[218:221], v[22:25]
	v_mfma_f32_16x16x32_bf16 v[18:21], v[202:205], v[218:221], v[18:21]
	v_mfma_f32_16x16x32_bf16 v[14:17], v[194:197], v[226:229], v[14:17]
	v_mfma_f32_16x16x32_bf16 v[10:13], v[202:205], v[226:229], v[10:13]
	v_mfma_f32_16x16x32_bf16 v[6:9], v[194:197], v[234:237], v[6:9]
	v_mfma_f32_16x16x32_bf16 v[0:3], v[202:205], v[234:237], v[0:3]
	v_mfma_f32_16x16x32_bf16 v[30:33], v[198:201], v[214:217], v[30:33]
	v_mfma_f32_16x16x32_bf16 v[26:29], v[206:209], v[214:217], v[26:29]
	v_mfma_f32_16x16x32_bf16 v[22:25], v[198:201], v[222:225], v[22:25]
	v_mfma_f32_16x16x32_bf16 v[18:21], v[206:209], v[222:225], v[18:21]
	v_mfma_f32_16x16x32_bf16 v[14:17], v[198:201], v[230:233], v[14:17]
	v_mfma_f32_16x16x32_bf16 v[10:13], v[206:209], v[230:233], v[10:13]
	v_mfma_f32_16x16x32_bf16 v[6:9], v[198:201], v[238:241], v[6:9]
	v_mfma_f32_16x16x32_bf16 v[0:3], v[206:209], v[238:241], v[0:3]
	s_barrier
	s_add_i32 s24, s24, 2
	s_add_u32 s22, s22, 0x100
	s_addc_u32 s23, s23, 0
	s_add_u32 s9, s9, 0x100
	s_addc_u32 s10, s10, 0
	s_cmp_gt_u32 s24, 13
	s_cbranch_scc0 .LBB0_228
	s_and_b64 vcc, exec, s[44:45]
	s_cbranch_vccz .LBB0_231
	s_barrier

.LBB0_251:
	s_ashr_i32 s47, s46, 31
	s_lshl_b64 s[2:3], s[46:47], 20
	v_readlane_b32 s4, v253, 36
	s_add_u32 s82, s4, s2
	v_readlane_b32 s2, v253, 37
	s_addc_u32 s83, s2, s3
	s_and_b64 s[2:3], s[40:41], exec
	s_cselect_b32 s2, s83, s15
	s_cselect_b32 s8, s82, s14
	s_add_u32 s22, s0, 0x80080
	s_addc_u32 s23, s1, 0
	s_add_u32 s9, s14, 0x100
	v_mov_b32_e32 v0, 0
	s_addc_u32 s10, s15, 0
	s_mov_b32 s24, -2
	v_mov_b32_e32 v1, v0
	v_mov_b32_e32 v2, v0
	v_mov_b32_e32 v3, v0
	v_mov_b32_e32 v6, v0
	v_mov_b32_e32 v7, v0
	v_mov_b32_e32 v8, v0
	v_mov_b32_e32 v9, v0
	v_mov_b32_e32 v10, v0
	v_mov_b32_e32 v11, v0
	v_mov_b32_e32 v12, v0
	v_mov_b32_e32 v13, v0
	v_mov_b32_e32 v14, v0
	v_mov_b32_e32 v15, v0
	v_mov_b32_e32 v16, v0
	v_mov_b32_e32 v17, v0
	v_mov_b32_e32 v18, v0
	v_mov_b32_e32 v19, v0
	v_mov_b32_e32 v20, v0
	v_mov_b32_e32 v21, v0
	v_mov_b32_e32 v22, v0
	v_mov_b32_e32 v23, v0
	v_mov_b32_e32 v24, v0
	v_mov_b32_e32 v25, v0
	v_mov_b32_e32 v26, v0
	v_mov_b32_e32 v27, v0
	v_mov_b32_e32 v28, v0
	v_mov_b32_e32 v29, v0
	v_mov_b32_e32 v30, v0
	v_mov_b32_e32 v31, v0
	v_mov_b32_e32 v32, v0
	v_mov_b32_e32 v33, v0
	v_mov_b32_e32 v62, v0
	v_mov_b32_e32 v63, v0
	v_mov_b32_e32 v64, v0
	v_mov_b32_e32 v65, v0
	v_mov_b32_e32 v70, v0
	v_mov_b32_e32 v71, v0
	v_mov_b32_e32 v72, v0
	v_mov_b32_e32 v73, v0
	v_mov_b32_e32 v74, v0
	v_mov_b32_e32 v75, v0
	v_mov_b32_e32 v76, v0
	v_mov_b32_e32 v77, v0
	v_mov_b32_e32 v78, v0
	v_mov_b32_e32 v79, v0
	v_mov_b32_e32 v80, v0
	v_mov_b32_e32 v81, v0
	v_mov_b32_e32 v82, v0
	v_mov_b32_e32 v83, v0
	v_mov_b32_e32 v84, v0
	v_mov_b32_e32 v85, v0
	v_mov_b32_e32 v86, v0
	v_mov_b32_e32 v87, v0
	v_mov_b32_e32 v88, v0
	v_mov_b32_e32 v89, v0
	v_mov_b32_e32 v90, v0
	v_mov_b32_e32 v91, v0
	v_mov_b32_e32 v92, v0
	v_mov_b32_e32 v93, v0
	v_mov_b32_e32 v94, v0
	v_mov_b32_e32 v95, v0
	v_mov_b32_e32 v96, v0
	v_mov_b32_e32 v97, v0
	v_mov_b32_e32 v34, v0
	v_mov_b32_e32 v35, v0
	v_mov_b32_e32 v36, v0
	v_mov_b32_e32 v37, v0
	v_mov_b32_e32 v38, v0
	v_mov_b32_e32 v39, v0
	v_mov_b32_e32 v40, v0
	v_mov_b32_e32 v41, v0
	v_mov_b32_e32 v42, v0
	v_mov_b32_e32 v43, v0
	v_mov_b32_e32 v44, v0
	v_mov_b32_e32 v45, v0
	v_mov_b32_e32 v46, v0
	v_mov_b32_e32 v47, v0
	v_mov_b32_e32 v48, v0
	v_mov_b32_e32 v49, v0
	v_mov_b32_e32 v50, v0
	v_mov_b32_e32 v51, v0
	v_mov_b32_e32 v52, v0
	v_mov_b32_e32 v53, v0
	v_mov_b32_e32 v54, v0
	v_mov_b32_e32 v55, v0
	v_mov_b32_e32 v56, v0
	v_mov_b32_e32 v57, v0
	v_mov_b32_e32 v58, v0
	v_mov_b32_e32 v59, v0
	v_mov_b32_e32 v60, v0
	v_mov_b32_e32 v61, v0
	v_mov_b32_e32 v66, v0
	v_mov_b32_e32 v67, v0
	v_mov_b32_e32 v68, v0
	v_mov_b32_e32 v69, v0
	v_mov_b32_e32 v98, v0
	v_mov_b32_e32 v99, v0
	v_mov_b32_e32 v100, v0
	v_mov_b32_e32 v101, v0
	v_mov_b32_e32 v102, v0
	v_mov_b32_e32 v103, v0
	v_mov_b32_e32 v104, v0
	v_mov_b32_e32 v105, v0
	v_mov_b32_e32 v106, v0
	v_mov_b32_e32 v107, v0
	v_mov_b32_e32 v108, v0
	v_mov_b32_e32 v109, v0
	v_mov_b32_e32 v110, v0
	v_mov_b32_e32 v111, v0
	v_mov_b32_e32 v112, v0
	v_mov_b32_e32 v113, v0
	v_mov_b32_e32 v114, v0
	v_mov_b32_e32 v115, v0
	v_mov_b32_e32 v116, v0
	v_mov_b32_e32 v117, v0
	v_mov_b32_e32 v118, v0
	v_mov_b32_e32 v119, v0
	v_mov_b32_e32 v120, v0
	v_mov_b32_e32 v121, v0
	v_mov_b32_e32 v122, v0
	v_mov_b32_e32 v123, v0
	v_mov_b32_e32 v124, v0
	v_mov_b32_e32 v125, v0
	v_mov_b32_e32 v126, v0
	v_mov_b32_e32 v127, v0
	v_mov_b32_e32 v128, v0
	v_mov_b32_e32 v129, v0
	s_cmp_eq_u32 s37, 1
	s_cbranch_scc1 .LBB0_252
	s_add_u32 s0, s22, 0xfff80080
	s_addc_u32 s1, s23, -1
	s_add_i32 s3, 0, 0x10000
	s_cmp_eq_u32 s24, 28
	s_cselect_b32 s15, s49, s1
	s_cselect_b32 s14, s48, s0
	v_add_u32_e32 v162, s3, v141
	s_cselect_b32 s1, s2, s10
	s_cselect_b32 s0, s8, s9
	s_add_i32 s6, 0, 0x14000
	ds_read_b128 v[144:147], v162
	ds_read_b128 v[148:151], v162 offset:1024
	ds_read_b128 v[172:175], v162 offset:2048
	ds_read_b128 v[190:193], v162 offset:3072
	v_add_u32_e32 v162, s6, v141
	ds_read_b128 v[194:197], v162
	ds_read_b128 v[198:201], v162 offset:1024
	ds_read_b128 v[202:205], v162 offset:2048
	ds_read_b128 v[206:209], v162 offset:3072
	v_lshl_add_u64 v[162:163], s[22:23], 0, v[136:137]
	s_add_i32 m0, s27, 0xc000
	ds_read_b128 v[210:213], v143
	ds_read_b128 v[214:217], v143 offset:1024
	ds_read_b128 v[218:221], v143 offset:2048
	ds_read_b128 v[222:225], v143 offset:3072
	ds_read_b128 v[226:229], v143 offset:4096
	ds_read_b128 v[230:233], v143 offset:5120
	ds_read_b128 v[234:237], v143 offset:6144
	ds_read_b128 v[238:241], v143 offset:7168
	global_load_lds_dwordx4 v[162:163], off
	v_lshl_add_u64 v[162:163], s[22:23], 0, v[138:139]
	s_add_i32 m0, s27, 0xe000
	s_nop 0
	global_load_lds_dwordx4 v[162:163], off
	s_waitcnt vmcnt(24)
	s_waitcnt lgkmcnt(0)
	s_barrier
	s_waitcnt lgkmcnt(0)
	v_mfma_f32_16x16x32_bf16 v[126:129], v[144:147], v[210:213], v[126:129]
	v_mfma_f32_16x16x32_bf16 v[122:125], v[172:175], v[210:213], v[122:125]
	v_mfma_f32_16x16x32_bf16 v[118:121], v[144:147], v[218:221], v[118:121]
	v_mfma_f32_16x16x32_bf16 v[114:117], v[172:175], v[218:221], v[114:117]
	v_mfma_f32_16x16x32_bf16 v[110:113], v[144:147], v[226:229], v[110:113]
	v_mfma_f32_16x16x32_bf16 v[106:109], v[172:175], v[226:229], v[106:109]
	v_mfma_f32_16x16x32_bf16 v[102:105], v[144:147], v[234:237], v[102:105]
	v_mfma_f32_16x16x32_bf16 v[98:101], v[172:175], v[234:237], v[98:101]
	v_mfma_f32_16x16x32_bf16 v[126:129], v[148:151], v[214:217], v[126:129]
	v_mfma_f32_16x16x32_bf16 v[122:125], v[190:193], v[214:217], v[122:125]
	v_mfma_f32_16x16x32_bf16 v[118:121], v[148:151], v[222:225], v[118:121]
	v_mfma_f32_16x16x32_bf16 v[114:117], v[190:193], v[222:225], v[114:117]
	v_mfma_f32_16x16x32_bf16 v[110:113], v[148:151], v[230:233], v[110:113]
	v_mfma_f32_16x16x32_bf16 v[106:109], v[190:193], v[230:233], v[106:109]
	v_mfma_f32_16x16x32_bf16 v[102:105], v[148:151], v[238:241], v[102:105]
	v_mfma_f32_16x16x32_bf16 v[98:101], v[190:193], v[238:241], v[98:101]
	v_mfma_f32_16x16x32_bf16 v[66:69], v[194:197], v[210:213], v[66:69]
	v_mfma_f32_16x16x32_bf16 v[58:61], v[202:205], v[210:213], v[58:61]
	v_mfma_f32_16x16x32_bf16 v[54:57], v[194:197], v[218:221], v[54:57]
	v_mfma_f32_16x16x32_bf16 v[50:53], v[202:205], v[218:221], v[50:53]
	v_mfma_f32_16x16x32_bf16 v[46:49], v[194:197], v[226:229], v[46:49]
	v_mfma_f32_16x16x32_bf16 v[42:45], v[202:205], v[226:229], v[42:45]
	v_mfma_f32_16x16x32_bf16 v[38:41], v[194:197], v[234:237], v[38:41]
	v_mfma_f32_16x16x32_bf16 v[34:37], v[202:205], v[234:237], v[34:37]
	v_mfma_f32_16x16x32_bf16 v[66:69], v[198:201], v[214:217], v[66:69]
	v_mfma_f32_16x16x32_bf16 v[58:61], v[206:209], v[214:217], v[58:61]
	v_mfma_f32_16x16x32_bf16 v[54:57], v[198:201], v[222:225], v[54:57]
	v_mfma_f32_16x16x32_bf16 v[50:53], v[206:209], v[222:225], v[50:53]
	v_mfma_f32_16x16x32_bf16 v[46:49], v[198:201], v[230:233], v[46:49]
	v_mfma_f32_16x16x32_bf16 v[42:45], v[206:209], v[230:233], v[42:45]
	v_mfma_f32_16x16x32_bf16 v[38:41], v[198:201], v[238:241], v[38:41]
	v_mfma_f32_16x16x32_bf16 v[34:37], v[206:209], v[238:241], v[34:37]
	s_barrier
	s_add_i32 s3, s3, s26
	v_lshl_add_u64 v[162:163], s[0:1], 0, v[4:5]
	s_mov_b32 m0, s3
	ds_read_b128 v[210:213], v143 offset:16384
	ds_read_b128 v[214:217], v143 offset:17408
	ds_read_b128 v[218:221], v143 offset:18432
	ds_read_b128 v[222:225], v143 offset:19456
	ds_read_b128 v[226:229], v143 offset:20480
	ds_read_b128 v[230:233], v143 offset:21504
	ds_read_b128 v[234:237], v143 offset:22528
	ds_read_b128 v[238:241], v143 offset:23552
	global_load_lds_dwordx4 v[162:163], off
	s_add_i32 m0, s3, 0x2000
	s_add_u32 s4, s0, 0x80000
	v_lshl_add_u64 v[166:167], s[0:1], 0, v[130:131]
	s_addc_u32 s5, s1, 0
	s_add_i32 s3, s6, s26
	global_load_lds_dwordx4 v[166:167], off
	v_lshl_add_u64 v[176:177], s[4:5], 0, v[4:5]
	s_mov_b32 m0, s3
	v_lshl_add_u64 v[242:243], s[14:15], 0, v[132:133]
	global_load_lds_dwordx4 v[176:177], off
	v_lshl_add_u64 v[176:177], s[4:5], 0, v[130:131]
	s_add_i32 m0, s3, 0x2000
	s_nop 0
	global_load_lds_dwordx4 v[176:177], off
	v_lshl_add_u64 v[176:177], s[14:15], 0, v[134:135]
	s_mov_b32 m0, s27
	s_nop 0
	global_load_lds_dwordx4 v[176:177], off
	s_mov_b32 m0, s30
	s_nop 0
	global_load_lds_dwordx4 v[242:243], off
	s_waitcnt vmcnt(24)
	s_waitcnt lgkmcnt(0)
	s_barrier
	s_waitcnt lgkmcnt(0)
	v_mfma_f32_16x16x32_bf16 v[94:97], v[144:147], v[210:213], v[94:97]
	v_mfma_f32_16x16x32_bf16 v[90:93], v[172:175], v[210:213], v[90:93]
	v_mfma_f32_16x16x32_bf16 v[86:89], v[144:147], v[218:221], v[86:89]
	v_mfma_f32_16x16x32_bf16 v[82:85], v[172:175], v[218:221], v[82:85]
	v_mfma_f32_16x16x32_bf16 v[78:81], v[144:147], v[226:229], v[78:81]
	v_mfma_f32_16x16x32_bf16 v[74:77], v[172:175], v[226:229], v[74:77]
	v_mfma_f32_16x16x32_bf16 v[70:73], v[144:147], v[234:237], v[70:73]
	v_mfma_f32_16x16x32_bf16 v[62:65], v[172:175], v[234:237], v[62:65]
	v_mfma_f32_16x16x32_bf16 v[94:97], v[148:151], v[214:217], v[94:97]
	v_mfma_f32_16x16x32_bf16 v[90:93], v[190:193], v[214:217], v[90:93]
	v_mfma_f32_16x16x32_bf16 v[86:89], v[148:151], v[222:225], v[86:89]
	v_mfma_f32_16x16x32_bf16 v[82:85], v[190:193], v[222:225], v[82:85]
	v_mfma_f32_16x16x32_bf16 v[78:81], v[148:151], v[230:233], v[78:81]
	v_mfma_f32_16x16x32_bf16 v[74:77], v[190:193], v[230:233], v[74:77]
	v_mfma_f32_16x16x32_bf16 v[70:73], v[148:151], v[238:241], v[70:73]
	v_mfma_f32_16x16x32_bf16 v[62:65], v[190:193], v[238:241], v[62:65]
	v_mfma_f32_16x16x32_bf16 v[30:33], v[194:197], v[210:213], v[30:33]
	v_mfma_f32_16x16x32_bf16 v[26:29], v[202:205], v[210:213], v[26:29]
	v_mfma_f32_16x16x32_bf16 v[22:25], v[194:197], v[218:221], v[22:25]
	v_mfma_f32_16x16x32_bf16 v[18:21], v[202:205], v[218:221], v[18:21]
	v_mfma_f32_16x16x32_bf16 v[14:17], v[194:197], v[226:229], v[14:17]
	v_mfma_f32_16x16x32_bf16 v[10:13], v[202:205], v[226:229], v[10:13]
	v_mfma_f32_16x16x32_bf16 v[6:9], v[194:197], v[234:237], v[6:9]
	v_mfma_f32_16x16x32_bf16 v[0:3], v[202:205], v[234:237], v[0:3]
	v_mfma_f32_16x16x32_bf16 v[30:33], v[198:201], v[214:217], v[30:33]
	v_mfma_f32_16x16x32_bf16 v[26:29], v[206:209], v[214:217], v[26:29]
	v_mfma_f32_16x16x32_bf16 v[22:25], v[198:201], v[222:225], v[22:25]
	v_mfma_f32_16x16x32_bf16 v[18:21], v[206:209], v[222:225], v[18:21]
	v_mfma_f32_16x16x32_bf16 v[14:17], v[198:201], v[230:233], v[14:17]
	v_mfma_f32_16x16x32_bf16 v[10:13], v[206:209], v[230:233], v[10:13]
	v_mfma_f32_16x16x32_bf16 v[6:9], v[198:201], v[238:241], v[6:9]
	v_mfma_f32_16x16x32_bf16 v[0:3], v[206:209], v[238:241], v[0:3]
	s_barrier
	s_branch .Lpeelmid_252
.LBB0_252:
	s_add_u32 s0, s22, 0xfff80080
	s_addc_u32 s1, s23, -1
	s_add_i32 s3, 0, 0x10000
	s_cmp_eq_u32 s24, 28
	s_cselect_b32 s15, s49, s1
	s_cselect_b32 s14, s48, s0
	v_add_u32_e32 v162, s3, v141
	s_cselect_b32 s1, s2, s10
	s_cselect_b32 s0, s8, s9
	s_add_i32 s6, 0, 0x14000
	ds_read_b128 v[144:147], v162
	ds_read_b128 v[148:151], v162 offset:1024
	ds_read_b128 v[172:175], v162 offset:2048
	ds_read_b128 v[190:193], v162 offset:3072
	v_add_u32_e32 v162, s6, v141
	ds_read_b128 v[194:197], v162
	ds_read_b128 v[198:201], v162 offset:1024
	ds_read_b128 v[202:205], v162 offset:2048
	ds_read_b128 v[206:209], v162 offset:3072
	v_lshl_add_u64 v[162:163], s[22:23], 0, v[136:137]
	s_add_i32 m0, s27, 0xc000
	ds_read_b128 v[210:213], v143
	ds_read_b128 v[214:217], v143 offset:1024
	ds_read_b128 v[218:221], v143 offset:2048
	ds_read_b128 v[222:225], v143 offset:3072
	ds_read_b128 v[226:229], v143 offset:4096
	ds_read_b128 v[230:233], v143 offset:5120
	ds_read_b128 v[234:237], v143 offset:6144
	ds_read_b128 v[238:241], v143 offset:7168
	global_load_lds_dwordx4 v[162:163], off
	v_lshl_add_u64 v[162:163], s[22:23], 0, v[138:139]
	s_add_i32 m0, s27, 0xe000
	s_nop 0
	global_load_lds_dwordx4 v[162:163], off
	s_waitcnt vmcnt(8)
	s_waitcnt lgkmcnt(0)
	s_barrier
	s_waitcnt lgkmcnt(0)
	v_mfma_f32_16x16x32_bf16 v[126:129], v[144:147], v[210:213], v[126:129]
	v_mfma_f32_16x16x32_bf16 v[122:125], v[172:175], v[210:213], v[122:125]
	v_mfma_f32_16x16x32_bf16 v[118:121], v[144:147], v[218:221], v[118:121]
	v_mfma_f32_16x16x32_bf16 v[114:117], v[172:175], v[218:221], v[114:117]
	v_mfma_f32_16x16x32_bf16 v[110:113], v[144:147], v[226:229], v[110:113]
	v_mfma_f32_16x16x32_bf16 v[106:109], v[172:175], v[226:229], v[106:109]
	v_mfma_f32_16x16x32_bf16 v[102:105], v[144:147], v[234:237], v[102:105]
	v_mfma_f32_16x16x32_bf16 v[98:101], v[172:175], v[234:237], v[98:101]
	v_mfma_f32_16x16x32_bf16 v[126:129], v[148:151], v[214:217], v[126:129]
	v_mfma_f32_16x16x32_bf16 v[122:125], v[190:193], v[214:217], v[122:125]
	v_mfma_f32_16x16x32_bf16 v[118:121], v[148:151], v[222:225], v[118:121]
	v_mfma_f32_16x16x32_bf16 v[114:117], v[190:193], v[222:225], v[114:117]
	v_mfma_f32_16x16x32_bf16 v[110:113], v[148:151], v[230:233], v[110:113]
	v_mfma_f32_16x16x32_bf16 v[106:109], v[190:193], v[230:233], v[106:109]
	v_mfma_f32_16x16x32_bf16 v[102:105], v[148:151], v[238:241], v[102:105]
	v_mfma_f32_16x16x32_bf16 v[98:101], v[190:193], v[238:241], v[98:101]
	v_mfma_f32_16x16x32_bf16 v[66:69], v[194:197], v[210:213], v[66:69]
	v_mfma_f32_16x16x32_bf16 v[58:61], v[202:205], v[210:213], v[58:61]
	v_mfma_f32_16x16x32_bf16 v[54:57], v[194:197], v[218:221], v[54:57]
	v_mfma_f32_16x16x32_bf16 v[50:53], v[202:205], v[218:221], v[50:53]
	v_mfma_f32_16x16x32_bf16 v[46:49], v[194:197], v[226:229], v[46:49]
	v_mfma_f32_16x16x32_bf16 v[42:45], v[202:205], v[226:229], v[42:45]
	v_mfma_f32_16x16x32_bf16 v[38:41], v[194:197], v[234:237], v[38:41]
	v_mfma_f32_16x16x32_bf16 v[34:37], v[202:205], v[234:237], v[34:37]
	v_mfma_f32_16x16x32_bf16 v[66:69], v[198:201], v[214:217], v[66:69]
	v_mfma_f32_16x16x32_bf16 v[58:61], v[206:209], v[214:217], v[58:61]
	v_mfma_f32_16x16x32_bf16 v[54:57], v[198:201], v[222:225], v[54:57]
	v_mfma_f32_16x16x32_bf16 v[50:53], v[206:209], v[222:225], v[50:53]
	v_mfma_f32_16x16x32_bf16 v[46:49], v[198:201], v[230:233], v[46:49]
	v_mfma_f32_16x16x32_bf16 v[42:45], v[206:209], v[230:233], v[42:45]
	v_mfma_f32_16x16x32_bf16 v[38:41], v[198:201], v[238:241], v[38:41]
	v_mfma_f32_16x16x32_bf16 v[34:37], v[206:209], v[238:241], v[34:37]
	s_barrier
	s_add_i32 s3, s3, s26
	v_lshl_add_u64 v[162:163], s[0:1], 0, v[4:5]
	s_mov_b32 m0, s3
	ds_read_b128 v[210:213], v143 offset:16384
	ds_read_b128 v[214:217], v143 offset:17408
	ds_read_b128 v[218:221], v143 offset:18432
	ds_read_b128 v[222:225], v143 offset:19456
	ds_read_b128 v[226:229], v143 offset:20480
	ds_read_b128 v[230:233], v143 offset:21504
	ds_read_b128 v[234:237], v143 offset:22528
	ds_read_b128 v[238:241], v143 offset:23552
	global_load_lds_dwordx4 v[162:163], off
	s_add_i32 m0, s3, 0x2000
	s_add_u32 s4, s0, 0x80000
	v_lshl_add_u64 v[166:167], s[0:1], 0, v[130:131]
	s_addc_u32 s5, s1, 0
	s_add_i32 s3, s6, s26
	global_load_lds_dwordx4 v[166:167], off
	v_lshl_add_u64 v[176:177], s[4:5], 0, v[4:5]
	s_mov_b32 m0, s3
	v_lshl_add_u64 v[242:243], s[14:15], 0, v[132:133]
	global_load_lds_dwordx4 v[176:177], off
	v_lshl_add_u64 v[176:177], s[4:5], 0, v[130:131]
	s_add_i32 m0, s3, 0x2000
	s_nop 0
	global_load_lds_dwordx4 v[176:177], off
	v_lshl_add_u64 v[176:177], s[14:15], 0, v[134:135]
	s_mov_b32 m0, s27
	s_nop 0
	global_load_lds_dwordx4 v[176:177], off
	s_mov_b32 m0, s30
	s_nop 0
	global_load_lds_dwordx4 v[242:243], off
	s_waitcnt vmcnt(8)
	s_waitcnt lgkmcnt(0)
	s_barrier
	s_waitcnt lgkmcnt(0)
	v_mfma_f32_16x16x32_bf16 v[94:97], v[144:147], v[210:213], v[94:97]
	v_mfma_f32_16x16x32_bf16 v[90:93], v[172:175], v[210:213], v[90:93]
	v_mfma_f32_16x16x32_bf16 v[86:89], v[144:147], v[218:221], v[86:89]
	v_mfma_f32_16x16x32_bf16 v[82:85], v[172:175], v[218:221], v[82:85]
	v_mfma_f32_16x16x32_bf16 v[78:81], v[144:147], v[226:229], v[78:81]
	v_mfma_f32_16x16x32_bf16 v[74:77], v[172:175], v[226:229], v[74:77]
	v_mfma_f32_16x16x32_bf16 v[70:73], v[144:147], v[234:237], v[70:73]
	v_mfma_f32_16x16x32_bf16 v[62:65], v[172:175], v[234:237], v[62:65]
	v_mfma_f32_16x16x32_bf16 v[94:97], v[148:151], v[214:217], v[94:97]
	v_mfma_f32_16x16x32_bf16 v[90:93], v[190:193], v[214:217], v[90:93]
	v_mfma_f32_16x16x32_bf16 v[86:89], v[148:151], v[222:225], v[86:89]
	v_mfma_f32_16x16x32_bf16 v[82:85], v[190:193], v[222:225], v[82:85]
	v_mfma_f32_16x16x32_bf16 v[78:81], v[148:151], v[230:233], v[78:81]
	v_mfma_f32_16x16x32_bf16 v[74:77], v[190:193], v[230:233], v[74:77]
	v_mfma_f32_16x16x32_bf16 v[70:73], v[148:151], v[238:241], v[70:73]
	v_mfma_f32_16x16x32_bf16 v[62:65], v[190:193], v[238:241], v[62:65]
	v_mfma_f32_16x16x32_bf16 v[30:33], v[194:197], v[210:213], v[30:33]
	v_mfma_f32_16x16x32_bf16 v[26:29], v[202:205], v[210:213], v[26:29]
	v_mfma_f32_16x16x32_bf16 v[22:25], v[194:197], v[218:221], v[22:25]
	v_mfma_f32_16x16x32_bf16 v[18:21], v[202:205], v[218:221], v[18:21]
	v_mfma_f32_16x16x32_bf16 v[14:17], v[194:197], v[226:229], v[14:17]
	v_mfma_f32_16x16x32_bf16 v[10:13], v[202:205], v[226:229], v[10:13]
	v_mfma_f32_16x16x32_bf16 v[6:9], v[194:197], v[234:237], v[6:9]
	v_mfma_f32_16x16x32_bf16 v[0:3], v[202:205], v[234:237], v[0:3]
	v_mfma_f32_16x16x32_bf16 v[30:33], v[198:201], v[214:217], v[30:33]
	v_mfma_f32_16x16x32_bf16 v[26:29], v[206:209], v[214:217], v[26:29]
	v_mfma_f32_16x16x32_bf16 v[22:25], v[198:201], v[222:225], v[22:25]
	v_mfma_f32_16x16x32_bf16 v[18:21], v[206:209], v[222:225], v[18:21]
	v_mfma_f32_16x16x32_bf16 v[14:17], v[198:201], v[230:233], v[14:17]
	v_mfma_f32_16x16x32_bf16 v[10:13], v[206:209], v[230:233], v[10:13]
	v_mfma_f32_16x16x32_bf16 v[6:9], v[198:201], v[238:241], v[6:9]
	v_mfma_f32_16x16x32_bf16 v[0:3], v[206:209], v[238:241], v[0:3]
	s_barrier
.Lpeelmid_252:
	s_add_i32 s3, 0, 0x18000
	v_add_u32_e32 v164, s3, v141
	s_add_i32 s6, 0, 0x1c000
	ds_read_b128 v[144:147], v164
	ds_read_b128 v[148:151], v164 offset:1024
	ds_read_b128 v[172:175], v164 offset:2048
	ds_read_b128 v[190:193], v164 offset:3072
	v_add_u32_e32 v164, s6, v141
	ds_read_b128 v[194:197], v164
	ds_read_b128 v[198:201], v164 offset:1024
	ds_read_b128 v[202:205], v164 offset:2048
	ds_read_b128 v[206:209], v164 offset:3072
	s_add_u32 s4, s14, 0x80000
	s_addc_u32 s5, s15, 0
	s_mov_b32 m0, s31
	v_lshl_add_u64 v[244:245], s[4:5], 0, v[134:135]
	ds_read_b128 v[210:213], v143 offset:32768
	ds_read_b128 v[214:217], v143 offset:33792
	ds_read_b128 v[218:221], v143 offset:34816
	ds_read_b128 v[222:225], v143 offset:35840
	ds_read_b128 v[226:229], v143 offset:36864
	ds_read_b128 v[230:233], v143 offset:37888
	ds_read_b128 v[234:237], v143 offset:38912
	ds_read_b128 v[238:241], v143 offset:39936
	global_load_lds_dwordx4 v[244:245], off
	v_lshl_add_u64 v[244:245], s[4:5], 0, v[132:133]
	s_mov_b32 m0, s34
	s_nop 0
	global_load_lds_dwordx4 v[244:245], off
	s_waitcnt vmcnt(8)
	s_waitcnt lgkmcnt(0)
	s_barrier
	s_waitcnt lgkmcnt(0)
	v_mfma_f32_16x16x32_bf16 v[126:129], v[144:147], v[210:213], v[126:129]
	v_mfma_f32_16x16x32_bf16 v[122:125], v[172:175], v[210:213], v[122:125]
	v_mfma_f32_16x16x32_bf16 v[118:121], v[144:147], v[218:221], v[118:121]
	v_mfma_f32_16x16x32_bf16 v[114:117], v[172:175], v[218:221], v[114:117]
	v_mfma_f32_16x16x32_bf16 v[110:113], v[144:147], v[226:229], v[110:113]
	v_mfma_f32_16x16x32_bf16 v[106:109], v[172:175], v[226:229], v[106:109]
	v_mfma_f32_16x16x32_bf16 v[102:105], v[144:147], v[234:237], v[102:105]
	v_mfma_f32_16x16x32_bf16 v[98:101], v[172:175], v[234:237], v[98:101]
	v_mfma_f32_16x16x32_bf16 v[126:129], v[148:151], v[214:217], v[126:129]
	v_mfma_f32_16x16x32_bf16 v[122:125], v[190:193], v[214:217], v[122:125]
	v_mfma_f32_16x16x32_bf16 v[118:121], v[148:151], v[222:225], v[118:121]
	v_mfma_f32_16x16x32_bf16 v[114:117], v[190:193], v[222:225], v[114:117]
	v_mfma_f32_16x16x32_bf16 v[110:113], v[148:151], v[230:233], v[110:113]
	v_mfma_f32_16x16x32_bf16 v[106:109], v[190:193], v[230:233], v[106:109]
	v_mfma_f32_16x16x32_bf16 v[102:105], v[148:151], v[238:241], v[102:105]
	v_mfma_f32_16x16x32_bf16 v[98:101], v[190:193], v[238:241], v[98:101]
	v_mfma_f32_16x16x32_bf16 v[66:69], v[194:197], v[210:213], v[66:69]
	v_mfma_f32_16x16x32_bf16 v[58:61], v[202:205], v[210:213], v[58:61]
	v_mfma_f32_16x16x32_bf16 v[54:57], v[194:197], v[218:221], v[54:57]
	v_mfma_f32_16x16x32_bf16 v[50:53], v[202:205], v[218:221], v[50:53]
	v_mfma_f32_16x16x32_bf16 v[46:49], v[194:197], v[226:229], v[46:49]
	v_mfma_f32_16x16x32_bf16 v[42:45], v[202:205], v[226:229], v[42:45]
	v_mfma_f32_16x16x32_bf16 v[38:41], v[194:197], v[234:237], v[38:41]
	v_mfma_f32_16x16x32_bf16 v[34:37], v[202:205], v[234:237], v[34:37]
	v_mfma_f32_16x16x32_bf16 v[66:69], v[198:201], v[214:217], v[66:69]
	v_mfma_f32_16x16x32_bf16 v[58:61], v[206:209], v[214:217], v[58:61]
	v_mfma_f32_16x16x32_bf16 v[54:57], v[198:201], v[222:225], v[54:57]
	v_mfma_f32_16x16x32_bf16 v[50:53], v[206:209], v[222:225], v[50:53]
	v_mfma_f32_16x16x32_bf16 v[46:49], v[198:201], v[230:233], v[46:49]
	v_mfma_f32_16x16x32_bf16 v[42:45], v[206:209], v[230:233], v[42:45]
	v_mfma_f32_16x16x32_bf16 v[38:41], v[198:201], v[238:241], v[38:41]
	v_mfma_f32_16x16x32_bf16 v[34:37], v[206:209], v[238:241], v[34:37]
	s_barrier
	s_add_i32 s3, s3, s26
	v_lshl_add_u64 v[162:163], v[162:163], 0, s[70:71]
	s_mov_b32 m0, s3
	ds_read_b128 v[210:213], v143 offset:49152
	ds_read_b128 v[214:217], v143 offset:50176
	ds_read_b128 v[218:221], v143 offset:51200
	ds_read_b128 v[222:225], v143 offset:52224
	ds_read_b128 v[226:229], v143 offset:53248
	ds_read_b128 v[230:233], v143 offset:54272
	ds_read_b128 v[234:237], v143 offset:55296
	ds_read_b128 v[238:241], v143 offset:56320
	global_load_lds_dwordx4 v[162:163], off
	s_add_i32 m0, s3, 0x2000
	s_add_u32 s0, s0, 0x80080
	v_lshl_add_u64 v[162:163], v[166:167], 0, s[70:71]
	s_addc_u32 s1, s1, 0
	s_add_i32 s3, s6, s26
	global_load_lds_dwordx4 v[162:163], off
	v_lshl_add_u64 v[162:163], s[0:1], 0, v[4:5]
	s_mov_b32 m0, s3
	s_nop 0
	global_load_lds_dwordx4 v[162:163], off
	v_lshl_add_u64 v[162:163], s[0:1], 0, v[130:131]
	s_add_i32 m0, s3, 0x2000
	s_nop 0
	global_load_lds_dwordx4 v[162:163], off
	v_lshl_add_u64 v[162:163], v[176:177], 0, s[70:71]
	s_mov_b32 m0, s35
	s_nop 0
	global_load_lds_dwordx4 v[162:163], off
	v_lshl_add_u64 v[162:163], v[242:243], 0, s[70:71]
	s_mov_b32 m0, s36
	s_nop 0
	global_load_lds_dwordx4 v[162:163], off
	s_waitcnt vmcnt(8)
	s_waitcnt lgkmcnt(0)
	s_barrier
	s_waitcnt lgkmcnt(0)
	v_mfma_f32_16x16x32_bf16 v[94:97], v[144:147], v[210:213], v[94:97]
	v_mfma_f32_16x16x32_bf16 v[90:93], v[172:175], v[210:213], v[90:93]
	v_mfma_f32_16x16x32_bf16 v[86:89], v[144:147], v[218:221], v[86:89]
	v_mfma_f32_16x16x32_bf16 v[82:85], v[172:175], v[218:221], v[82:85]
	v_mfma_f32_16x16x32_bf16 v[78:81], v[144:147], v[226:229], v[78:81]
	v_mfma_f32_16x16x32_bf16 v[74:77], v[172:175], v[226:229], v[74:77]
	v_mfma_f32_16x16x32_bf16 v[70:73], v[144:147], v[234:237], v[70:73]
	v_mfma_f32_16x16x32_bf16 v[62:65], v[172:175], v[234:237], v[62:65]
	v_mfma_f32_16x16x32_bf16 v[94:97], v[148:151], v[214:217], v[94:97]
	v_mfma_f32_16x16x32_bf16 v[90:93], v[190:193], v[214:217], v[90:93]
	v_mfma_f32_16x16x32_bf16 v[86:89], v[148:151], v[222:225], v[86:89]
	v_mfma_f32_16x16x32_bf16 v[82:85], v[190:193], v[222:225], v[82:85]
	v_mfma_f32_16x16x32_bf16 v[78:81], v[148:151], v[230:233], v[78:81]
	v_mfma_f32_16x16x32_bf16 v[74:77], v[190:193], v[230:233], v[74:77]
	v_mfma_f32_16x16x32_bf16 v[70:73], v[148:151], v[238:241], v[70:73]
	v_mfma_f32_16x16x32_bf16 v[62:65], v[190:193], v[238:241], v[62:65]
	v_mfma_f32_16x16x32_bf16 v[30:33], v[194:197], v[210:213], v[30:33]
	v_mfma_f32_16x16x32_bf16 v[26:29], v[202:205], v[210:213], v[26:29]
	v_mfma_f32_16x16x32_bf16 v[22:25], v[194:197], v[218:221], v[22:25]
	v_mfma_f32_16x16x32_bf16 v[18:21], v[202:205], v[218:221], v[18:21]
	v_mfma_f32_16x16x32_bf16 v[14:17], v[194:197], v[226:229], v[14:17]
	v_mfma_f32_16x16x32_bf16 v[10:13], v[202:205], v[226:229], v[10:13]
	v_mfma_f32_16x16x32_bf16 v[6:9], v[194:197], v[234:237], v[6:9]
	v_mfma_f32_16x16x32_bf16 v[0:3], v[202:205], v[234:237], v[0:3]
	v_mfma_f32_16x16x32_bf16 v[30:33], v[198:201], v[214:217], v[30:33]
	v_mfma_f32_16x16x32_bf16 v[26:29], v[206:209], v[214:217], v[26:29]
	v_mfma_f32_16x16x32_bf16 v[22:25], v[198:201], v[222:225], v[22:25]
	v_mfma_f32_16x16x32_bf16 v[18:21], v[206:209], v[222:225], v[18:21]
	v_mfma_f32_16x16x32_bf16 v[14:17], v[198:201], v[230:233], v[14:17]
	v_mfma_f32_16x16x32_bf16 v[10:13], v[206:209], v[230:233], v[10:13]
	v_mfma_f32_16x16x32_bf16 v[6:9], v[198:201], v[238:241], v[6:9]
	v_mfma_f32_16x16x32_bf16 v[0:3], v[206:209], v[238:241], v[0:3]
	s_barrier
	s_add_i32 s24, s24, 2
	s_add_u32 s22, s22, 0x100
	s_addc_u32 s23, s23, 0
	s_add_u32 s9, s9, 0x100
	s_addc_u32 s10, s10, 0
	s_cmp_gt_u32 s24, 29
	s_cbranch_scc0 .LBB0_252
	s_and_b64 vcc, exec, s[44:45]
	s_cbranch_vccz .LBB0_255
	s_barrier

.LBB0_851:
	s_ashr_i32 s3, s37, 24
	s_lshl_b32 s2, s37, 8
	s_andn2_b32 s3, s3, 63
	s_add_i32 s2, s3, s2
	s_ashr_i32 s3, s2, 31
	s_lshl_b64 s[2:3], s[2:3], 12
	v_readlane_b32 s4, v252, 6
	v_readlane_b32 s5, v252, 7
	s_add_u32 s76, s4, s2
	s_addc_u32 s77, s5, s3
	s_and_b64 s[2:3], s[38:39], exec
	s_cselect_b32 s2, s77, s15
	s_cselect_b32 s8, s76, s14
	s_ashr_i32 s59, s58, 31
	s_lshl_b64 s[4:5], s[58:59], 20
	v_readlane_b32 s6, v252, 4
	v_readlane_b32 s7, v252, 5
	s_add_u32 s78, s6, s4
	s_addc_u32 s79, s7, s5
	s_and_b64 s[4:5], s[38:39], exec
	s_cselect_b32 s10, s79, s1
	s_cselect_b32 s24, s78, s0
	s_add_u32 s22, s14, 0x80080
	s_addc_u32 s23, s15, 0
	s_add_u32 s9, s0, 0x100
	v_mov_b32_e32 v0, 0
	s_addc_u32 s25, s1, 0
	s_mov_b32 s28, -2
	v_mov_b32_e32 v1, v0
	v_mov_b32_e32 v2, v0
	v_mov_b32_e32 v3, v0
	v_mov_b32_e32 v6, v0
	v_mov_b32_e32 v7, v0
	v_mov_b32_e32 v8, v0
	v_mov_b32_e32 v9, v0
	v_mov_b32_e32 v10, v0
	v_mov_b32_e32 v11, v0
	v_mov_b32_e32 v12, v0
	v_mov_b32_e32 v13, v0
	v_mov_b32_e32 v14, v0
	v_mov_b32_e32 v15, v0
	v_mov_b32_e32 v16, v0
	v_mov_b32_e32 v17, v0
	v_mov_b32_e32 v18, v0
	v_mov_b32_e32 v19, v0
	v_mov_b32_e32 v20, v0
	v_mov_b32_e32 v21, v0
	v_mov_b32_e32 v22, v0
	v_mov_b32_e32 v23, v0
	v_mov_b32_e32 v24, v0
	v_mov_b32_e32 v25, v0
	v_mov_b32_e32 v26, v0
	v_mov_b32_e32 v27, v0
	v_mov_b32_e32 v28, v0
	v_mov_b32_e32 v29, v0
	v_mov_b32_e32 v30, v0
	v_mov_b32_e32 v31, v0
	v_mov_b32_e32 v32, v0
	v_mov_b32_e32 v33, v0
	v_mov_b32_e32 v66, v0
	v_mov_b32_e32 v67, v0
	v_mov_b32_e32 v68, v0
	v_mov_b32_e32 v69, v0
	v_mov_b32_e32 v70, v0
	v_mov_b32_e32 v71, v0
	v_mov_b32_e32 v72, v0
	v_mov_b32_e32 v73, v0
	v_mov_b32_e32 v74, v0
	v_mov_b32_e32 v75, v0
	v_mov_b32_e32 v76, v0
	v_mov_b32_e32 v77, v0
	v_mov_b32_e32 v78, v0
	v_mov_b32_e32 v79, v0
	v_mov_b32_e32 v80, v0
	v_mov_b32_e32 v81, v0
	v_mov_b32_e32 v82, v0
	v_mov_b32_e32 v83, v0
	v_mov_b32_e32 v84, v0
	v_mov_b32_e32 v85, v0
	v_mov_b32_e32 v86, v0
	v_mov_b32_e32 v87, v0
	v_mov_b32_e32 v88, v0
	v_mov_b32_e32 v89, v0
	v_mov_b32_e32 v90, v0
	v_mov_b32_e32 v91, v0
	v_mov_b32_e32 v92, v0
	v_mov_b32_e32 v93, v0
	v_mov_b32_e32 v94, v0
	v_mov_b32_e32 v95, v0
	v_mov_b32_e32 v96, v0
	v_mov_b32_e32 v97, v0
	v_mov_b32_e32 v34, v0
	v_mov_b32_e32 v35, v0
	v_mov_b32_e32 v36, v0
	v_mov_b32_e32 v37, v0
	v_mov_b32_e32 v38, v0
	v_mov_b32_e32 v39, v0
	v_mov_b32_e32 v40, v0
	v_mov_b32_e32 v41, v0
	v_mov_b32_e32 v42, v0
	v_mov_b32_e32 v43, v0
	v_mov_b32_e32 v44, v0
	v_mov_b32_e32 v45, v0
	v_mov_b32_e32 v46, v0
	v_mov_b32_e32 v47, v0
	v_mov_b32_e32 v48, v0
	v_mov_b32_e32 v49, v0
	v_mov_b32_e32 v50, v0
	v_mov_b32_e32 v51, v0
	v_mov_b32_e32 v52, v0
	v_mov_b32_e32 v53, v0
	v_mov_b32_e32 v54, v0
	v_mov_b32_e32 v55, v0
	v_mov_b32_e32 v56, v0
	v_mov_b32_e32 v57, v0
	v_mov_b32_e32 v58, v0
	v_mov_b32_e32 v59, v0
	v_mov_b32_e32 v60, v0
	v_mov_b32_e32 v61, v0
	v_mov_b32_e32 v62, v0
	v_mov_b32_e32 v63, v0
	v_mov_b32_e32 v64, v0
	v_mov_b32_e32 v65, v0
	v_mov_b32_e32 v98, v0
	v_mov_b32_e32 v99, v0
	v_mov_b32_e32 v100, v0
	v_mov_b32_e32 v101, v0
	v_mov_b32_e32 v102, v0
	v_mov_b32_e32 v103, v0
	v_mov_b32_e32 v104, v0
	v_mov_b32_e32 v105, v0
	v_mov_b32_e32 v106, v0
	v_mov_b32_e32 v107, v0
	v_mov_b32_e32 v108, v0
	v_mov_b32_e32 v109, v0
	v_mov_b32_e32 v110, v0
	v_mov_b32_e32 v111, v0
	v_mov_b32_e32 v112, v0
	v_mov_b32_e32 v113, v0
	v_mov_b32_e32 v114, v0
	v_mov_b32_e32 v115, v0
	v_mov_b32_e32 v116, v0
	v_mov_b32_e32 v117, v0
	v_mov_b32_e32 v118, v0
	v_mov_b32_e32 v119, v0
	v_mov_b32_e32 v120, v0
	v_mov_b32_e32 v121, v0
	v_mov_b32_e32 v122, v0
	v_mov_b32_e32 v123, v0
	v_mov_b32_e32 v124, v0
	v_mov_b32_e32 v125, v0
	v_mov_b32_e32 v126, v0
	v_mov_b32_e32 v127, v0
	v_mov_b32_e32 v128, v0
	v_mov_b32_e32 v129, v0
	s_cmp_eq_u32 s36, 1
	s_cbranch_scc1 .LBB0_852
	s_add_u32 s0, s22, 0xfff80080
	s_addc_u32 s1, s23, -1
	s_add_i32 s3, 0, 0x10000
	s_cmp_eq_u32 s28, 28
	s_cselect_b32 s15, s2, s1
	s_cselect_b32 s14, s8, s0
	v_add_u32_e32 v167, s3, v163
	s_cselect_b32 s1, s10, s25
	s_cselect_b32 s0, s24, s9
	s_add_i32 s6, 0, 0x14000
	ds_read_b128 v[140:143], v167
	ds_read_b128 v[144:147], v167 offset:1024
	ds_read_b128 v[148:151], v167 offset:2048
	ds_read_b128 v[172:175], v167 offset:3072
	v_add_u32_e32 v167, s6, v163
	ds_read_b128 v[190:193], v167
	ds_read_b128 v[194:197], v167 offset:1024
	ds_read_b128 v[198:201], v167 offset:2048
	ds_read_b128 v[202:205], v167 offset:3072
	v_lshl_add_u64 v[176:177], s[22:23], 0, v[136:137]
	s_add_i32 m0, s26, 0xc000
	ds_read_b128 v[206:209], v166
	ds_read_b128 v[210:213], v166 offset:1024
	ds_read_b128 v[214:217], v166 offset:2048
	ds_read_b128 v[218:221], v166 offset:3072
	ds_read_b128 v[222:225], v166 offset:4096
	ds_read_b128 v[226:229], v166 offset:5120
	ds_read_b128 v[230:233], v166 offset:6144
	ds_read_b128 v[234:237], v166 offset:7168
	global_load_lds_dwordx4 v[176:177], off
	v_lshl_add_u64 v[176:177], s[22:23], 0, v[138:139]
	s_add_i32 m0, s26, 0xe000
	s_nop 0
	global_load_lds_dwordx4 v[176:177], off
	s_waitcnt vmcnt(24)
	s_waitcnt lgkmcnt(0)
	s_barrier
	s_waitcnt lgkmcnt(0)
	v_mfma_f32_16x16x32_bf16 v[126:129], v[140:143], v[206:209], v[126:129]
	v_mfma_f32_16x16x32_bf16 v[122:125], v[148:151], v[206:209], v[122:125]
	v_mfma_f32_16x16x32_bf16 v[118:121], v[140:143], v[214:217], v[118:121]
	v_mfma_f32_16x16x32_bf16 v[114:117], v[148:151], v[214:217], v[114:117]
	v_mfma_f32_16x16x32_bf16 v[110:113], v[140:143], v[222:225], v[110:113]
	v_mfma_f32_16x16x32_bf16 v[106:109], v[148:151], v[222:225], v[106:109]
	v_mfma_f32_16x16x32_bf16 v[102:105], v[140:143], v[230:233], v[102:105]
	v_mfma_f32_16x16x32_bf16 v[98:101], v[148:151], v[230:233], v[98:101]
	v_mfma_f32_16x16x32_bf16 v[126:129], v[144:147], v[210:213], v[126:129]
	v_mfma_f32_16x16x32_bf16 v[122:125], v[172:175], v[210:213], v[122:125]
	v_mfma_f32_16x16x32_bf16 v[118:121], v[144:147], v[218:221], v[118:121]
	v_mfma_f32_16x16x32_bf16 v[114:117], v[172:175], v[218:221], v[114:117]
	v_mfma_f32_16x16x32_bf16 v[110:113], v[144:147], v[226:229], v[110:113]
	v_mfma_f32_16x16x32_bf16 v[106:109], v[172:175], v[226:229], v[106:109]
	v_mfma_f32_16x16x32_bf16 v[102:105], v[144:147], v[234:237], v[102:105]
	v_mfma_f32_16x16x32_bf16 v[98:101], v[172:175], v[234:237], v[98:101]
	v_mfma_f32_16x16x32_bf16 v[62:65], v[190:193], v[206:209], v[62:65]
	v_mfma_f32_16x16x32_bf16 v[58:61], v[198:201], v[206:209], v[58:61]
	v_mfma_f32_16x16x32_bf16 v[54:57], v[190:193], v[214:217], v[54:57]
	v_mfma_f32_16x16x32_bf16 v[50:53], v[198:201], v[214:217], v[50:53]
	v_mfma_f32_16x16x32_bf16 v[46:49], v[190:193], v[222:225], v[46:49]
	v_mfma_f32_16x16x32_bf16 v[42:45], v[198:201], v[222:225], v[42:45]
	v_mfma_f32_16x16x32_bf16 v[38:41], v[190:193], v[230:233], v[38:41]
	v_mfma_f32_16x16x32_bf16 v[34:37], v[198:201], v[230:233], v[34:37]
	v_mfma_f32_16x16x32_bf16 v[62:65], v[194:197], v[210:213], v[62:65]
	v_mfma_f32_16x16x32_bf16 v[58:61], v[202:205], v[210:213], v[58:61]
	v_mfma_f32_16x16x32_bf16 v[54:57], v[194:197], v[218:221], v[54:57]
	v_mfma_f32_16x16x32_bf16 v[50:53], v[202:205], v[218:221], v[50:53]
	v_mfma_f32_16x16x32_bf16 v[46:49], v[194:197], v[226:229], v[46:49]
	v_mfma_f32_16x16x32_bf16 v[42:45], v[202:205], v[226:229], v[42:45]
	v_mfma_f32_16x16x32_bf16 v[38:41], v[194:197], v[234:237], v[38:41]
	v_mfma_f32_16x16x32_bf16 v[34:37], v[202:205], v[234:237], v[34:37]
	s_barrier
	s_add_i32 s3, s3, s11
	v_lshl_add_u64 v[176:177], s[0:1], 0, v[4:5]
	s_mov_b32 m0, s3
	ds_read_b128 v[206:209], v166 offset:16384
	ds_read_b128 v[210:213], v166 offset:17408
	ds_read_b128 v[214:217], v166 offset:18432
	ds_read_b128 v[218:221], v166 offset:19456
	ds_read_b128 v[222:225], v166 offset:20480
	ds_read_b128 v[226:229], v166 offset:21504
	ds_read_b128 v[230:233], v166 offset:22528
	ds_read_b128 v[234:237], v166 offset:23552
	global_load_lds_dwordx4 v[176:177], off
	s_add_i32 m0, s3, 0x2000
	s_add_u32 s4, s0, 0x80000
	v_lshl_add_u64 v[238:239], s[0:1], 0, v[134:135]
	s_addc_u32 s5, s1, 0
	s_add_i32 s3, s6, s11
	global_load_lds_dwordx4 v[238:239], off
	v_lshl_add_u64 v[240:241], s[4:5], 0, v[4:5]
	s_mov_b32 m0, s3
	v_lshl_add_u64 v[242:243], s[14:15], 0, v[132:133]
	global_load_lds_dwordx4 v[240:241], off
	v_lshl_add_u64 v[240:241], s[4:5], 0, v[134:135]
	s_add_i32 m0, s3, 0x2000
	s_nop 0
	global_load_lds_dwordx4 v[240:241], off
	v_lshl_add_u64 v[240:241], s[14:15], 0, v[130:131]
	s_mov_b32 m0, s26
	s_nop 0
	global_load_lds_dwordx4 v[240:241], off
	s_mov_b32 m0, s27
	s_nop 0
	global_load_lds_dwordx4 v[242:243], off
	s_waitcnt vmcnt(24)
	s_waitcnt lgkmcnt(0)
	s_barrier
	s_waitcnt lgkmcnt(0)
	v_mfma_f32_16x16x32_bf16 v[94:97], v[140:143], v[206:209], v[94:97]
	v_mfma_f32_16x16x32_bf16 v[90:93], v[148:151], v[206:209], v[90:93]
	v_mfma_f32_16x16x32_bf16 v[86:89], v[140:143], v[214:217], v[86:89]
	v_mfma_f32_16x16x32_bf16 v[82:85], v[148:151], v[214:217], v[82:85]
	v_mfma_f32_16x16x32_bf16 v[78:81], v[140:143], v[222:225], v[78:81]
	v_mfma_f32_16x16x32_bf16 v[74:77], v[148:151], v[222:225], v[74:77]
	v_mfma_f32_16x16x32_bf16 v[70:73], v[140:143], v[230:233], v[70:73]
	v_mfma_f32_16x16x32_bf16 v[66:69], v[148:151], v[230:233], v[66:69]
	v_mfma_f32_16x16x32_bf16 v[94:97], v[144:147], v[210:213], v[94:97]
	v_mfma_f32_16x16x32_bf16 v[90:93], v[172:175], v[210:213], v[90:93]
	v_mfma_f32_16x16x32_bf16 v[86:89], v[144:147], v[218:221], v[86:89]
	v_mfma_f32_16x16x32_bf16 v[82:85], v[172:175], v[218:221], v[82:85]
	v_mfma_f32_16x16x32_bf16 v[78:81], v[144:147], v[226:229], v[78:81]
	v_mfma_f32_16x16x32_bf16 v[74:77], v[172:175], v[226:229], v[74:77]
	v_mfma_f32_16x16x32_bf16 v[70:73], v[144:147], v[234:237], v[70:73]
	v_mfma_f32_16x16x32_bf16 v[66:69], v[172:175], v[234:237], v[66:69]
	v_mfma_f32_16x16x32_bf16 v[30:33], v[190:193], v[206:209], v[30:33]
	v_mfma_f32_16x16x32_bf16 v[26:29], v[198:201], v[206:209], v[26:29]
	v_mfma_f32_16x16x32_bf16 v[22:25], v[190:193], v[214:217], v[22:25]
	v_mfma_f32_16x16x32_bf16 v[18:21], v[198:201], v[214:217], v[18:21]
	v_mfma_f32_16x16x32_bf16 v[14:17], v[190:193], v[222:225], v[14:17]
	v_mfma_f32_16x16x32_bf16 v[10:13], v[198:201], v[222:225], v[10:13]
	v_mfma_f32_16x16x32_bf16 v[6:9], v[190:193], v[230:233], v[6:9]
	v_mfma_f32_16x16x32_bf16 v[0:3], v[198:201], v[230:233], v[0:3]
	v_mfma_f32_16x16x32_bf16 v[30:33], v[194:197], v[210:213], v[30:33]
	v_mfma_f32_16x16x32_bf16 v[26:29], v[202:205], v[210:213], v[26:29]
	v_mfma_f32_16x16x32_bf16 v[22:25], v[194:197], v[218:221], v[22:25]
	v_mfma_f32_16x16x32_bf16 v[18:21], v[202:205], v[218:221], v[18:21]
	v_mfma_f32_16x16x32_bf16 v[14:17], v[194:197], v[226:229], v[14:17]
	v_mfma_f32_16x16x32_bf16 v[10:13], v[202:205], v[226:229], v[10:13]
	v_mfma_f32_16x16x32_bf16 v[6:9], v[194:197], v[234:237], v[6:9]
	v_mfma_f32_16x16x32_bf16 v[0:3], v[202:205], v[234:237], v[0:3]
	s_barrier
	s_branch .Lpeelmid_852
.LBB0_852:
	s_add_u32 s0, s22, 0xfff80080
	s_addc_u32 s1, s23, -1
	s_add_i32 s3, 0, 0x10000
	s_cmp_eq_u32 s28, 28
	s_cselect_b32 s15, s2, s1
	s_cselect_b32 s14, s8, s0
	v_add_u32_e32 v167, s3, v163
	s_cselect_b32 s1, s10, s25
	s_cselect_b32 s0, s24, s9
	s_add_i32 s6, 0, 0x14000
	ds_read_b128 v[140:143], v167
	ds_read_b128 v[144:147], v167 offset:1024
	ds_read_b128 v[148:151], v167 offset:2048
	ds_read_b128 v[172:175], v167 offset:3072
	v_add_u32_e32 v167, s6, v163
	ds_read_b128 v[190:193], v167
	ds_read_b128 v[194:197], v167 offset:1024
	ds_read_b128 v[198:201], v167 offset:2048
	ds_read_b128 v[202:205], v167 offset:3072
	v_lshl_add_u64 v[176:177], s[22:23], 0, v[136:137]
	s_add_i32 m0, s26, 0xc000
	ds_read_b128 v[206:209], v166
	ds_read_b128 v[210:213], v166 offset:1024
	ds_read_b128 v[214:217], v166 offset:2048
	ds_read_b128 v[218:221], v166 offset:3072
	ds_read_b128 v[222:225], v166 offset:4096
	ds_read_b128 v[226:229], v166 offset:5120
	ds_read_b128 v[230:233], v166 offset:6144
	ds_read_b128 v[234:237], v166 offset:7168
	global_load_lds_dwordx4 v[176:177], off
	v_lshl_add_u64 v[176:177], s[22:23], 0, v[138:139]
	s_add_i32 m0, s26, 0xe000
	s_nop 0
	global_load_lds_dwordx4 v[176:177], off
	s_waitcnt vmcnt(8)
	s_waitcnt lgkmcnt(0)
	s_barrier
	s_waitcnt lgkmcnt(0)
	v_mfma_f32_16x16x32_bf16 v[126:129], v[140:143], v[206:209], v[126:129]
	v_mfma_f32_16x16x32_bf16 v[122:125], v[148:151], v[206:209], v[122:125]
	v_mfma_f32_16x16x32_bf16 v[118:121], v[140:143], v[214:217], v[118:121]
	v_mfma_f32_16x16x32_bf16 v[114:117], v[148:151], v[214:217], v[114:117]
	v_mfma_f32_16x16x32_bf16 v[110:113], v[140:143], v[222:225], v[110:113]
	v_mfma_f32_16x16x32_bf16 v[106:109], v[148:151], v[222:225], v[106:109]
	v_mfma_f32_16x16x32_bf16 v[102:105], v[140:143], v[230:233], v[102:105]
	v_mfma_f32_16x16x32_bf16 v[98:101], v[148:151], v[230:233], v[98:101]
	v_mfma_f32_16x16x32_bf16 v[126:129], v[144:147], v[210:213], v[126:129]
	v_mfma_f32_16x16x32_bf16 v[122:125], v[172:175], v[210:213], v[122:125]
	v_mfma_f32_16x16x32_bf16 v[118:121], v[144:147], v[218:221], v[118:121]
	v_mfma_f32_16x16x32_bf16 v[114:117], v[172:175], v[218:221], v[114:117]
	v_mfma_f32_16x16x32_bf16 v[110:113], v[144:147], v[226:229], v[110:113]
	v_mfma_f32_16x16x32_bf16 v[106:109], v[172:175], v[226:229], v[106:109]
	v_mfma_f32_16x16x32_bf16 v[102:105], v[144:147], v[234:237], v[102:105]
	v_mfma_f32_16x16x32_bf16 v[98:101], v[172:175], v[234:237], v[98:101]
	v_mfma_f32_16x16x32_bf16 v[62:65], v[190:193], v[206:209], v[62:65]
	v_mfma_f32_16x16x32_bf16 v[58:61], v[198:201], v[206:209], v[58:61]
	v_mfma_f32_16x16x32_bf16 v[54:57], v[190:193], v[214:217], v[54:57]
	v_mfma_f32_16x16x32_bf16 v[50:53], v[198:201], v[214:217], v[50:53]
	v_mfma_f32_16x16x32_bf16 v[46:49], v[190:193], v[222:225], v[46:49]
	v_mfma_f32_16x16x32_bf16 v[42:45], v[198:201], v[222:225], v[42:45]
	v_mfma_f32_16x16x32_bf16 v[38:41], v[190:193], v[230:233], v[38:41]
	v_mfma_f32_16x16x32_bf16 v[34:37], v[198:201], v[230:233], v[34:37]
	v_mfma_f32_16x16x32_bf16 v[62:65], v[194:197], v[210:213], v[62:65]
	v_mfma_f32_16x16x32_bf16 v[58:61], v[202:205], v[210:213], v[58:61]
	v_mfma_f32_16x16x32_bf16 v[54:57], v[194:197], v[218:221], v[54:57]
	v_mfma_f32_16x16x32_bf16 v[50:53], v[202:205], v[218:221], v[50:53]
	v_mfma_f32_16x16x32_bf16 v[46:49], v[194:197], v[226:229], v[46:49]
	v_mfma_f32_16x16x32_bf16 v[42:45], v[202:205], v[226:229], v[42:45]
	v_mfma_f32_16x16x32_bf16 v[38:41], v[194:197], v[234:237], v[38:41]
	v_mfma_f32_16x16x32_bf16 v[34:37], v[202:205], v[234:237], v[34:37]
	s_barrier
	s_add_i32 s3, s3, s11
	v_lshl_add_u64 v[176:177], s[0:1], 0, v[4:5]
	s_mov_b32 m0, s3
	ds_read_b128 v[206:209], v166 offset:16384
	ds_read_b128 v[210:213], v166 offset:17408
	ds_read_b128 v[214:217], v166 offset:18432
	ds_read_b128 v[218:221], v166 offset:19456
	ds_read_b128 v[222:225], v166 offset:20480
	ds_read_b128 v[226:229], v166 offset:21504
	ds_read_b128 v[230:233], v166 offset:22528
	ds_read_b128 v[234:237], v166 offset:23552
	global_load_lds_dwordx4 v[176:177], off
	s_add_i32 m0, s3, 0x2000
	s_add_u32 s4, s0, 0x80000
	v_lshl_add_u64 v[238:239], s[0:1], 0, v[134:135]
	s_addc_u32 s5, s1, 0
	s_add_i32 s3, s6, s11
	global_load_lds_dwordx4 v[238:239], off
	v_lshl_add_u64 v[240:241], s[4:5], 0, v[4:5]
	s_mov_b32 m0, s3
	v_lshl_add_u64 v[242:243], s[14:15], 0, v[132:133]
	global_load_lds_dwordx4 v[240:241], off
	v_lshl_add_u64 v[240:241], s[4:5], 0, v[134:135]
	s_add_i32 m0, s3, 0x2000
	s_nop 0
	global_load_lds_dwordx4 v[240:241], off
	v_lshl_add_u64 v[240:241], s[14:15], 0, v[130:131]
	s_mov_b32 m0, s26
	s_nop 0
	global_load_lds_dwordx4 v[240:241], off
	s_mov_b32 m0, s27
	s_nop 0
	global_load_lds_dwordx4 v[242:243], off
	s_waitcnt vmcnt(8)
	s_waitcnt lgkmcnt(0)
	s_barrier
	s_waitcnt lgkmcnt(0)
	v_mfma_f32_16x16x32_bf16 v[94:97], v[140:143], v[206:209], v[94:97]
	v_mfma_f32_16x16x32_bf16 v[90:93], v[148:151], v[206:209], v[90:93]
	v_mfma_f32_16x16x32_bf16 v[86:89], v[140:143], v[214:217], v[86:89]
	v_mfma_f32_16x16x32_bf16 v[82:85], v[148:151], v[214:217], v[82:85]
	v_mfma_f32_16x16x32_bf16 v[78:81], v[140:143], v[222:225], v[78:81]
	v_mfma_f32_16x16x32_bf16 v[74:77], v[148:151], v[222:225], v[74:77]
	v_mfma_f32_16x16x32_bf16 v[70:73], v[140:143], v[230:233], v[70:73]
	v_mfma_f32_16x16x32_bf16 v[66:69], v[148:151], v[230:233], v[66:69]
	v_mfma_f32_16x16x32_bf16 v[94:97], v[144:147], v[210:213], v[94:97]
	v_mfma_f32_16x16x32_bf16 v[90:93], v[172:175], v[210:213], v[90:93]
	v_mfma_f32_16x16x32_bf16 v[86:89], v[144:147], v[218:221], v[86:89]
	v_mfma_f32_16x16x32_bf16 v[82:85], v[172:175], v[218:221], v[82:85]
	v_mfma_f32_16x16x32_bf16 v[78:81], v[144:147], v[226:229], v[78:81]
	v_mfma_f32_16x16x32_bf16 v[74:77], v[172:175], v[226:229], v[74:77]
	v_mfma_f32_16x16x32_bf16 v[70:73], v[144:147], v[234:237], v[70:73]
	v_mfma_f32_16x16x32_bf16 v[66:69], v[172:175], v[234:237], v[66:69]
	v_mfma_f32_16x16x32_bf16 v[30:33], v[190:193], v[206:209], v[30:33]
	v_mfma_f32_16x16x32_bf16 v[26:29], v[198:201], v[206:209], v[26:29]
	v_mfma_f32_16x16x32_bf16 v[22:25], v[190:193], v[214:217], v[22:25]
	v_mfma_f32_16x16x32_bf16 v[18:21], v[198:201], v[214:217], v[18:21]
	v_mfma_f32_16x16x32_bf16 v[14:17], v[190:193], v[222:225], v[14:17]
	v_mfma_f32_16x16x32_bf16 v[10:13], v[198:201], v[222:225], v[10:13]
	v_mfma_f32_16x16x32_bf16 v[6:9], v[190:193], v[230:233], v[6:9]
	v_mfma_f32_16x16x32_bf16 v[0:3], v[198:201], v[230:233], v[0:3]
	v_mfma_f32_16x16x32_bf16 v[30:33], v[194:197], v[210:213], v[30:33]
	v_mfma_f32_16x16x32_bf16 v[26:29], v[202:205], v[210:213], v[26:29]
	v_mfma_f32_16x16x32_bf16 v[22:25], v[194:197], v[218:221], v[22:25]
	v_mfma_f32_16x16x32_bf16 v[18:21], v[202:205], v[218:221], v[18:21]
	v_mfma_f32_16x16x32_bf16 v[14:17], v[194:197], v[226:229], v[14:17]
	v_mfma_f32_16x16x32_bf16 v[10:13], v[202:205], v[226:229], v[10:13]
	v_mfma_f32_16x16x32_bf16 v[6:9], v[194:197], v[234:237], v[6:9]
	v_mfma_f32_16x16x32_bf16 v[0:3], v[202:205], v[234:237], v[0:3]
	s_barrier
.Lpeelmid_852:
	s_add_i32 s3, 0, 0x18000
	v_add_u32_e32 v167, s3, v163
	s_add_i32 s6, 0, 0x1c000
	ds_read_b128 v[140:143], v167
	ds_read_b128 v[144:147], v167 offset:1024
	ds_read_b128 v[148:151], v167 offset:2048
	ds_read_b128 v[172:175], v167 offset:3072
	v_add_u32_e32 v167, s6, v163
	ds_read_b128 v[190:193], v167
	ds_read_b128 v[194:197], v167 offset:1024
	ds_read_b128 v[198:201], v167 offset:2048
	ds_read_b128 v[202:205], v167 offset:3072
	s_add_u32 s4, s14, 0x80000
	s_addc_u32 s5, s15, 0
	s_mov_b32 m0, s30
	v_lshl_add_u64 v[244:245], s[4:5], 0, v[130:131]
	ds_read_b128 v[206:209], v166 offset:32768
	ds_read_b128 v[210:213], v166 offset:33792
	ds_read_b128 v[214:217], v166 offset:34816
	ds_read_b128 v[218:221], v166 offset:35840
	ds_read_b128 v[222:225], v166 offset:36864
	ds_read_b128 v[226:229], v166 offset:37888
	ds_read_b128 v[230:233], v166 offset:38912
	ds_read_b128 v[234:237], v166 offset:39936
	global_load_lds_dwordx4 v[244:245], off
	v_lshl_add_u64 v[244:245], s[4:5], 0, v[132:133]
	s_mov_b32 m0, s31
	s_nop 0
	global_load_lds_dwordx4 v[244:245], off
	s_waitcnt vmcnt(8)
	s_waitcnt lgkmcnt(0)
	s_barrier
	s_waitcnt lgkmcnt(0)
	v_mfma_f32_16x16x32_bf16 v[126:129], v[140:143], v[206:209], v[126:129]
	v_mfma_f32_16x16x32_bf16 v[122:125], v[148:151], v[206:209], v[122:125]
	v_mfma_f32_16x16x32_bf16 v[118:121], v[140:143], v[214:217], v[118:121]
	v_mfma_f32_16x16x32_bf16 v[114:117], v[148:151], v[214:217], v[114:117]
	v_mfma_f32_16x16x32_bf16 v[110:113], v[140:143], v[222:225], v[110:113]
	v_mfma_f32_16x16x32_bf16 v[106:109], v[148:151], v[222:225], v[106:109]
	v_mfma_f32_16x16x32_bf16 v[102:105], v[140:143], v[230:233], v[102:105]
	v_mfma_f32_16x16x32_bf16 v[98:101], v[148:151], v[230:233], v[98:101]
	v_mfma_f32_16x16x32_bf16 v[126:129], v[144:147], v[210:213], v[126:129]
	v_mfma_f32_16x16x32_bf16 v[122:125], v[172:175], v[210:213], v[122:125]
	v_mfma_f32_16x16x32_bf16 v[118:121], v[144:147], v[218:221], v[118:121]
	v_mfma_f32_16x16x32_bf16 v[114:117], v[172:175], v[218:221], v[114:117]
	v_mfma_f32_16x16x32_bf16 v[110:113], v[144:147], v[226:229], v[110:113]
	v_mfma_f32_16x16x32_bf16 v[106:109], v[172:175], v[226:229], v[106:109]
	v_mfma_f32_16x16x32_bf16 v[102:105], v[144:147], v[234:237], v[102:105]
	v_mfma_f32_16x16x32_bf16 v[98:101], v[172:175], v[234:237], v[98:101]
	v_mfma_f32_16x16x32_bf16 v[62:65], v[190:193], v[206:209], v[62:65]
	v_mfma_f32_16x16x32_bf16 v[58:61], v[198:201], v[206:209], v[58:61]
	v_mfma_f32_16x16x32_bf16 v[54:57], v[190:193], v[214:217], v[54:57]
	v_mfma_f32_16x16x32_bf16 v[50:53], v[198:201], v[214:217], v[50:53]
	v_mfma_f32_16x16x32_bf16 v[46:49], v[190:193], v[222:225], v[46:49]
	v_mfma_f32_16x16x32_bf16 v[42:45], v[198:201], v[222:225], v[42:45]
	v_mfma_f32_16x16x32_bf16 v[38:41], v[190:193], v[230:233], v[38:41]
	v_mfma_f32_16x16x32_bf16 v[34:37], v[198:201], v[230:233], v[34:37]
	v_mfma_f32_16x16x32_bf16 v[62:65], v[194:197], v[210:213], v[62:65]
	v_mfma_f32_16x16x32_bf16 v[58:61], v[202:205], v[210:213], v[58:61]
	v_mfma_f32_16x16x32_bf16 v[54:57], v[194:197], v[218:221], v[54:57]
	v_mfma_f32_16x16x32_bf16 v[50:53], v[202:205], v[218:221], v[50:53]
	v_mfma_f32_16x16x32_bf16 v[46:49], v[194:197], v[226:229], v[46:49]
	v_mfma_f32_16x16x32_bf16 v[42:45], v[202:205], v[226:229], v[42:45]
	v_mfma_f32_16x16x32_bf16 v[38:41], v[194:197], v[234:237], v[38:41]
	v_mfma_f32_16x16x32_bf16 v[34:37], v[202:205], v[234:237], v[34:37]
	s_barrier
	s_add_i32 s3, s3, s11
	v_lshl_add_u64 v[176:177], v[176:177], 0, s[70:71]
	s_mov_b32 m0, s3
	ds_read_b128 v[206:209], v166 offset:49152
	ds_read_b128 v[210:213], v166 offset:50176
	ds_read_b128 v[214:217], v166 offset:51200
	ds_read_b128 v[218:221], v166 offset:52224
	ds_read_b128 v[222:225], v166 offset:53248
	ds_read_b128 v[226:229], v166 offset:54272
	ds_read_b128 v[230:233], v166 offset:55296
	ds_read_b128 v[234:237], v166 offset:56320
	global_load_lds_dwordx4 v[176:177], off
	s_add_i32 m0, s3, 0x2000
	s_add_u32 s0, s0, 0x80080
	v_lshl_add_u64 v[176:177], v[238:239], 0, s[70:71]
	s_addc_u32 s1, s1, 0
	s_add_i32 s3, s6, s11
	global_load_lds_dwordx4 v[176:177], off
	v_lshl_add_u64 v[176:177], s[0:1], 0, v[4:5]
	s_mov_b32 m0, s3
	s_nop 0
	global_load_lds_dwordx4 v[176:177], off
	v_lshl_add_u64 v[176:177], s[0:1], 0, v[134:135]
	s_add_i32 m0, s3, 0x2000
	s_nop 0
	global_load_lds_dwordx4 v[176:177], off
	v_lshl_add_u64 v[176:177], v[240:241], 0, s[70:71]
	s_mov_b32 m0, s34
	s_nop 0
	global_load_lds_dwordx4 v[176:177], off
	v_lshl_add_u64 v[176:177], v[242:243], 0, s[70:71]
	s_mov_b32 m0, s35
	s_nop 0
	global_load_lds_dwordx4 v[176:177], off
	s_waitcnt vmcnt(8)
	s_waitcnt lgkmcnt(0)
	s_barrier
	s_waitcnt lgkmcnt(0)
	v_mfma_f32_16x16x32_bf16 v[94:97], v[140:143], v[206:209], v[94:97]
	v_mfma_f32_16x16x32_bf16 v[90:93], v[148:151], v[206:209], v[90:93]
	v_mfma_f32_16x16x32_bf16 v[86:89], v[140:143], v[214:217], v[86:89]
	v_mfma_f32_16x16x32_bf16 v[82:85], v[148:151], v[214:217], v[82:85]
	v_mfma_f32_16x16x32_bf16 v[78:81], v[140:143], v[222:225], v[78:81]
	v_mfma_f32_16x16x32_bf16 v[74:77], v[148:151], v[222:225], v[74:77]
	v_mfma_f32_16x16x32_bf16 v[70:73], v[140:143], v[230:233], v[70:73]
	v_mfma_f32_16x16x32_bf16 v[66:69], v[148:151], v[230:233], v[66:69]
	v_mfma_f32_16x16x32_bf16 v[94:97], v[144:147], v[210:213], v[94:97]
	v_mfma_f32_16x16x32_bf16 v[90:93], v[172:175], v[210:213], v[90:93]
	v_mfma_f32_16x16x32_bf16 v[86:89], v[144:147], v[218:221], v[86:89]
	v_mfma_f32_16x16x32_bf16 v[82:85], v[172:175], v[218:221], v[82:85]
	v_mfma_f32_16x16x32_bf16 v[78:81], v[144:147], v[226:229], v[78:81]
	v_mfma_f32_16x16x32_bf16 v[74:77], v[172:175], v[226:229], v[74:77]
	v_mfma_f32_16x16x32_bf16 v[70:73], v[144:147], v[234:237], v[70:73]
	v_mfma_f32_16x16x32_bf16 v[66:69], v[172:175], v[234:237], v[66:69]
	v_mfma_f32_16x16x32_bf16 v[30:33], v[190:193], v[206:209], v[30:33]
	v_mfma_f32_16x16x32_bf16 v[26:29], v[198:201], v[206:209], v[26:29]
	v_mfma_f32_16x16x32_bf16 v[22:25], v[190:193], v[214:217], v[22:25]
	v_mfma_f32_16x16x32_bf16 v[18:21], v[198:201], v[214:217], v[18:21]
	v_mfma_f32_16x16x32_bf16 v[14:17], v[190:193], v[222:225], v[14:17]
	v_mfma_f32_16x16x32_bf16 v[10:13], v[198:201], v[222:225], v[10:13]
	v_mfma_f32_16x16x32_bf16 v[6:9], v[190:193], v[230:233], v[6:9]
	v_mfma_f32_16x16x32_bf16 v[0:3], v[198:201], v[230:233], v[0:3]
	v_mfma_f32_16x16x32_bf16 v[30:33], v[194:197], v[210:213], v[30:33]
	v_mfma_f32_16x16x32_bf16 v[26:29], v[202:205], v[210:213], v[26:29]
	v_mfma_f32_16x16x32_bf16 v[22:25], v[194:197], v[218:221], v[22:25]
	v_mfma_f32_16x16x32_bf16 v[18:21], v[202:205], v[218:221], v[18:21]
	v_mfma_f32_16x16x32_bf16 v[14:17], v[194:197], v[226:229], v[14:17]
	v_mfma_f32_16x16x32_bf16 v[10:13], v[202:205], v[226:229], v[10:13]
	v_mfma_f32_16x16x32_bf16 v[6:9], v[194:197], v[234:237], v[6:9]
	v_mfma_f32_16x16x32_bf16 v[0:3], v[202:205], v[234:237], v[0:3]
	s_barrier
	s_add_i32 s28, s28, 2
	s_add_u32 s22, s22, 0x100
	s_addc_u32 s23, s23, 0
	s_add_u32 s9, s9, 0x100
	s_addc_u32 s25, s25, 0
	s_cmp_gt_u32 s28, 29
	s_cbranch_scc0 .LBB0_852
	s_and_b64 vcc, exec, s[48:49]
	s_cbranch_vccz .LBB0_855
	s_barrier
